# rows phase: rope tables in LDS, hoisted conv weights, overlapped row loads; N1: norm gain and modulation vectors staged in LDS, real prefetch overlap; final norm: hoisted gain; P0 GEMV and FFT reducti
# speedup vs baseline: 1.0183x; 1.0109x over previous
.LBB0_12:
	v_lshl_add_u64 v[46:47], v[28:29], 0, s[6:7]
	v_add_co_u32_e32 v70, vcc, s1, v46
	ds_read2_b32 v[42:43], v35 offset1:4
	ds_read2_b32 v[44:45], v35 offset0:128 offset1:132
	v_addc_co_u32_e32 v71, vcc, 0, v47, vcc
	v_add_co_u32_e32 v72, vcc, s8, v46
	ds_read2_b32 v[48:49], v35 offset0:8 offset1:12
	ds_read2_b32 v[50:51], v35 offset0:136 offset1:140
	ds_read2_b32 v[52:53], v35 offset0:16 offset1:20
	ds_read2_b32 v[54:55], v35 offset0:144 offset1:148
	ds_read2_b32 v[56:57], v35 offset0:24 offset1:28
	ds_read2_b32 v[58:59], v35 offset0:152 offset1:156
	v_addc_co_u32_e32 v73, vcc, 0, v47, vcc
	v_add_co_u32_e32 v74, vcc, s9, v46
	global_load_dwordx4 v[66:69], v[46:47], off nt
	s_nop 0
	v_addc_co_u32_e32 v75, vcc, 0, v47, vcc
	v_add_co_u32_e32 v78, vcc, s10, v46
	v_add_u32_e32 v60, 0x400, v35
	s_nop 0
	v_addc_co_u32_e32 v79, vcc, 0, v47, vcc
	v_add_co_u32_e32 v82, vcc, s11, v46
	v_add_u32_e32 v62, 0x800, v35
	s_nop 0
	v_addc_co_u32_e32 v83, vcc, 0, v47, vcc
	v_add_co_u32_e32 v86, vcc, s12, v46
	v_add_u32_e32 v63, 0xc00, v35
	s_nop 0
	v_addc_co_u32_e32 v87, vcc, 0, v47, vcc
	v_add_u32_e32 v64, 0x1000, v35
	v_add_co_u32_e32 v46, vcc, s13, v46
	ds_read2_b32 v[94:95], v60 offset1:4
	ds_read2_b32 v[96:97], v60 offset0:128 offset1:132
	ds_read2_b32 v[98:99], v62 offset1:4
	ds_read2_b32 v[100:101], v62 offset0:128 offset1:132
	ds_read2_b32 v[102:103], v63 offset1:4
	ds_read2_b32 v[104:105], v63 offset0:128 offset1:132
	ds_read2_b32 v[106:107], v64 offset1:4
	ds_read2_b32 v[108:109], v60 offset0:8 offset1:12
	ds_read2_b32 v[110:111], v60 offset0:136 offset1:140
	ds_read2_b32 v[112:113], v62 offset0:8 offset1:12
	ds_read2_b32 v[114:115], v62 offset0:136 offset1:140
	ds_read2_b32 v[116:117], v63 offset0:8 offset1:12
	ds_read2_b32 v[118:119], v63 offset0:136 offset1:140
	ds_read2_b32 v[120:121], v64 offset0:8 offset1:12
	ds_read2_b32 v[122:123], v60 offset0:16 offset1:20
	ds_read2_b32 v[124:125], v60 offset0:144 offset1:148
	ds_read2_b32 v[126:127], v62 offset0:16 offset1:20
	ds_read2_b32 v[128:129], v62 offset0:144 offset1:148
	ds_read2_b32 v[130:131], v63 offset0:16 offset1:20
	ds_read2_b32 v[132:133], v63 offset0:144 offset1:148
	ds_read2_b32 v[134:135], v64 offset0:16 offset1:20
	v_addc_co_u32_e32 v47, vcc, 0, v47, vcc
	ds_read2_b32 v[136:137], v60 offset0:24 offset1:28
	ds_read2_b32 v[138:139], v60 offset0:152 offset1:156
	ds_read2_b32 v[140:141], v62 offset0:24 offset1:28
	ds_read2_b32 v[142:143], v62 offset0:152 offset1:156
	ds_read2_b32 v[144:145], v63 offset0:24 offset1:28
	ds_read2_b32 v[146:147], v63 offset0:152 offset1:156
	ds_read2_b32 v[148:149], v64 offset0:24 offset1:28
	global_load_dwordx4 v[62:65], v[70:71], off nt
	s_nop 0
	global_load_dwordx4 v[70:73], v[72:73], off nt
	s_nop 0
	global_load_dwordx4 v[74:77], v[74:75], off nt
	s_nop 0
	global_load_dwordx4 v[78:81], v[78:79], off nt
	s_nop 0
	global_load_dwordx4 v[82:85], v[82:83], off nt
	s_nop 0
	global_load_dwordx4 v[86:89], v[86:87], off nt
	s_nop 0
	global_load_dwordx4 v[90:93], v[46:47], off nt
	s_waitcnt lgkmcnt(14)
	v_mov_b32_e32 v46, v43
	v_mov_b32_e32 v60, v45
	v_mov_b32_e32 v162, v95
	v_mov_b32_e32 v164, v97
	v_mov_b32_e32 v166, v99
	v_mov_b32_e32 v168, v101
	v_mov_b32_e32 v170, v103
	v_mov_b32_e32 v172, v105
	v_mov_b32_e32 v174, v107
	v_mov_b32_e32 v150, v49
	v_mov_b32_e32 v152, v51
	v_mov_b32_e32 v176, v109
	v_mov_b32_e32 v178, v111
	v_mov_b32_e32 v180, v113
	v_mov_b32_e32 v182, v115
	v_mov_b32_e32 v184, v117
	v_mov_b32_e32 v186, v119
	v_mov_b32_e32 v188, v121
	v_mov_b32_e32 v154, v53
	v_mov_b32_e32 v156, v55
	s_waitcnt lgkmcnt(13)
	v_mov_b32_e32 v190, v123
	s_waitcnt lgkmcnt(12)
	v_mov_b32_e32 v192, v125
	s_waitcnt lgkmcnt(11)
	v_mov_b32_e32 v194, v127
	s_waitcnt lgkmcnt(10)
	v_mov_b32_e32 v196, v129
	s_waitcnt lgkmcnt(9)
	v_mov_b32_e32 v198, v131
	s_waitcnt lgkmcnt(8)
	v_mov_b32_e32 v200, v133
	s_waitcnt lgkmcnt(7)
	v_mov_b32_e32 v202, v135
	s_add_u32 s6, s6, 0xc0000
	s_addc_u32 s7, s7, 0
	v_mov_b32_e32 v158, v57
	v_mov_b32_e32 v160, v59
	s_waitcnt lgkmcnt(6)
	v_mov_b32_e32 v204, v137
	s_waitcnt lgkmcnt(5)
	v_mov_b32_e32 v206, v139
	s_waitcnt lgkmcnt(4)
	v_mov_b32_e32 v208, v141
	s_waitcnt lgkmcnt(3)
	v_mov_b32_e32 v210, v143
	s_waitcnt lgkmcnt(2)
	v_mov_b32_e32 v212, v145
	s_waitcnt lgkmcnt(1)
	v_mov_b32_e32 v214, v147
	s_waitcnt lgkmcnt(0)
	v_mov_b32_e32 v216, v149
	v_add_u32_e32 v35, 0x80, v35
	s_cmp_eq_u32 s6, 0x300000
	s_waitcnt vmcnt(7)
	v_pk_fma_f32 v[40:41], v[66:67], v[42:43], v[40:41] op_sel_hi:[1,0,1]
	v_pk_fma_f32 v[38:39], v[68:69], v[42:43], v[38:39] op_sel_hi:[1,0,1]
	v_pk_fma_f32 v[36:37], v[66:67], v[44:45], v[36:37] op_sel_hi:[1,0,1]
	v_pk_fma_f32 v[32:33], v[68:69], v[44:45], v[32:33] op_sel_hi:[1,0,1]
	v_pk_fma_f32 v[30:31], v[66:67], v[94:95], v[30:31] op_sel_hi:[1,0,1]
	v_pk_fma_f32 v[26:27], v[68:69], v[94:95], v[26:27] op_sel_hi:[1,0,1]
	v_pk_fma_f32 v[24:25], v[66:67], v[96:97], v[24:25] op_sel_hi:[1,0,1]
	v_pk_fma_f32 v[22:23], v[68:69], v[96:97], v[22:23] op_sel_hi:[1,0,1]
	v_pk_fma_f32 v[20:21], v[66:67], v[98:99], v[20:21] op_sel_hi:[1,0,1]
	v_pk_fma_f32 v[18:19], v[68:69], v[98:99], v[18:19] op_sel_hi:[1,0,1]
	v_pk_fma_f32 v[16:17], v[66:67], v[100:101], v[16:17] op_sel_hi:[1,0,1]
	v_pk_fma_f32 v[14:15], v[68:69], v[100:101], v[14:15] op_sel_hi:[1,0,1]
	v_pk_fma_f32 v[12:13], v[66:67], v[102:103], v[12:13] op_sel_hi:[1,0,1]
	v_pk_fma_f32 v[8:9], v[68:69], v[102:103], v[8:9] op_sel_hi:[1,0,1]
	v_pk_fma_f32 v[10:11], v[66:67], v[104:105], v[10:11] op_sel_hi:[1,0,1]
	v_pk_fma_f32 v[6:7], v[68:69], v[104:105], v[6:7] op_sel_hi:[1,0,1]
	v_pk_fma_f32 v[4:5], v[66:67], v[106:107], v[4:5] op_sel_hi:[1,0,1]
	v_pk_fma_f32 v[2:3], v[68:69], v[106:107], v[2:3] op_sel_hi:[1,0,1]
	s_waitcnt vmcnt(6)
	v_pk_fma_f32 v[40:41], v[62:63], v[46:47], v[40:41] op_sel_hi:[1,0,1]
	v_pk_fma_f32 v[38:39], v[64:65], v[46:47], v[38:39] op_sel_hi:[1,0,1]
	v_pk_fma_f32 v[36:37], v[62:63], v[60:61], v[36:37] op_sel_hi:[1,0,1]
	v_pk_fma_f32 v[32:33], v[64:65], v[60:61], v[32:33] op_sel_hi:[1,0,1]
	v_pk_fma_f32 v[30:31], v[62:63], v[162:163], v[30:31] op_sel_hi:[1,0,1]
	v_pk_fma_f32 v[26:27], v[64:65], v[162:163], v[26:27] op_sel_hi:[1,0,1]
	v_pk_fma_f32 v[24:25], v[62:63], v[164:165], v[24:25] op_sel_hi:[1,0,1]
	v_pk_fma_f32 v[22:23], v[64:65], v[164:165], v[22:23] op_sel_hi:[1,0,1]
	v_pk_fma_f32 v[20:21], v[62:63], v[166:167], v[20:21] op_sel_hi:[1,0,1]
	v_pk_fma_f32 v[18:19], v[64:65], v[166:167], v[18:19] op_sel_hi:[1,0,1]
	v_pk_fma_f32 v[16:17], v[62:63], v[168:169], v[16:17] op_sel_hi:[1,0,1]
	v_pk_fma_f32 v[14:15], v[64:65], v[168:169], v[14:15] op_sel_hi:[1,0,1]
	v_pk_fma_f32 v[12:13], v[62:63], v[170:171], v[12:13] op_sel_hi:[1,0,1]
	v_pk_fma_f32 v[8:9], v[64:65], v[170:171], v[8:9] op_sel_hi:[1,0,1]
	v_pk_fma_f32 v[10:11], v[62:63], v[172:173], v[10:11] op_sel_hi:[1,0,1]
	v_pk_fma_f32 v[6:7], v[64:65], v[172:173], v[6:7] op_sel_hi:[1,0,1]
	v_pk_fma_f32 v[4:5], v[62:63], v[174:175], v[4:5] op_sel_hi:[1,0,1]
	v_pk_fma_f32 v[2:3], v[64:65], v[174:175], v[2:3] op_sel_hi:[1,0,1]
	s_waitcnt vmcnt(5)
	v_pk_fma_f32 v[38:39], v[72:73], v[48:49], v[38:39] op_sel_hi:[1,0,1]
	v_pk_fma_f32 v[40:41], v[70:71], v[48:49], v[40:41] op_sel_hi:[1,0,1]
	v_pk_fma_f32 v[32:33], v[72:73], v[50:51], v[32:33] op_sel_hi:[1,0,1]
	v_pk_fma_f32 v[36:37], v[70:71], v[50:51], v[36:37] op_sel_hi:[1,0,1]
	v_pk_fma_f32 v[26:27], v[72:73], v[108:109], v[26:27] op_sel_hi:[1,0,1]
	v_pk_fma_f32 v[30:31], v[70:71], v[108:109], v[30:31] op_sel_hi:[1,0,1]
	v_pk_fma_f32 v[22:23], v[72:73], v[110:111], v[22:23] op_sel_hi:[1,0,1]
	v_pk_fma_f32 v[24:25], v[70:71], v[110:111], v[24:25] op_sel_hi:[1,0,1]
	v_pk_fma_f32 v[18:19], v[72:73], v[112:113], v[18:19] op_sel_hi:[1,0,1]
	v_pk_fma_f32 v[20:21], v[70:71], v[112:113], v[20:21] op_sel_hi:[1,0,1]
	v_pk_fma_f32 v[14:15], v[72:73], v[114:115], v[14:15] op_sel_hi:[1,0,1]
	v_pk_fma_f32 v[16:17], v[70:71], v[114:115], v[16:17] op_sel_hi:[1,0,1]
	v_pk_fma_f32 v[8:9], v[72:73], v[116:117], v[8:9] op_sel_hi:[1,0,1]
	v_pk_fma_f32 v[12:13], v[70:71], v[116:117], v[12:13] op_sel_hi:[1,0,1]
	v_pk_fma_f32 v[6:7], v[72:73], v[118:119], v[6:7] op_sel_hi:[1,0,1]
	v_pk_fma_f32 v[10:11], v[70:71], v[118:119], v[10:11] op_sel_hi:[1,0,1]
	v_pk_fma_f32 v[2:3], v[72:73], v[120:121], v[2:3] op_sel_hi:[1,0,1]
	v_pk_fma_f32 v[4:5], v[70:71], v[120:121], v[4:5] op_sel_hi:[1,0,1]
	s_waitcnt vmcnt(4)
	v_pk_fma_f32 v[38:39], v[76:77], v[150:151], v[38:39] op_sel_hi:[1,0,1]
	v_pk_fma_f32 v[40:41], v[74:75], v[150:151], v[40:41] op_sel_hi:[1,0,1]
	v_pk_fma_f32 v[32:33], v[76:77], v[152:153], v[32:33] op_sel_hi:[1,0,1]
	v_pk_fma_f32 v[36:37], v[74:75], v[152:153], v[36:37] op_sel_hi:[1,0,1]
	v_pk_fma_f32 v[26:27], v[76:77], v[176:177], v[26:27] op_sel_hi:[1,0,1]
	v_pk_fma_f32 v[30:31], v[74:75], v[176:177], v[30:31] op_sel_hi:[1,0,1]
	v_pk_fma_f32 v[22:23], v[76:77], v[178:179], v[22:23] op_sel_hi:[1,0,1]
	v_pk_fma_f32 v[24:25], v[74:75], v[178:179], v[24:25] op_sel_hi:[1,0,1]
	v_pk_fma_f32 v[18:19], v[76:77], v[180:181], v[18:19] op_sel_hi:[1,0,1]
	v_pk_fma_f32 v[20:21], v[74:75], v[180:181], v[20:21] op_sel_hi:[1,0,1]
	v_pk_fma_f32 v[14:15], v[76:77], v[182:183], v[14:15] op_sel_hi:[1,0,1]
	v_pk_fma_f32 v[16:17], v[74:75], v[182:183], v[16:17] op_sel_hi:[1,0,1]
	v_pk_fma_f32 v[8:9], v[76:77], v[184:185], v[8:9] op_sel_hi:[1,0,1]
	v_pk_fma_f32 v[12:13], v[74:75], v[184:185], v[12:13] op_sel_hi:[1,0,1]
	v_pk_fma_f32 v[6:7], v[76:77], v[186:187], v[6:7] op_sel_hi:[1,0,1]
	v_pk_fma_f32 v[10:11], v[74:75], v[186:187], v[10:11] op_sel_hi:[1,0,1]
	v_pk_fma_f32 v[2:3], v[76:77], v[188:189], v[2:3] op_sel_hi:[1,0,1]
	v_pk_fma_f32 v[4:5], v[74:75], v[188:189], v[4:5] op_sel_hi:[1,0,1]
	s_waitcnt vmcnt(3)
	v_pk_fma_f32 v[38:39], v[80:81], v[52:53], v[38:39] op_sel_hi:[1,0,1]
	v_pk_fma_f32 v[40:41], v[78:79], v[52:53], v[40:41] op_sel_hi:[1,0,1]
	v_pk_fma_f32 v[32:33], v[80:81], v[54:55], v[32:33] op_sel_hi:[1,0,1]
	v_pk_fma_f32 v[36:37], v[78:79], v[54:55], v[36:37] op_sel_hi:[1,0,1]
	v_pk_fma_f32 v[26:27], v[80:81], v[122:123], v[26:27] op_sel_hi:[1,0,1]
	v_pk_fma_f32 v[30:31], v[78:79], v[122:123], v[30:31] op_sel_hi:[1,0,1]
	v_pk_fma_f32 v[22:23], v[80:81], v[124:125], v[22:23] op_sel_hi:[1,0,1]
	v_pk_fma_f32 v[24:25], v[78:79], v[124:125], v[24:25] op_sel_hi:[1,0,1]
	v_pk_fma_f32 v[18:19], v[80:81], v[126:127], v[18:19] op_sel_hi:[1,0,1]
	v_pk_fma_f32 v[20:21], v[78:79], v[126:127], v[20:21] op_sel_hi:[1,0,1]
	v_pk_fma_f32 v[14:15], v[80:81], v[128:129], v[14:15] op_sel_hi:[1,0,1]
	v_pk_fma_f32 v[16:17], v[78:79], v[128:129], v[16:17] op_sel_hi:[1,0,1]
	v_pk_fma_f32 v[8:9], v[80:81], v[130:131], v[8:9] op_sel_hi:[1,0,1]
	v_pk_fma_f32 v[12:13], v[78:79], v[130:131], v[12:13] op_sel_hi:[1,0,1]
	v_pk_fma_f32 v[6:7], v[80:81], v[132:133], v[6:7] op_sel_hi:[1,0,1]
	v_pk_fma_f32 v[10:11], v[78:79], v[132:133], v[10:11] op_sel_hi:[1,0,1]
	v_pk_fma_f32 v[2:3], v[80:81], v[134:135], v[2:3] op_sel_hi:[1,0,1]
	v_pk_fma_f32 v[4:5], v[78:79], v[134:135], v[4:5] op_sel_hi:[1,0,1]
	s_waitcnt vmcnt(2)
	v_pk_fma_f32 v[38:39], v[84:85], v[154:155], v[38:39] op_sel_hi:[1,0,1]
	v_pk_fma_f32 v[40:41], v[82:83], v[154:155], v[40:41] op_sel_hi:[1,0,1]
	v_pk_fma_f32 v[32:33], v[84:85], v[156:157], v[32:33] op_sel_hi:[1,0,1]
	v_pk_fma_f32 v[36:37], v[82:83], v[156:157], v[36:37] op_sel_hi:[1,0,1]
	v_pk_fma_f32 v[26:27], v[84:85], v[190:191], v[26:27] op_sel_hi:[1,0,1]
	v_pk_fma_f32 v[30:31], v[82:83], v[190:191], v[30:31] op_sel_hi:[1,0,1]
	v_pk_fma_f32 v[22:23], v[84:85], v[192:193], v[22:23] op_sel_hi:[1,0,1]
	v_pk_fma_f32 v[24:25], v[82:83], v[192:193], v[24:25] op_sel_hi:[1,0,1]
	v_pk_fma_f32 v[18:19], v[84:85], v[194:195], v[18:19] op_sel_hi:[1,0,1]
	v_pk_fma_f32 v[20:21], v[82:83], v[194:195], v[20:21] op_sel_hi:[1,0,1]
	v_pk_fma_f32 v[14:15], v[84:85], v[196:197], v[14:15] op_sel_hi:[1,0,1]
	v_pk_fma_f32 v[16:17], v[82:83], v[196:197], v[16:17] op_sel_hi:[1,0,1]
	v_pk_fma_f32 v[8:9], v[84:85], v[198:199], v[8:9] op_sel_hi:[1,0,1]
	v_pk_fma_f32 v[12:13], v[82:83], v[198:199], v[12:13] op_sel_hi:[1,0,1]
	v_pk_fma_f32 v[6:7], v[84:85], v[200:201], v[6:7] op_sel_hi:[1,0,1]
	v_pk_fma_f32 v[10:11], v[82:83], v[200:201], v[10:11] op_sel_hi:[1,0,1]
	v_pk_fma_f32 v[2:3], v[84:85], v[202:203], v[2:3] op_sel_hi:[1,0,1]
	v_pk_fma_f32 v[4:5], v[82:83], v[202:203], v[4:5] op_sel_hi:[1,0,1]
	s_waitcnt vmcnt(1)
	v_pk_fma_f32 v[38:39], v[88:89], v[56:57], v[38:39] op_sel_hi:[1,0,1]
	v_pk_fma_f32 v[40:41], v[86:87], v[56:57], v[40:41] op_sel_hi:[1,0,1]
	v_pk_fma_f32 v[32:33], v[88:89], v[58:59], v[32:33] op_sel_hi:[1,0,1]
	v_pk_fma_f32 v[36:37], v[86:87], v[58:59], v[36:37] op_sel_hi:[1,0,1]
	v_pk_fma_f32 v[26:27], v[88:89], v[136:137], v[26:27] op_sel_hi:[1,0,1]
	v_pk_fma_f32 v[30:31], v[86:87], v[136:137], v[30:31] op_sel_hi:[1,0,1]
	v_pk_fma_f32 v[22:23], v[88:89], v[138:139], v[22:23] op_sel_hi:[1,0,1]
	v_pk_fma_f32 v[24:25], v[86:87], v[138:139], v[24:25] op_sel_hi:[1,0,1]
	v_pk_fma_f32 v[18:19], v[88:89], v[140:141], v[18:19] op_sel_hi:[1,0,1]
	v_pk_fma_f32 v[20:21], v[86:87], v[140:141], v[20:21] op_sel_hi:[1,0,1]
	v_pk_fma_f32 v[14:15], v[88:89], v[142:143], v[14:15] op_sel_hi:[1,0,1]
	v_pk_fma_f32 v[16:17], v[86:87], v[142:143], v[16:17] op_sel_hi:[1,0,1]
	v_pk_fma_f32 v[8:9], v[88:89], v[144:145], v[8:9] op_sel_hi:[1,0,1]
	v_pk_fma_f32 v[12:13], v[86:87], v[144:145], v[12:13] op_sel_hi:[1,0,1]
	v_pk_fma_f32 v[6:7], v[88:89], v[146:147], v[6:7] op_sel_hi:[1,0,1]
	v_pk_fma_f32 v[10:11], v[86:87], v[146:147], v[10:11] op_sel_hi:[1,0,1]
	v_pk_fma_f32 v[2:3], v[88:89], v[148:149], v[2:3] op_sel_hi:[1,0,1]
	v_pk_fma_f32 v[4:5], v[86:87], v[148:149], v[4:5] op_sel_hi:[1,0,1]
	s_waitcnt vmcnt(0)
	v_pk_fma_f32 v[38:39], v[92:93], v[158:159], v[38:39] op_sel_hi:[1,0,1]
	v_pk_fma_f32 v[40:41], v[90:91], v[158:159], v[40:41] op_sel_hi:[1,0,1]
	v_pk_fma_f32 v[32:33], v[92:93], v[160:161], v[32:33] op_sel_hi:[1,0,1]
	v_pk_fma_f32 v[36:37], v[90:91], v[160:161], v[36:37] op_sel_hi:[1,0,1]
	v_pk_fma_f32 v[26:27], v[92:93], v[204:205], v[26:27] op_sel_hi:[1,0,1]
	v_pk_fma_f32 v[30:31], v[90:91], v[204:205], v[30:31] op_sel_hi:[1,0,1]
	v_pk_fma_f32 v[22:23], v[92:93], v[206:207], v[22:23] op_sel_hi:[1,0,1]
	v_pk_fma_f32 v[24:25], v[90:91], v[206:207], v[24:25] op_sel_hi:[1,0,1]
	v_pk_fma_f32 v[18:19], v[92:93], v[208:209], v[18:19] op_sel_hi:[1,0,1]
	v_pk_fma_f32 v[20:21], v[90:91], v[208:209], v[20:21] op_sel_hi:[1,0,1]
	v_pk_fma_f32 v[14:15], v[92:93], v[210:211], v[14:15] op_sel_hi:[1,0,1]
	v_pk_fma_f32 v[16:17], v[90:91], v[210:211], v[16:17] op_sel_hi:[1,0,1]
	v_pk_fma_f32 v[8:9], v[92:93], v[212:213], v[8:9] op_sel_hi:[1,0,1]
	v_pk_fma_f32 v[12:13], v[90:91], v[212:213], v[12:13] op_sel_hi:[1,0,1]
	v_pk_fma_f32 v[6:7], v[92:93], v[214:215], v[6:7] op_sel_hi:[1,0,1]
	v_pk_fma_f32 v[10:11], v[90:91], v[214:215], v[10:11] op_sel_hi:[1,0,1]
	v_pk_fma_f32 v[2:3], v[92:93], v[216:217], v[2:3] op_sel_hi:[1,0,1]
	v_pk_fma_f32 v[4:5], v[90:91], v[216:217], v[4:5] op_sel_hi:[1,0,1]
	s_cbranch_scc0 .LBB0_12
	v_mbcnt_lo_u32_b32 v28, -1, 0
	v_mbcnt_hi_u32_b32 v29, -1, v28
	v_and_b32_e32 v35, 64, v29
	v_xor_b32_e32 v28, 16, v29
	v_add_u32_e32 v35, 64, v35
	v_cmp_lt_i32_e32 vcc, v28, v35
	v_xor_b32_e32 v43, 32, v29
	s_mul_i32 s1, s24, 0x900
	v_cndmask_b32_e32 v28, v29, v28, vcc
	v_lshlrev_b32_e32 v28, 2, v28
	v_mov_b32_e32 v42, v40
	s_nop 1
	v_permlane16_swap_b32_e32 v40, v42
	v_cmp_lt_i32_e32 vcc, v43, v35
	v_add_f32_e32 v40, v40, v42
	v_cndmask_b32_e32 v29, v29, v43, vcc
	v_lshlrev_b32_e32 v35, 2, v29
	v_mov_b32_e32 v42, v40
	s_nop 1
	v_permlane32_swap_b32_e32 v40, v42
	v_lshl_add_u32 v29, v61, 4, 0
	v_cmp_gt_u32_e32 vcc, 16, v61
	v_add_u32_e32 v29, s1, v29
	s_and_saveexec_b64 s[6:7], vcc
	s_cbranch_execz .LBB0_15
	v_add_f32_e32 v40, v40, v42
	ds_write_b32 v29, v40 offset:40960
.LBB0_15:
	s_or_b64 exec, exec, s[6:7]
	v_mov_b32_e32 v40, v41
	s_nop 1
	v_permlane16_swap_b32_e32 v41, v40
	v_add_f32_e32 v40, v41, v40
	v_mov_b32_e32 v41, v40
	s_nop 1
	v_permlane32_swap_b32_e32 v40, v41
	s_and_saveexec_b64 s[6:7], vcc
	s_cbranch_execz .LBB0_17
	v_add_f32_e32 v40, v40, v41
	ds_write_b32 v29, v40 offset:40964
.LBB0_17:
	s_or_b64 exec, exec, s[6:7]
	v_mov_b32_e32 v40, v38
	s_nop 1
	v_permlane16_swap_b32_e32 v38, v40
	v_add_f32_e32 v38, v38, v40
	v_mov_b32_e32 v40, v38
	s_nop 1
	v_permlane32_swap_b32_e32 v38, v40
	s_and_saveexec_b64 s[6:7], vcc
	s_cbranch_execz .LBB0_19
	v_add_f32_e32 v38, v38, v40
	ds_write_b32 v29, v38 offset:40968
.LBB0_19:
	s_or_b64 exec, exec, s[6:7]
	v_mov_b32_e32 v38, v39
	s_nop 1
	v_permlane16_swap_b32_e32 v39, v38
	v_add_f32_e32 v38, v39, v38
	v_mov_b32_e32 v39, v38
	s_nop 1
	v_permlane32_swap_b32_e32 v38, v39
	s_and_saveexec_b64 s[6:7], vcc
	s_cbranch_execz .LBB0_21
	v_add_f32_e32 v38, v38, v39
	ds_write_b32 v29, v38 offset:40972
.LBB0_21:
	s_or_b64 exec, exec, s[6:7]
	v_mov_b32_e32 v38, v36
	s_nop 1
	v_permlane16_swap_b32_e32 v36, v38
	v_add_f32_e32 v36, v36, v38
	v_mov_b32_e32 v38, v36
	s_nop 1
	v_permlane32_swap_b32_e32 v36, v38
	s_and_saveexec_b64 s[6:7], vcc
	s_cbranch_execz .LBB0_23
	v_add_f32_e32 v36, v36, v38
	ds_write_b32 v29, v36 offset:41216
.LBB0_23:
	s_or_b64 exec, exec, s[6:7]
	v_mov_b32_e32 v36, v37
	s_nop 1
	v_permlane16_swap_b32_e32 v37, v36
	v_add_f32_e32 v36, v37, v36
	v_mov_b32_e32 v37, v36
	s_nop 1
	v_permlane32_swap_b32_e32 v36, v37
	s_and_saveexec_b64 s[6:7], vcc
	s_cbranch_execz .LBB0_25
	v_add_f32_e32 v36, v36, v37
	ds_write_b32 v29, v36 offset:41220
.LBB0_25:
	s_or_b64 exec, exec, s[6:7]
	v_mov_b32_e32 v36, v32
	s_nop 1
	v_permlane16_swap_b32_e32 v32, v36
	v_add_f32_e32 v32, v32, v36
	v_mov_b32_e32 v36, v32
	s_nop 1
	v_permlane32_swap_b32_e32 v32, v36
	s_and_saveexec_b64 s[6:7], vcc
	s_cbranch_execz .LBB0_27
	v_add_f32_e32 v32, v32, v36
	ds_write_b32 v29, v32 offset:41224
.LBB0_27:
	s_or_b64 exec, exec, s[6:7]
	v_mov_b32_e32 v32, v33
	s_nop 1
	v_permlane16_swap_b32_e32 v33, v32
	v_add_f32_e32 v32, v33, v32
	v_mov_b32_e32 v33, v32
	s_nop 1
	v_permlane32_swap_b32_e32 v32, v33
	s_and_saveexec_b64 s[6:7], vcc
	s_cbranch_execz .LBB0_29
	v_add_f32_e32 v32, v32, v33
	ds_write_b32 v29, v32 offset:41228
.LBB0_29:
	s_or_b64 exec, exec, s[6:7]
	v_mov_b32_e32 v32, v30
	s_nop 1
	v_permlane16_swap_b32_e32 v30, v32
	v_add_f32_e32 v30, v30, v32
	v_mov_b32_e32 v32, v30
	s_nop 1
	v_permlane32_swap_b32_e32 v30, v32
	s_and_saveexec_b64 s[6:7], vcc
	s_cbranch_execz .LBB0_31
	v_add_f32_e32 v30, v30, v32
	ds_write_b32 v29, v30 offset:41472
.LBB0_31:
	s_or_b64 exec, exec, s[6:7]
	v_mov_b32_e32 v30, v31
	s_nop 1
	v_permlane16_swap_b32_e32 v31, v30
	v_add_f32_e32 v30, v31, v30
	v_mov_b32_e32 v31, v30
	s_nop 1
	v_permlane32_swap_b32_e32 v30, v31
	s_and_saveexec_b64 s[6:7], vcc
	s_cbranch_execz .LBB0_33
	v_add_f32_e32 v30, v30, v31
	ds_write_b32 v29, v30 offset:41476
.LBB0_33:
	s_or_b64 exec, exec, s[6:7]
	v_mov_b32_e32 v30, v26
	s_nop 1
	v_permlane16_swap_b32_e32 v26, v30
	v_add_f32_e32 v26, v26, v30
	v_mov_b32_e32 v30, v26
	s_nop 1
	v_permlane32_swap_b32_e32 v26, v30
	s_and_saveexec_b64 s[6:7], vcc
	s_cbranch_execz .LBB0_35
	v_add_f32_e32 v26, v26, v30
	ds_write_b32 v29, v26 offset:41480
.LBB0_35:
	s_or_b64 exec, exec, s[6:7]
	v_mov_b32_e32 v26, v27
	s_nop 1
	v_permlane16_swap_b32_e32 v27, v26
	v_add_f32_e32 v26, v27, v26
	v_mov_b32_e32 v27, v26
	s_nop 1
	v_permlane32_swap_b32_e32 v26, v27
	s_and_saveexec_b64 s[6:7], vcc
	s_cbranch_execz .LBB0_37
	v_add_f32_e32 v26, v26, v27
	ds_write_b32 v29, v26 offset:41484
.LBB0_37:
	s_or_b64 exec, exec, s[6:7]
	v_mov_b32_e32 v26, v24
	s_nop 1
	v_permlane16_swap_b32_e32 v24, v26
	v_add_f32_e32 v24, v24, v26
	v_mov_b32_e32 v26, v24
	s_nop 1
	v_permlane32_swap_b32_e32 v24, v26
	s_and_saveexec_b64 s[6:7], vcc
	s_cbranch_execz .LBB0_39
	v_add_f32_e32 v24, v24, v26
	ds_write_b32 v29, v24 offset:41728
.LBB0_39:
	s_or_b64 exec, exec, s[6:7]
	v_mov_b32_e32 v24, v25
	s_nop 1
	v_permlane16_swap_b32_e32 v25, v24
	v_add_f32_e32 v24, v25, v24
	v_mov_b32_e32 v25, v24
	s_nop 1
	v_permlane32_swap_b32_e32 v24, v25
	s_and_saveexec_b64 s[6:7], vcc
	s_cbranch_execz .LBB0_41
	v_add_f32_e32 v24, v24, v25
	ds_write_b32 v29, v24 offset:41732
.LBB0_41:
	s_or_b64 exec, exec, s[6:7]
	v_mov_b32_e32 v24, v22
	s_nop 1
	v_permlane16_swap_b32_e32 v22, v24
	v_add_f32_e32 v22, v22, v24
	v_mov_b32_e32 v24, v22
	s_nop 1
	v_permlane32_swap_b32_e32 v22, v24
	s_and_saveexec_b64 s[6:7], vcc
	s_cbranch_execz .LBB0_43
	v_add_f32_e32 v22, v22, v24
	ds_write_b32 v29, v22 offset:41736
.LBB0_43:
	s_or_b64 exec, exec, s[6:7]
	v_mov_b32_e32 v22, v23
	s_nop 1
	v_permlane16_swap_b32_e32 v23, v22
	v_add_f32_e32 v22, v23, v22
	v_mov_b32_e32 v23, v22
	s_nop 1
	v_permlane32_swap_b32_e32 v22, v23
	s_and_saveexec_b64 s[6:7], vcc
	s_cbranch_execz .LBB0_45
	v_add_f32_e32 v22, v22, v23
	ds_write_b32 v29, v22 offset:41740
.LBB0_45:
	s_or_b64 exec, exec, s[6:7]
	v_mov_b32_e32 v22, v20
	s_nop 1
	v_permlane16_swap_b32_e32 v20, v22
	v_add_f32_e32 v20, v20, v22
	v_mov_b32_e32 v22, v20
	s_nop 1
	v_permlane32_swap_b32_e32 v20, v22
	s_and_saveexec_b64 s[6:7], vcc
	s_cbranch_execz .LBB0_47
	v_add_f32_e32 v20, v20, v22
	ds_write_b32 v29, v20 offset:41984
.LBB0_47:
	s_or_b64 exec, exec, s[6:7]
	v_mov_b32_e32 v20, v21
	s_nop 1
	v_permlane16_swap_b32_e32 v21, v20
	v_add_f32_e32 v20, v21, v20
	v_mov_b32_e32 v21, v20
	s_nop 1
	v_permlane32_swap_b32_e32 v20, v21
	s_and_saveexec_b64 s[6:7], vcc
	s_cbranch_execz .LBB0_49
	v_add_f32_e32 v20, v20, v21
	ds_write_b32 v29, v20 offset:41988
.LBB0_49:
	s_or_b64 exec, exec, s[6:7]
	v_mov_b32_e32 v20, v18
	s_nop 1
	v_permlane16_swap_b32_e32 v18, v20
	v_add_f32_e32 v18, v18, v20
	v_mov_b32_e32 v20, v18
	s_nop 1
	v_permlane32_swap_b32_e32 v18, v20
	s_and_saveexec_b64 s[6:7], vcc
	s_cbranch_execz .LBB0_51
	v_add_f32_e32 v18, v18, v20
	ds_write_b32 v29, v18 offset:41992
.LBB0_51:
	s_or_b64 exec, exec, s[6:7]
	v_mov_b32_e32 v18, v19
	s_nop 1
	v_permlane16_swap_b32_e32 v19, v18
	v_add_f32_e32 v18, v19, v18
	v_mov_b32_e32 v19, v18
	s_nop 1
	v_permlane32_swap_b32_e32 v18, v19
	s_and_saveexec_b64 s[6:7], vcc
	s_cbranch_execz .LBB0_53
	v_add_f32_e32 v18, v18, v19
	ds_write_b32 v29, v18 offset:41996
.LBB0_53:
	s_or_b64 exec, exec, s[6:7]
	v_mov_b32_e32 v18, v16
	s_nop 1
	v_permlane16_swap_b32_e32 v16, v18
	v_add_f32_e32 v16, v16, v18
	v_mov_b32_e32 v18, v16
	s_nop 1
	v_permlane32_swap_b32_e32 v16, v18
	s_and_saveexec_b64 s[6:7], vcc
	s_cbranch_execz .LBB0_55
	v_add_f32_e32 v16, v16, v18
	ds_write_b32 v29, v16 offset:42240
.LBB0_55:
	s_or_b64 exec, exec, s[6:7]
	v_mov_b32_e32 v16, v17
	s_nop 1
	v_permlane16_swap_b32_e32 v17, v16
	v_add_f32_e32 v16, v17, v16
	v_mov_b32_e32 v17, v16
	s_nop 1
	v_permlane32_swap_b32_e32 v16, v17
	s_and_saveexec_b64 s[6:7], vcc
	s_cbranch_execz .LBB0_57
	v_add_f32_e32 v16, v16, v17
	ds_write_b32 v29, v16 offset:42244
.LBB0_57:
	s_or_b64 exec, exec, s[6:7]
	v_mov_b32_e32 v16, v14
	s_nop 1
	v_permlane16_swap_b32_e32 v14, v16
	v_add_f32_e32 v14, v14, v16
	v_mov_b32_e32 v16, v14
	s_nop 1
	v_permlane32_swap_b32_e32 v14, v16
	s_and_saveexec_b64 s[6:7], vcc
	s_cbranch_execz .LBB0_59
	v_add_f32_e32 v14, v14, v16
	ds_write_b32 v29, v14 offset:42248
.LBB0_59:
	s_or_b64 exec, exec, s[6:7]
	v_mov_b32_e32 v14, v15
	s_nop 1
	v_permlane16_swap_b32_e32 v15, v14
	v_add_f32_e32 v14, v15, v14
	v_mov_b32_e32 v15, v14
	s_nop 1
	v_permlane32_swap_b32_e32 v14, v15
	s_and_saveexec_b64 s[6:7], vcc
	s_cbranch_execz .LBB0_61
	v_add_f32_e32 v14, v14, v15
	ds_write_b32 v29, v14 offset:42252
.LBB0_61:
	s_or_b64 exec, exec, s[6:7]
	v_mov_b32_e32 v14, v12
	s_nop 1
	v_permlane16_swap_b32_e32 v12, v14
	v_add_f32_e32 v12, v12, v14
	v_mov_b32_e32 v14, v12
	s_nop 1
	v_permlane32_swap_b32_e32 v12, v14
	s_and_saveexec_b64 s[6:7], vcc
	s_cbranch_execz .LBB0_63
	v_add_f32_e32 v12, v12, v14
	ds_write_b32 v29, v12 offset:42496
.LBB0_63:
	s_or_b64 exec, exec, s[6:7]
	v_mov_b32_e32 v12, v13
	s_nop 1
	v_permlane16_swap_b32_e32 v13, v12
	v_add_f32_e32 v12, v13, v12
	v_mov_b32_e32 v13, v12
	s_nop 1
	v_permlane32_swap_b32_e32 v12, v13
	s_and_saveexec_b64 s[6:7], vcc
	s_cbranch_execz .LBB0_65
	v_add_f32_e32 v12, v12, v13
	ds_write_b32 v29, v12 offset:42500
.LBB0_65:
	s_or_b64 exec, exec, s[6:7]
	v_mov_b32_e32 v12, v8
	s_nop 1
	v_permlane16_swap_b32_e32 v8, v12
	v_add_f32_e32 v8, v8, v12
	v_mov_b32_e32 v12, v8
	s_nop 1
	v_permlane32_swap_b32_e32 v8, v12
	s_and_saveexec_b64 s[6:7], vcc
	s_cbranch_execz .LBB0_67
	v_add_f32_e32 v8, v8, v12
	ds_write_b32 v29, v8 offset:42504
.LBB0_67:
	s_or_b64 exec, exec, s[6:7]
	v_mov_b32_e32 v8, v9
	s_nop 1
	v_permlane16_swap_b32_e32 v9, v8
	v_add_f32_e32 v8, v9, v8
	v_mov_b32_e32 v9, v8
	s_nop 1
	v_permlane32_swap_b32_e32 v8, v9
	s_and_saveexec_b64 s[6:7], vcc
	s_cbranch_execz .LBB0_69
	v_add_f32_e32 v8, v8, v9
	ds_write_b32 v29, v8 offset:42508
.LBB0_69:
	s_or_b64 exec, exec, s[6:7]
	v_mov_b32_e32 v8, v10
	s_nop 1
	v_permlane16_swap_b32_e32 v10, v8
	v_add_f32_e32 v8, v10, v8
	v_mov_b32_e32 v9, v8
	s_nop 1
	v_permlane32_swap_b32_e32 v8, v9
	s_and_saveexec_b64 s[6:7], vcc
	s_cbranch_execz .LBB0_71
	v_add_f32_e32 v8, v8, v9
	ds_write_b32 v29, v8 offset:42752
.LBB0_71:
	s_or_b64 exec, exec, s[6:7]
	v_mov_b32_e32 v8, v11
	s_nop 1
	v_permlane16_swap_b32_e32 v11, v8
	v_add_f32_e32 v8, v11, v8
	v_mov_b32_e32 v9, v8
	s_nop 1
	v_permlane32_swap_b32_e32 v8, v9
	s_and_saveexec_b64 s[6:7], vcc
	s_cbranch_execz .LBB0_73
	v_add_f32_e32 v8, v8, v9
	ds_write_b32 v29, v8 offset:42756
.LBB0_73:
	s_or_b64 exec, exec, s[6:7]
	v_mov_b32_e32 v8, v6
	s_nop 1
	v_permlane16_swap_b32_e32 v6, v8
	v_add_f32_e32 v6, v6, v8
	v_mov_b32_e32 v8, v6
	s_nop 1
	v_permlane32_swap_b32_e32 v6, v8
	s_and_saveexec_b64 s[6:7], vcc
	s_cbranch_execz .LBB0_75
	v_add_f32_e32 v6, v6, v8
	ds_write_b32 v29, v6 offset:42760
.LBB0_75:
	s_or_b64 exec, exec, s[6:7]
	v_mov_b32_e32 v6, v7
	s_nop 1
	v_permlane16_swap_b32_e32 v7, v6
	v_add_f32_e32 v6, v7, v6
	v_mov_b32_e32 v7, v6
	s_nop 1
	v_permlane32_swap_b32_e32 v6, v7
	s_and_saveexec_b64 s[6:7], vcc
	s_cbranch_execz .LBB0_77
	v_add_f32_e32 v6, v6, v7
	ds_write_b32 v29, v6 offset:42764
.LBB0_77:
	s_or_b64 exec, exec, s[6:7]
	v_mov_b32_e32 v6, v4
	s_nop 1
	v_permlane16_swap_b32_e32 v4, v6
	v_add_f32_e32 v4, v4, v6
	v_mov_b32_e32 v6, v4
	s_nop 1
	v_permlane32_swap_b32_e32 v4, v6
	s_and_saveexec_b64 s[6:7], vcc
	s_cbranch_execz .LBB0_79
	v_add_f32_e32 v4, v4, v6
	ds_write_b32 v29, v4 offset:43008
.LBB0_79:
	s_or_b64 exec, exec, s[6:7]
	v_mov_b32_e32 v4, v5
	s_nop 1
	v_permlane16_swap_b32_e32 v5, v4
	v_add_f32_e32 v4, v5, v4
	v_mov_b32_e32 v5, v4
	s_nop 1
	v_permlane32_swap_b32_e32 v4, v5
	s_and_saveexec_b64 s[6:7], vcc
	s_cbranch_execz .LBB0_81
	v_add_f32_e32 v4, v4, v5
	ds_write_b32 v29, v4 offset:43012
.LBB0_81:
	s_or_b64 exec, exec, s[6:7]
	v_mov_b32_e32 v4, v2
	s_nop 1
	v_permlane16_swap_b32_e32 v2, v4
	v_add_f32_e32 v2, v2, v4
	v_mov_b32_e32 v4, v2
	s_nop 1
	v_permlane32_swap_b32_e32 v2, v4
	s_and_saveexec_b64 s[6:7], vcc
	s_cbranch_execz .LBB0_83
	v_add_f32_e32 v2, v2, v4
	ds_write_b32 v29, v2 offset:43016
.LBB0_83:
	s_or_b64 exec, exec, s[6:7]
	v_mov_b32_e32 v2, v3
	s_nop 1
	v_permlane16_swap_b32_e32 v3, v2
	v_add_f32_e32 v2, v3, v2
	v_mov_b32_e32 v3, v2
	s_nop 1
	v_permlane32_swap_b32_e32 v2, v3
	s_and_saveexec_b64 s[6:7], vcc
	s_cbranch_execz .LBB0_85
	v_add_f32_e32 v2, v2, v3
	ds_write_b32 v29, v2 offset:43020

.LBB0_340:
	v_readlane_b32 s0, v254, 7
	v_mov_b32_e32 v2, v0
	v_readlane_b32 s10, v250, 11
	s_waitcnt lgkmcnt(0)
	v_mov_b32_e32 v3, s0
	v_readlane_b32 s0, v254, 8
	ds_read_b64 v[4:5], v3
	v_readlane_b32 s11, v250, 12
	v_mov_b32_e32 v3, s0
	v_readlane_b32 s0, v254, 9
	ds_read_b64 v[6:7], v3
	v_readfirstlane_b32 s9, v2
	v_mov_b32_e32 v3, s0
	ds_read_b64 v[8:9], v3
	s_waitcnt lgkmcnt(0)
	v_readfirstlane_b32 s2, v4
	v_readfirstlane_b32 s4, v5
	v_readfirstlane_b32 s7, v6
	v_readfirstlane_b32 s8, v7
	v_readfirstlane_b32 s0, v8
	s_andn2_b64 vcc, exec, s[10:11]
	v_readfirstlane_b32 s1, v9
	s_cbranch_vccnz .LBB0_354
	s_ashr_i32 s9, s9, 6
	v_readlane_b32 s10, v250, 17
	s_add_i32 s10, s10, s9
	v_lshlrev_b32_e32 v2, 2, v2
	s_cmpk_lt_i32 s10, 0x4800
	v_and_b32_e32 v14, 0xfc, v2
	s_cselect_b64 s[40:41], -1, 0
	s_and_b64 vcc, exec, s[40:41]
	v_lshlrev_b32_e32 v98, 2, v14
	s_mov_b32 s100, s9
.Lmy_n1_stage:
	s_cmp_lt_u32 s100, 4
	s_cbranch_scc0 .Lmy_n1_mod
	s_lshl_b32 s101, s100, 10
	s_add_u32 s12, s0, s101
	s_addc_u32 s13, s1, 0
	s_branch .Lmy_n1_issue
.Lmy_n1_mod:
	s_sub_u32 s101, s100, 4
	s_lshr_b32 s14, s101, 3
	s_mul_i32 s14, s14, 0x6000
	s_and_b32 s101, s101, 7
	s_lshl_b32 s101, s101, 10
	s_add_u32 s101, s101, s14
	v_readlane_b32 s12, v250, 14
	v_readlane_b32 s13, v250, 15
	s_nop 3
	s_add_u32 s12, s12, s101
	s_addc_u32 s13, s13, 0
.Lmy_n1_issue:
	s_lshl_b32 s101, s100, 10
	s_mov_b32 m0, s101
	s_nop 4
	global_load_lds_dwordx4 v98, s[12:13]
	s_add_u32 s100, s100, 8
	s_cmp_lt_u32 s100, 76
	s_cbranch_scc1 .Lmy_n1_stage
	s_waitcnt vmcnt(0)
	s_barrier
	s_cbranch_vccz .LBB0_343
	s_add_i32 s11, s10, 0xffffc000
	s_ashr_i32 s12, s10, 31
	s_cmpk_lt_i32 s10, 0x4000
	s_cselect_b32 s13, s12, 0
	s_cselect_b32 s12, s10, s11
	s_cselect_b32 s11, s4, s8
	s_cselect_b32 s14, s2, s7
	s_lshl_b64 s[12:13], s[12:13], 12
	s_add_u32 s12, s14, s12
	s_addc_u32 s13, s11, s13
	global_load_dwordx4 v[62:65], v98, s[12:13] nt
	global_load_dwordx4 v[58:61], v98, s[12:13] offset:1024 nt
	global_load_dwordx4 v[54:57], v98, s[12:13] offset:2048 nt
	global_load_dwordx4 v[50:53], v98, s[12:13] offset:3072 nt

.LBB0_347:
	s_waitcnt vmcnt(8)
	s_add_i32 s9, s9, s12
	s_add_i32 s0, s9, 0xffffff80
	v_mov_b64_e32 v[2:3], v[14:15]
	v_mov_b64_e32 v[6:7], v[18:19]
	v_mov_b64_e32 v[10:11], v[22:23]
	v_mov_b64_e32 v[48:49], v[28:29]
	v_mov_b64_e32 v[52:53], v[32:33]
	v_mov_b64_e32 v[56:57], v[36:37]
	v_mov_b64_e32 v[60:61], v[40:41]
	v_mov_b64_e32 v[64:65], v[44:45]
	s_cmpk_lt_i32 s0, 0x4800
	v_mov_b64_e32 v[4:5], v[16:17]
	v_mov_b64_e32 v[8:9], v[20:21]
	v_mov_b64_e32 v[12:13], v[24:25]
	v_mov_b64_e32 v[46:47], v[26:27]
	v_mov_b64_e32 v[50:51], v[30:31]
	v_mov_b64_e32 v[54:55], v[34:35]
	v_mov_b64_e32 v[58:59], v[38:39]
	v_mov_b64_e32 v[62:63], v[42:43]
	s_cbranch_scc0 .LBB0_354

.LBB0_352:
	s_waitcnt vmcnt(8)
	v_pk_mul_f32 v[80:81], v[64:65], v[64:65]
	v_pk_mul_f32 v[82:83], v[62:63], v[62:63]
	v_mul_f32_e32 v76, v54, v54
	v_pk_mov_b32 v[84:85], v[82:83], v[80:81] op_sel:[1,0]
	v_mov_b32_e32 v83, v81
	v_pk_add_f32 v[80:81], v[84:85], v[82:83]
	v_pk_mul_f32 v[82:83], v[60:61], v[60:61]
	v_pk_mul_f32 v[84:85], v[58:59], v[58:59]
	v_pk_add_f32 v[80:81], v[80:81], v[80:81] op_sel_hi:[0,1]
	v_pk_mov_b32 v[86:87], v[84:85], v[82:83] op_sel:[1,0]
	v_mov_b32_e32 v85, v83
	v_pk_add_f32 v[82:83], v[86:87], v[84:85]
	v_pk_fma_f32 v[84:85], v[54:55], v[54:55], v[76:77] op_sel_hi:[1,1,0]
	v_mul_f32_e32 v76, v56, v56
	v_pk_add_f32 v[82:83], v[82:83], v[82:83] op_sel_hi:[0,1]
	v_pk_fma_f32 v[86:87], v[56:57], v[56:57], v[76:77] op_sel_hi:[1,1,0]
	v_mul_f32_e32 v84, v50, v50
	v_mul_f32_e32 v86, v51, v51
	v_mul_f32_e32 v82, v52, v52
	v_mul_f32_e32 v80, v53, v53
	v_pk_add_f32 v[84:85], v[84:85], v[86:87]
	v_pk_add_f32 v[80:81], v[82:83], v[80:81]
	s_add_i32 s44, s9, 0xffffff80
	v_pk_add_f32 v[80:81], v[84:85], v[80:81]
	s_min_i32 s0, s44, 0x4000
	v_add_f32_e32 v76, v80, v81
	s_nop 1
	v_mov_b32_dpp v80, v76 quad_perm:[1,0,3,2] row_mask:0xf bank_mask:0xf
	s_lshr_b32 s0, s0, 11
	s_lshl_b32 s100, s0, 13
	s_mulk_i32 s0, 0x1800
	s_ashr_i32 s1, s0, 31
	s_lshl_b64 s[0:1], s[0:1], 2
	s_waitcnt lgkmcnt(0)
	v_add_f32_e32 v76, v76, v80
	s_nop 1
	v_mov_b32_dpp v80, v76 quad_perm:[2,3,0,1] row_mask:0xf bank_mask:0xf
	v_readlane_b32 s10, v250, 14
	s_add_u32 s40, s10, s0
	s_mov_b32 s0, 0xf800000
	v_readlane_b32 s11, v250, 15
	s_waitcnt lgkmcnt(0)
	v_add_f32_e32 v76, v76, v80
	s_nop 1
	v_mov_b32_dpp v80, v76 row_half_mirror row_mask:0xf bank_mask:0xf
	s_addc_u32 s41, s11, s1
	s_add_u32 s42, s40, 0x1000
	s_addc_u32 s43, s41, 0
	s_ashr_i32 s45, s44, 31
	s_waitcnt lgkmcnt(0)
	v_add_f32_e32 v76, v76, v80
	s_nop 1
	v_mov_b32_dpp v80, v76 row_mirror row_mask:0xf bank_mask:0xf
	s_waitcnt lgkmcnt(0)
	v_add_f32_e32 v76, v76, v80
	v_mov_b32_e32 v80, v76
	s_nop 1
	v_permlane16_swap_b32_e32 v76, v80
	s_waitcnt lgkmcnt(0)
	v_add_f32_e32 v76, v76, v80
	v_mov_b32_e32 v80, v76
	s_nop 1
	v_permlane32_swap_b32_e32 v76, v80
	s_waitcnt lgkmcnt(0)
	v_add_f32_e32 v76, v76, v80
	v_fmamk_f32 v76, v76, 0x3a800000, v212
	v_cmp_gt_f32_e32 vcc, s0, v76
	v_mul_f32_e32 v80, 0x4f800000, v76
	s_nop 0
	v_cndmask_b32_e32 v76, v76, v80, vcc
	v_sqrt_f32_e32 v80, v76
	s_nop 0
	v_add_u32_e32 v81, -1, v80
	v_fma_f32 v82, -v81, v80, v76
	v_cmp_ge_f32_e64 s[0:1], 0, v82
	v_add_u32_e32 v82, 1, v80
	s_nop 0
	v_cndmask_b32_e64 v81, v80, v81, s[0:1]
	v_fma_f32 v80, -v82, v80, v76
	v_cmp_lt_f32_e64 s[0:1], 0, v80
	s_nop 1
	v_cndmask_b32_e64 v80, v81, v82, s[0:1]
	v_mul_f32_e32 v81, 0x37800000, v80
	v_cndmask_b32_e32 v80, v80, v81, vcc
	v_cmp_class_f32_e32 vcc, v76, v241
	s_nop 1
	v_cndmask_b32_e32 v76, v80, v76, vcc
	v_div_scale_f32 v80, s[0:1], v76, v76, 1.0
	v_rcp_f32_e32 v81, v80
	s_lshl_b64 s[0:1], s[44:45], 11
	v_fma_f32 v82, -v80, v81, 1.0
	v_fmac_f32_e32 v81, v82, v81
	v_div_scale_f32 v82, vcc, 1.0, v76, 1.0
	v_mul_f32_e32 v83, v82, v81
	v_fma_f32 v84, -v80, v83, v82
	v_fmac_f32_e32 v83, v84, v81
	v_fma_f32 v80, -v80, v83, v82
	v_div_fmas_f32 v80, v80, v81, v83
	v_div_fixup_f32 v76, v80, v76, 1.0
	v_add_u32_e32 v92, s100, v98
	ds_read_b128 v[80:83], v98
	ds_read_b128 v[84:87], v92 offset:8192
	ds_read_b128 v[88:91], v92 offset:4096
	v_pk_mul_f32 v[64:65], v[64:65], v[76:77] op_sel_hi:[1,0]
	v_pk_mul_f32 v[62:63], v[62:63], v[76:77] op_sel_hi:[1,0]
	v_pk_mul_f32 v[60:61], v[60:61], v[76:77] op_sel_hi:[1,0]
	v_pk_mul_f32 v[58:59], v[58:59], v[76:77] op_sel_hi:[1,0]
	v_pk_mul_f32 v[56:57], v[56:57], v[76:77] op_sel_hi:[1,0]
	v_pk_mul_f32 v[54:55], v[54:55], v[76:77] op_sel_hi:[1,0]
	v_pk_mul_f32 v[52:53], v[52:53], v[76:77] op_sel_hi:[1,0]
	v_pk_mul_f32 v[50:51], v[50:51], v[76:77] op_sel_hi:[1,0]
	s_waitcnt lgkmcnt(2)
	v_pk_mul_f32 v[62:63], v[80:81], v[62:63]
	v_pk_mul_f32 v[64:65], v[82:83], v[64:65]
	s_waitcnt lgkmcnt(1)
	v_pk_add_f32 v[80:81], v[86:87], 1.0 op_sel_hi:[1,0]
	v_pk_add_f32 v[82:83], v[84:85], 1.0 op_sel_hi:[1,0]
	s_waitcnt lgkmcnt(0)
	v_pk_fma_f32 v[64:65], v[80:81], v[64:65], v[90:91]
	v_pk_fma_f32 v[62:63], v[82:83], v[62:63], v[88:89]
	s_nop 0
	v_cvt_pk_bf16_f32 v62, v62, v63
	v_cvt_pk_bf16_f32 v63, v64, v65
	v_lshl_add_u64 v[64:65], v[74:75], 0, s[0:1]
	global_store_dwordx2 v[64:65], v[62:63], off
	ds_read_b128 v[80:83], v98 offset:1024
	v_lshlrev_b32_e32 v62, 2, v68
	ds_read_b128 v[84:87], v92 offset:9216
	ds_read_b128 v[88:91], v92 offset:5120
	v_readlane_b32 s0, v253, 58
	s_add_i32 s44, s0, s9
	s_cmpk_gt_i32 s44, 0x47ff
	s_waitcnt lgkmcnt(2)
	v_pk_mul_f32 v[58:59], v[80:81], v[58:59]
	v_pk_mul_f32 v[60:61], v[82:83], v[60:61]
	s_waitcnt lgkmcnt(1)
	v_pk_add_f32 v[80:81], v[86:87], 1.0 op_sel_hi:[1,0]
	v_pk_add_f32 v[82:83], v[84:85], 1.0 op_sel_hi:[1,0]
	s_waitcnt lgkmcnt(0)
	v_pk_fma_f32 v[60:61], v[80:81], v[60:61], v[90:91]
	v_pk_fma_f32 v[58:59], v[82:83], v[58:59], v[88:89]
	s_nop 0
	v_cvt_pk_bf16_f32 v58, v58, v59
	v_cvt_pk_bf16_f32 v59, v60, v61
	global_store_dwordx2 v[64:65], v[58:59], off offset:512
	ds_read_b128 v[80:83], v98 offset:2048
	v_lshlrev_b32_e32 v58, 2, v70
	ds_read_b128 v[84:87], v92 offset:10240
	ds_read_b128 v[88:91], v92 offset:6144
	s_waitcnt lgkmcnt(2)
	v_pk_mul_f32 v[54:55], v[80:81], v[54:55]
	v_pk_mul_f32 v[56:57], v[82:83], v[56:57]
	s_waitcnt lgkmcnt(1)
	v_pk_add_f32 v[60:61], v[86:87], 1.0 op_sel_hi:[1,0]
	v_pk_add_f32 v[80:81], v[84:85], 1.0 op_sel_hi:[1,0]
	s_waitcnt lgkmcnt(0)
	v_pk_fma_f32 v[56:57], v[56:57], v[60:61], v[90:91]
	v_pk_fma_f32 v[54:55], v[54:55], v[80:81], v[88:89]
	s_nop 0
	v_cvt_pk_bf16_f32 v54, v54, v55
	v_cvt_pk_bf16_f32 v55, v56, v57
	global_store_dwordx2 v[64:65], v[54:55], off offset:1024
	ds_read_b128 v[80:83], v98 offset:3072
	v_lshlrev_b32_e32 v54, 2, v72
	ds_read_b128 v[84:87], v92 offset:11264
	ds_read_b128 v[88:91], v92 offset:7168
	s_waitcnt lgkmcnt(2)
	v_pk_mul_f32 v[50:51], v[50:51], v[80:81]
	v_pk_mul_f32 v[52:53], v[52:53], v[82:83]
	s_waitcnt lgkmcnt(1)
	v_pk_add_f32 v[56:57], v[86:87], 1.0 op_sel_hi:[1,0]
	v_pk_add_f32 v[60:61], v[84:85], 1.0 op_sel_hi:[1,0]
	s_waitcnt lgkmcnt(0)
	v_pk_fma_f32 v[52:53], v[52:53], v[56:57], v[90:91]
	v_pk_fma_f32 v[50:51], v[50:51], v[60:61], v[88:89]
	s_nop 0
	v_cvt_pk_bf16_f32 v50, v50, v51
	v_cvt_pk_bf16_f32 v51, v52, v53
	global_store_dwordx2 v[64:65], v[50:51], off offset:1536
	s_cbranch_scc1 .LBB0_347
	s_min_i32 s0, s44, 0x4000
	s_lshr_b32 s0, s0, 11
	s_lshl_b32 s100, s0, 13
	s_mulk_i32 s0, 0x1800
	s_ashr_i32 s1, s0, 31
	s_lshl_b64 s[0:1], s[0:1], 2
	v_readlane_b32 s10, v250, 14
	v_readlane_b32 s11, v250, 15
	s_add_u32 s40, s10, s0
	s_addc_u32 s41, s11, s1
	s_add_u32 s42, s40, 0x1000
	s_addc_u32 s43, s41, 0
	v_add_u32_e32 v92, s100, v98
	ds_read_b128 v[80:83], v98
	ds_read_b128 v[84:87], v92 offset:8192
	ds_read_b128 v[88:91], v92 offset:4096
	v_pk_mul_f32 v[50:51], v[48:49], v[48:49]
	v_pk_mul_f32 v[52:53], v[46:47], v[46:47]
	s_mov_b32 s0, 0xf800000
	v_pk_mov_b32 v[56:57], v[52:53], v[50:51] op_sel:[1,0]
	v_mov_b32_e32 v53, v51
	v_pk_add_f32 v[50:51], v[56:57], v[52:53]
	v_pk_mul_f32 v[52:53], v[12:13], v[12:13]
	v_pk_add_f32 v[50:51], v[50:51], v[50:51] op_sel_hi:[0,1]
	v_pk_mul_f32 v[56:57], v[10:11], v[10:11]
	v_mul_f32_e32 v50, v6, v6
	v_pk_mov_b32 v[60:61], v[56:57], v[52:53] op_sel:[1,0]
	v_mov_b32_e32 v57, v53
	v_pk_add_f32 v[52:53], v[60:61], v[56:57]
	v_pk_fma_f32 v[56:57], v[6:7], v[6:7], v[50:51] op_sel_hi:[1,1,0]
	v_mul_f32_e32 v50, v8, v8
	v_pk_add_f32 v[52:53], v[52:53], v[52:53] op_sel_hi:[0,1]
	v_pk_fma_f32 v[60:61], v[8:9], v[8:9], v[50:51] op_sel_hi:[1,1,0]
	v_mul_f32_e32 v56, v2, v2
	v_mul_f32_e32 v60, v3, v3
	v_mul_f32_e32 v52, v4, v4
	v_mul_f32_e32 v50, v5, v5
	v_pk_add_f32 v[56:57], v[56:57], v[60:61]
	v_pk_add_f32 v[50:51], v[52:53], v[50:51]
	s_ashr_i32 s45, s44, 31
	v_pk_add_f32 v[50:51], v[56:57], v[50:51]
	s_nop 0
	v_add_f32_e32 v50, v50, v51
	s_nop 1
	v_mov_b32_dpp v51, v50 quad_perm:[1,0,3,2] row_mask:0xf bank_mask:0xf
	s_waitcnt lgkmcnt(0)
	v_add_f32_e32 v50, v50, v51
	s_nop 1
	v_mov_b32_dpp v51, v50 quad_perm:[2,3,0,1] row_mask:0xf bank_mask:0xf
	s_waitcnt lgkmcnt(0)
	v_add_f32_e32 v50, v50, v51
	s_nop 1
	v_mov_b32_dpp v51, v50 row_half_mirror row_mask:0xf bank_mask:0xf
	s_waitcnt lgkmcnt(0)
	v_add_f32_e32 v50, v50, v51
	s_nop 1
	v_mov_b32_dpp v51, v50 row_mirror row_mask:0xf bank_mask:0xf
	s_waitcnt lgkmcnt(0)
	v_add_f32_e32 v50, v50, v51
	v_mov_b32_e32 v51, v50
	s_nop 1
	v_permlane16_swap_b32_e32 v50, v51
	s_waitcnt lgkmcnt(0)
	v_add_f32_e32 v50, v50, v51
	v_mov_b32_e32 v51, v50
	s_nop 1
	v_permlane32_swap_b32_e32 v50, v51
	s_waitcnt lgkmcnt(0)
	v_add_f32_e32 v50, v50, v51
	v_fmamk_f32 v50, v50, 0x3a800000, v212
	v_cmp_gt_f32_e32 vcc, s0, v50
	v_mul_f32_e32 v51, 0x4f800000, v50
	s_nop 0
	v_cndmask_b32_e32 v50, v50, v51, vcc
	v_sqrt_f32_e32 v51, v50
	s_nop 0
	v_add_u32_e32 v52, -1, v51
	v_fma_f32 v53, -v52, v51, v50
	v_cmp_ge_f32_e64 s[0:1], 0, v53
	v_add_u32_e32 v53, 1, v51
	s_nop 0
	v_cndmask_b32_e64 v52, v51, v52, s[0:1]
	v_fma_f32 v51, -v53, v51, v50
	v_cmp_lt_f32_e64 s[0:1], 0, v51
	s_nop 1
	v_cndmask_b32_e64 v51, v52, v53, s[0:1]
	v_mul_f32_e32 v52, 0x37800000, v51
	v_cndmask_b32_e32 v51, v51, v52, vcc
	v_cmp_class_f32_e32 vcc, v50, v241
	s_nop 1
	v_cndmask_b32_e32 v50, v51, v50, vcc
	v_div_scale_f32 v51, s[0:1], v50, v50, 1.0
	v_rcp_f32_e32 v52, v51
	s_lshl_b64 s[0:1], s[44:45], 11
	v_fma_f32 v53, -v51, v52, 1.0
	v_fmac_f32_e32 v52, v53, v52
	v_div_scale_f32 v53, vcc, 1.0, v50, 1.0
	v_mul_f32_e32 v55, v53, v52
	v_fma_f32 v56, -v51, v55, v53
	v_fmac_f32_e32 v55, v56, v52
	v_fma_f32 v51, -v51, v55, v53
	v_div_fmas_f32 v51, v51, v52, v55
	v_div_fixup_f32 v50, v51, v50, 1.0
	v_pk_mul_f32 v[48:49], v[48:49], v[50:51] op_sel_hi:[1,0]
	v_pk_mul_f32 v[46:47], v[46:47], v[50:51] op_sel_hi:[1,0]
	s_waitcnt lgkmcnt(2)
	v_pk_mul_f32 v[48:49], v[82:83], v[48:49]
	v_pk_mul_f32 v[46:47], v[80:81], v[46:47]
	s_waitcnt lgkmcnt(1)
	v_pk_add_f32 v[52:53], v[86:87], 1.0 op_sel_hi:[1,0]
	v_pk_add_f32 v[56:57], v[84:85], 1.0 op_sel_hi:[1,0]
	s_waitcnt lgkmcnt(0)
	v_pk_fma_f32 v[48:49], v[52:53], v[48:49], v[90:91]
	v_pk_fma_f32 v[46:47], v[56:57], v[46:47], v[88:89]
	v_lshl_add_u64 v[52:53], v[74:75], 0, s[0:1]
	v_cvt_pk_bf16_f32 v46, v46, v47
	v_cvt_pk_bf16_f32 v47, v48, v49
	global_store_dwordx2 v[52:53], v[46:47], off
	ds_read_b128 v[46:49], v98 offset:1024
	s_nop 0
	ds_read_b128 v[60:63], v92 offset:9216
	s_nop 0
	ds_read_b128 v[80:83], v92 offset:5120
	v_pk_mul_f32 v[12:13], v[12:13], v[50:51] op_sel_hi:[1,0]
	v_pk_mul_f32 v[10:11], v[10:11], v[50:51] op_sel_hi:[1,0]
	v_pk_mul_f32 v[8:9], v[8:9], v[50:51] op_sel_hi:[1,0]
	v_pk_mul_f32 v[6:7], v[6:7], v[50:51] op_sel_hi:[1,0]
	v_pk_mul_f32 v[4:5], v[4:5], v[50:51] op_sel_hi:[1,0]
	v_pk_mul_f32 v[2:3], v[2:3], v[50:51] op_sel_hi:[1,0]
	s_waitcnt lgkmcnt(2)
	v_pk_mul_f32 v[10:11], v[46:47], v[10:11]
	v_pk_mul_f32 v[12:13], v[48:49], v[12:13]
	s_waitcnt lgkmcnt(1)
	v_pk_add_f32 v[46:47], v[62:63], 1.0 op_sel_hi:[1,0]
	v_pk_add_f32 v[48:49], v[60:61], 1.0 op_sel_hi:[1,0]
	s_waitcnt lgkmcnt(0)
	v_pk_fma_f32 v[12:13], v[46:47], v[12:13], v[82:83]
	v_pk_fma_f32 v[10:11], v[48:49], v[10:11], v[80:81]
	s_nop 0
	v_cvt_pk_bf16_f32 v10, v10, v11
	v_cvt_pk_bf16_f32 v11, v12, v13
	global_store_dwordx2 v[52:53], v[10:11], off offset:512
	ds_read_b128 v[10:13], v98 offset:2048
	s_nop 0
	ds_read_b128 v[46:49], v92 offset:10240
	s_nop 0
	ds_read_b128 v[56:59], v92 offset:6144
	s_waitcnt lgkmcnt(2)
	v_pk_mul_f32 v[6:7], v[10:11], v[6:7]
	v_pk_mul_f32 v[8:9], v[12:13], v[8:9]
	s_waitcnt lgkmcnt(1)
	v_pk_add_f32 v[10:11], v[48:49], 1.0 op_sel_hi:[1,0]
	v_pk_add_f32 v[12:13], v[46:47], 1.0 op_sel_hi:[1,0]
	s_waitcnt lgkmcnt(0)
	v_pk_fma_f32 v[8:9], v[8:9], v[10:11], v[58:59]
	v_pk_fma_f32 v[6:7], v[6:7], v[12:13], v[56:57]
	s_nop 0
	v_cvt_pk_bf16_f32 v6, v6, v7
	v_cvt_pk_bf16_f32 v7, v8, v9
	global_store_dwordx2 v[52:53], v[6:7], off offset:1024
	ds_read_b128 v[6:9], v98 offset:3072
	s_nop 0
	ds_read_b128 v[10:13], v92 offset:11264
	ds_read_b128 v[46:49], v92 offset:7168
	s_waitcnt lgkmcnt(2)
	v_pk_mul_f32 v[2:3], v[2:3], v[6:7]
	v_pk_mul_f32 v[4:5], v[4:5], v[8:9]
	s_waitcnt lgkmcnt(1)
	v_pk_add_f32 v[6:7], v[12:13], 1.0 op_sel_hi:[1,0]
	v_pk_add_f32 v[8:9], v[10:11], 1.0 op_sel_hi:[1,0]
	s_waitcnt lgkmcnt(0)
	v_pk_fma_f32 v[4:5], v[4:5], v[6:7], v[48:49]
	v_pk_fma_f32 v[2:3], v[2:3], v[8:9], v[46:47]
	s_nop 0
	v_cvt_pk_bf16_f32 v2, v2, v3
	v_cvt_pk_bf16_f32 v3, v4, v5
	global_store_dwordx2 v[52:53], v[2:3], off offset:1536
	s_branch .LBB0_347

.LBB0_627:
	s_andn2_b64 vcc, exec, s[0:1]
	s_cbranch_vccnz .LBB0_696
	s_ashr_i32 s16, s19, 6
	v_lshlrev_b32_e32 v4, 4, v13
	v_and_b32_e32 v6, 63, v13
	v_readlane_b32 s8, v251, 50
	v_readlane_b32 s9, v251, 51
	v_lshlrev_b32_e32 v6, 4, v6
	s_lshl_b32 s10, s16, 10
	s_add_u32 s8, s8, s10
	s_addc_u32 s9, s9, 0
	s_add_i32 m0, s10, 0x26000
	s_nop 4
	global_load_lds_dwordx4 v6, s[8:9]
	s_cmp_lt_i32 s16, 7
	v_and_b32_e32 v2, 0x3f0, v4
	s_waitcnt lgkmcnt(0)
	v_mov_b32_e32 v3, v99
	s_cselect_b64 s[0:1], -1, 0
	s_cmp_gt_i32 s16, 6
	s_mul_i32 s7, s16, 0xc00
	s_mul_hi_i32 s8, s38, 0x50
	s_mul_i32 s9, s38, 0x50
	s_cbranch_scc1 .LBB0_630
	s_add_u32 s10, s74, s9
	s_addc_u32 s11, s75, s8
	s_ashr_i32 s12, s7, 31
	s_add_u32 s10, s10, s7
	s_addc_u32 s11, s11, s12
	v_lshl_add_u64 v[6:7], s[10:11], 0, v[2:3]
	s_add_i32 s10, s7, 0
	s_add_i32 m0, s10, 0x20c00
	s_mov_b64 s[12:13], 0x400
	global_load_lds_dwordx4 v[6:7], off
	v_lshl_add_u64 v[6:7], v[6:7], 0, s[12:13]
	s_add_i32 m0, s10, 0x21000
	s_nop 0
	global_load_lds_dwordx4 v[6:7], off

.LBB0_696:
	v_readlane_b32 s0, v254, 14
	s_ashr_i32 s8, s2, 6
	v_and_b32_e32 v2, 63, v148
	s_waitcnt lgkmcnt(0)
	v_mov_b32_e32 v3, s0
	ds_read_b128 v[4:7], v3
	s_add_i32 s22, s8, s89
	s_cmpk_gt_i32 s22, 0x47ff
	s_waitcnt lgkmcnt(0)
	v_readfirstlane_b32 s0, v4
	v_readfirstlane_b32 s1, v5
	v_readfirstlane_b32 s7, v6
	v_readfirstlane_b32 s9, v7
	v_lshlrev_b32_e32 v4, 3, v2
	s_cbranch_scc1 .LBB0_735
	v_and_b32_e32 v5, 64, v1
	v_xor_b32_e32 v3, 16, v1
	v_add_u32_e32 v5, 64, v5
	v_cmp_lt_i32_e32 vcc, v3, v5
	v_xor_b32_e32 v6, 1, v1
	s_lshl_b32 s10, s90, 8
	v_cndmask_b32_e32 v3, v1, v3, vcc
	v_cmp_lt_i32_e32 vcc, v6, v5
	s_mov_b32 s11, s69
	s_and_b64 s[12:13], s[46:47], exec
	v_cndmask_b32_e32 v6, v1, v6, vcc
	v_lshlrev_b32_e32 v7, 2, v6
	v_xor_b32_e32 v6, 2, v1
	v_cmp_lt_i32_e32 vcc, v6, v5
	s_movk_i32 s4, 0x4800
	s_cselect_b32 s4, s4, 0x4000
	v_cndmask_b32_e32 v6, v1, v6, vcc
	v_lshlrev_b32_e32 v66, 2, v6
	v_xor_b32_e32 v6, 4, v1
	v_cmp_lt_i32_e32 vcc, v6, v5
	s_lshl_b64 s[10:11], s[10:11], 2
	s_mul_i32 s68, s90, 0x300
	v_cndmask_b32_e32 v6, v1, v6, vcc
	v_lshlrev_b32_e32 v67, 2, v6
	v_xor_b32_e32 v6, 8, v1
	v_cmp_lt_i32_e32 vcc, v6, v5
	s_add_u32 s10, s7, s10
	s_addc_u32 s11, s9, s11
	v_cndmask_b32_e32 v6, v1, v6, vcc
	v_lshlrev_b32_e32 v68, 2, v6
	v_xor_b32_e32 v6, 32, v1
	v_cmp_lt_i32_e32 vcc, v6, v5
	s_lshl_b64 s[12:13], s[68:69], 2
	v_lshlrev_b32_e32 v9, 1, v2
	v_cndmask_b32_e32 v5, v1, v6, vcc
	v_lshrrev_b32_e32 v10, 2, v148
	s_add_u32 s0, s0, s12
	v_lshlrev_b32_e32 v69, 2, v5
	v_and_b32_e32 v5, 24, v9
	v_and_b32_e32 v16, 4, v10
	v_and_b32_e32 v17, 35, v148
	s_addc_u32 s1, s1, s13
	v_or3_b32 v10, v16, v17, v5
	v_readlane_b32 s12, v251, 54
	v_lshlrev_b32_e32 v98, 1, v10
	v_readlane_b32 s13, v251, 55
	v_and_b32_e32 v12, 16, v148
	v_cmp_eq_u32_e64 s[40:41], 0, v12
	v_lshl_add_u64 v[10:11], s[12:13], 0, v[98:99]
	v_lshlrev_b32_e32 v98, 4, v2
	v_lshl_add_u64 v[12:13], s[0:1], 0, v[98:99]
	s_ashr_i32 s23, s22, 31
	s_mul_hi_i32 s0, s22, 0x600
	s_mul_i32 s1, s22, 0x600
	v_or3_b32 v5, v17, v5, v16
	v_lshl_or_b32 v16, v5, 1, s1
	v_mov_b32_e32 v17, s0
	s_lshl_b64 s[0:1], s[22:23], 11
	v_readlane_b32 s7, v253, 59
	s_add_u32 s0, s7, s0
	v_readlane_b32 s7, v253, 60
	v_mov_b32_e32 v5, v99
	s_addc_u32 s1, s7, s1
	v_lshl_add_u64 v[18:19], s[0:1], 0, v[4:5]
	s_lshl_b64 s[0:1], s[22:23], 12
	v_or_b32_e32 v20, s0, v4
	s_add_u32 s0, s0, 0x7100500
	v_mov_b32_e32 v8, 0
	v_mov_b32_e32 v21, s1
	s_addc_u32 s1, s1, 0
	v_lshlrev_b32_e32 v3, 2, v3
	v_lshlrev_b32_e32 v6, 2, v2
	v_and_b32_e32 v70, 15, v148
	v_cmp_gt_u32_e64 s[38:39], 32, v2
	v_lshl_add_u64 v[14:15], s[10:11], 0, v[98:99]
	v_or_b32_e32 v22, s0, v9
	v_mov_b32_e32 v23, s1
	s_mov_b32 s7, s22
	v_mov_b32_e32 v9, v8
	v_mov_b32_e32 v42, v8
	v_mov_b32_e32 v43, v8
	v_mov_b32_e32 v48, v8
	v_mov_b32_e32 v49, v8
	v_mov_b32_e32 v50, v8
	v_mov_b32_e32 v51, v8
	v_mov_b32_e32 v44, v8
	v_mov_b32_e32 v45, v8
	v_mov_b32_e32 v46, v8
	v_mov_b32_e32 v47, v8
	v_mov_b32_e32 v52, v8
	v_mov_b32_e32 v53, v8
	v_mov_b32_e32 v54, v8
	v_mov_b32_e32 v55, v8
	s_mov_b32 s12, 0xf800000
	s_movk_i32 s13, 0x7ff
	global_load_dwordx4 v[104:107], v[12:13], off
	global_load_dwordx4 v[108:111], v[12:13], off offset:1024
	global_load_dwordx4 v[112:115], v[12:13], off offset:2048
	global_load_dwordx4 v[116:119], v[14:15], off
	s_branch .LBB0_699

.LBB0_712:
.LBB0_713:
	v_readlane_b32 s10, v251, 56
	s_add_i32 s36, s10, s7
	s_cmpk_lt_i32 s36, 0x4800
	s_cselect_b64 s[42:43], -1, 0
	s_cmpk_gt_i32 s36, 0x47ff
	v_readlane_b32 s11, v251, 57
	s_cbranch_scc1 .LBB0_721
	s_ashr_i32 s37, s36, 31
	s_lshl_b64 s[10:11], s[36:37], 12
	s_add_u32 s52, s92, s10
	s_addc_u32 s53, s93, s11
	global_load_ushort v5, v64, s[52:53] offset:1280
	v_mov_b32_e32 v43, 0
	s_cmp_ge_i32 s36, s4
	v_mov_b32_e32 v42, 0
	v_mov_b32_e32 v51, 0
	v_mov_b32_e32 v50, 0
	v_mov_b32_e32 v47, 0
	v_mov_b32_e32 v46, 0
	v_mov_b32_e32 v55, 0
	v_mov_b32_e32 v54, 0
	s_cbranch_scc1 .LBB0_720
	v_lshlrev_b32_e32 v98, 1, v6
	global_load_dwordx2 v[24:25], v98, s[52:53] offset:2560
	global_load_dwordx2 v[28:29], v98, s[52:53] offset:3072
	global_load_dwordx2 v[34:35], v98, s[52:53] offset:3584
	s_cmpk_lt_i32 s36, 0x4000
	s_cselect_b32 s9, s13, 0xff
	s_and_b32 s10, s9, s36
	s_cmp_eq_u32 s10, 0
	s_cbranch_scc1 .LBB0_717
	v_lshl_add_u64 v[46:47], s[52:53], 0, v[98:99]
	global_load_dwordx2 v[42:43], v[46:47], off offset:-1024
	s_nop 0
	global_load_dwordx2 v[46:47], v[46:47], off offset:-512
	s_branch .LBB0_718

.LBB0_720:
.LBB0_721:
	s_waitcnt vmcnt(0)
	v_lshlrev_b32_e32 v64, 16, v72
	v_lshlrev_b32_e32 v71, 16, v65
	v_lshlrev_b32_e32 v5, 16, v5
	ds_bpermute_b32 v65, v3, v64
	s_andn2_b64 vcc, exec, s[50:51]
	s_cbranch_vccnz .LBB0_723
	s_and_b32 s9, s7, 63
	s_bfe_u32 s10, s7, 0x50006
	v_mov_b32_e32 v72, s9
	v_mov_b32_e32 v73, s10
	v_cndmask_b32_e64 v72, v72, v73, s[38:39]
	v_lshlrev_b32_e32 v73, 2, v70
	v_lshl_or_b32 v72, v72, 6, v73
	v_or_b32_e32 v72, 0x26000, v72
	ds_read_b32 v73, v72 offset:4096
	s_waitcnt lgkmcnt(0)
	v_mul_f32_e32 v65, v73, v65
	ds_read_b32 v72, v72
	v_cndmask_b32_e64 v65, v65, -v65, s[40:41]
	s_waitcnt lgkmcnt(0)
	v_fmac_f32_e32 v65, v72, v64
	v_mov_b32_e32 v64, v65
.LBB0_723:
	s_waitcnt lgkmcnt(0)
	v_bfe_u32 v65, v64, 16, 1
	s_movk_i32 s9, 0x7fff
	v_add3_u32 v64, v64, v65, s9
	v_lshrrev_b32_e32 v72, 16, v64
	v_lshl_add_u64 v[64:65], s[86:87], 0, v[16:17]
	v_add_co_u32_e32 v64, vcc, 0xb900000, v64
	s_nop 1
	v_addc_co_u32_e32 v65, vcc, 0, v65, vcc
	s_andn2_b64 vcc, exec, s[0:1]
	global_store_short v[64:65], v72, off offset:256
	global_store_short v[64:65], v72, off offset:640
	global_store_short v[64:65], v72, off offset:1024
	global_store_short v[64:65], v72, off offset:1408
	s_cbranch_vccnz .LBB0_725
	v_mov_b32_e32 v72, v104
	v_mov_b32_e32 v73, v105
	v_mov_b32_e32 v74, v106
	v_mov_b32_e32 v75, v107
	v_mov_b32_e32 v76, v108
	v_mov_b32_e32 v77, v109
	v_mov_b32_e32 v78, v110
	v_mov_b32_e32 v79, v111
	v_mov_b32_e32 v80, v112
	v_mov_b32_e32 v81, v113
	v_mov_b32_e32 v82, v114
	v_mov_b32_e32 v83, v115
	v_mov_b32_e32 v84, v116
	v_mov_b32_e32 v85, v117
	v_mov_b32_e32 v86, v118
	v_mov_b32_e32 v87, v119
	v_lshlrev_b32_e32 v88, 16, v59
	v_and_b32_e32 v89, 0xffff0000, v59
	v_lshlrev_b32_e32 v90, 16, v57
	v_and_b32_e32 v91, 0xffff0000, v57
	v_lshlrev_b32_e32 v92, 16, v39
	v_and_b32_e32 v93, 0xffff0000, v39
	v_lshlrev_b32_e32 v94, 16, v41
	v_and_b32_e32 v95, 0xffff0000, v41
	v_pk_mul_f32 v[88:89], v[90:91], v[88:89]
	v_pk_mul_f32 v[90:91], v[92:93], v[94:95]
	v_lshlrev_b32_e32 v96, 16, v61
	v_and_b32_e32 v97, 0xffff0000, v61
	v_lshlrev_b32_e32 v100, 16, v63
	v_and_b32_e32 v101, 0xffff0000, v63
	v_pk_mul_f32 v[92:93], v[100:101], v[96:97]
	v_and_b32_e32 v59, 0xffff0000, v56
	v_and_b32_e32 v57, 0xffff0000, v38
	v_and_b32_e32 v61, 0xffff0000, v62
	v_lshlrev_b32_e32 v64, 16, v33
	v_and_b32_e32 v65, 0xffff0000, v33
	v_pk_mul_f32 v[78:79], v[90:91], v[78:79]
	s_nop 0
	v_pk_fma_f32 v[74:75], v[88:89], v[74:75], v[78:79]
	v_lshlrev_b32_e32 v78, 16, v58
	v_pk_fma_f32 v[74:75], v[92:93], v[82:83], v[74:75]
	v_and_b32_e32 v79, 0xffff0000, v58
	v_lshlrev_b32_e32 v58, 16, v56
	v_lshlrev_b32_e32 v56, 16, v38
	v_lshlrev_b32_e32 v82, 16, v40
	v_and_b32_e32 v83, 0xffff0000, v40
	v_pk_mul_f32 v[56:57], v[56:57], v[82:83]
	v_pk_add_f32 v[74:75], v[86:87], v[74:75]
	v_lshlrev_b32_e32 v86, 16, v60
	v_and_b32_e32 v87, 0xffff0000, v60
	v_lshlrev_b32_e32 v60, 16, v62
	v_pk_mul_f32 v[58:59], v[58:59], v[78:79]
	v_pk_mul_f32 v[56:57], v[56:57], v[76:77]
	v_pk_mul_f32 v[60:61], v[60:61], v[86:87]
	v_pk_fma_f32 v[56:57], v[58:59], v[72:73], v[56:57]
	v_pk_mul_f32 v[64:65], v[74:75], v[64:65]
	v_pk_fma_f32 v[56:57], v[60:61], v[80:81], v[56:57]
	v_lshlrev_b32_e32 v74, 16, v32
	v_and_b32_e32 v75, 0xffff0000, v32
	v_pk_add_f32 v[56:57], v[84:85], v[56:57]
	v_mov_b32_e32 v61, v65
	v_pk_mul_f32 v[56:57], v[56:57], v[74:75]
	v_mov_b32_e32 v59, v64
	v_mov_b32_e32 v60, v57
	v_mov_b32_e32 v58, v56
	v_pk_mul_f32 v[60:61], v[60:61], v[60:61]
	s_nop 0
	v_pk_fma_f32 v[58:59], v[58:59], v[58:59], v[60:61]
	s_nop 0
	v_add_f32_e32 v58, v58, v59
	s_nop 1
	v_mov_b32_dpp v59, v58 quad_perm:[1,0,3,2] row_mask:0xf bank_mask:0xf
	s_waitcnt lgkmcnt(0)
	v_add_f32_e32 v58, v58, v59
	s_nop 1
	v_mov_b32_dpp v59, v58 quad_perm:[2,3,0,1] row_mask:0xf bank_mask:0xf
	s_waitcnt lgkmcnt(0)
	v_add_f32_e32 v58, v58, v59
	s_nop 1
	v_mov_b32_dpp v59, v58 row_half_mirror row_mask:0xf bank_mask:0xf
	s_waitcnt lgkmcnt(0)
	v_add_f32_e32 v58, v58, v59
	s_nop 1
	v_mov_b32_dpp v59, v58 row_mirror row_mask:0xf bank_mask:0xf
	s_waitcnt lgkmcnt(0)
	v_add_f32_e32 v58, v58, v59
	v_mov_b32_e32 v59, v58
	s_nop 1
	v_permlane16_swap_b32_e32 v58, v59
	s_waitcnt lgkmcnt(0)
	v_add_f32_e32 v58, v58, v59
	v_mov_b32_e32 v59, v58
	s_nop 1
	v_permlane32_swap_b32_e32 v58, v59
	s_waitcnt lgkmcnt(0)
	v_add_f32_e32 v58, v58, v59
	v_fmamk_f32 v58, v58, 0x3b800000, v212
	v_cmp_gt_f32_e32 vcc, s12, v58
	v_mul_f32_e32 v59, 0x4f800000, v58
	s_nop 0
	v_cndmask_b32_e32 v58, v58, v59, vcc
	v_sqrt_f32_e32 v59, v58
	s_nop 0
	v_add_u32_e32 v60, -1, v59
	v_fma_f32 v61, -v60, v59, v58
	v_cmp_ge_f32_e64 s[0:1], 0, v61
	v_add_u32_e32 v61, 1, v59
	s_nop 0
	v_cndmask_b32_e64 v60, v59, v60, s[0:1]
	v_fma_f32 v59, -v61, v59, v58
	v_cmp_lt_f32_e64 s[0:1], 0, v59
	s_nop 1
	v_cndmask_b32_e64 v59, v60, v61, s[0:1]
	v_mul_f32_e32 v60, 0x37800000, v59
	v_cndmask_b32_e32 v59, v59, v60, vcc
	v_cmp_class_f32_e32 vcc, v58, v241
	s_nop 1
	v_cndmask_b32_e32 v58, v59, v58, vcc
	v_div_scale_f32 v59, s[0:1], v58, v58, 1.0
	v_rcp_f32_e32 v60, v59
	s_nop 0
	v_fma_f32 v61, -v59, v60, 1.0
	v_fmac_f32_e32 v60, v61, v60
	v_div_scale_f32 v61, vcc, 1.0, v58, 1.0
	v_mul_f32_e32 v62, v61, v60
	v_fma_f32 v63, -v59, v62, v61
	v_fmac_f32_e32 v62, v63, v60
	v_fma_f32 v59, -v59, v62, v61
	v_div_fmas_f32 v59, v59, v60, v62
	v_div_fixup_f32 v58, v59, v58, 1.0
	v_pk_mul_f32 v[56:57], v[56:57], v[58:59] op_sel_hi:[1,0]
	v_pk_mul_f32 v[58:59], v[64:65], v[58:59] op_sel_hi:[1,0]
	v_cvt_pk_bf16_f32 v56, v56, v57
	v_cvt_pk_bf16_f32 v57, v58, v59
	global_store_dwordx2 v[18:19], v[56:57], off
.LBB0_725:
	s_andn2_b64 vcc, exec, s[48:49]
	s_cbranch_vccnz .LBB0_730
	ds_bpermute_b32 v56, v3, v71
	s_cmpk_gt_i32 s44, 0x3fff
	v_mov_b32_e32 v57, v71
	s_cbranch_scc1 .LBB0_728
	s_and_b32 s0, s44, 63
	s_bfe_u32 s1, s44, 0x50006
	v_mov_b32_e32 v57, s0
	v_mov_b32_e32 v58, s1
	v_cndmask_b32_e64 v57, v57, v58, s[38:39]
	v_lshlrev_b32_e32 v58, 2, v70
	v_lshl_or_b32 v57, v57, 6, v58
	v_or_b32_e32 v57, 0x26000, v57
	ds_read_b32 v58, v57 offset:4096
	s_waitcnt lgkmcnt(0)
	v_mul_f32_e32 v56, v58, v56
	ds_read_b32 v59, v57
	v_cndmask_b32_e64 v57, v56, -v56, s[40:41]
	s_waitcnt lgkmcnt(0)
	v_fmac_f32_e32 v57, v71, v59
.LBB0_728:
	s_waitcnt lgkmcnt(0)
	v_bfe_u32 v56, v57, 16, 1
	s_movk_i32 s0, 0x7fff
	v_add3_u32 v56, v57, v56, s0
	v_lshrrev_b32_e32 v58, 16, v56
	v_mad_i64_i32 v[56:57], s[0:1], s44, v203, v[10:11]
	s_cmp_ge_i32 s44, s4
	global_store_short v[56:57], v58, off
	global_store_short v[56:57], v58, off offset:384
	global_store_short v[56:57], v58, off offset:768
	global_store_short v[56:57], v58, off offset:1152
	s_cbranch_scc1 .LBB0_730
	v_mov_b32_e32 v56, v104
	v_mov_b32_e32 v57, v105
	v_mov_b32_e32 v58, v106
	v_mov_b32_e32 v59, v107
	v_mov_b32_e32 v60, v108
	v_mov_b32_e32 v61, v109
	v_mov_b32_e32 v62, v110
	v_mov_b32_e32 v63, v111
	v_mov_b32_e32 v72, v112
	v_mov_b32_e32 v73, v113
	v_mov_b32_e32 v74, v114
	v_mov_b32_e32 v75, v115
	v_mov_b32_e32 v76, v116
	v_mov_b32_e32 v77, v117
	v_mov_b32_e32 v78, v118
	v_mov_b32_e32 v79, v119
	v_lshlrev_b32_e32 v80, 16, v9
	v_and_b32_e32 v81, 0xffff0000, v9
	v_lshlrev_b32_e32 v82, 16, v45
	v_and_b32_e32 v83, 0xffff0000, v45
	v_lshlrev_b32_e32 v84, 16, v31
	v_and_b32_e32 v85, 0xffff0000, v31
	v_lshlrev_b32_e32 v86, 16, v37
	v_and_b32_e32 v87, 0xffff0000, v37
	v_pk_mul_f32 v[80:81], v[82:83], v[80:81]
	v_pk_mul_f32 v[82:83], v[84:85], v[86:87]
	v_lshlrev_b32_e32 v88, 16, v49
	v_and_b32_e32 v89, 0xffff0000, v49
	v_lshlrev_b32_e32 v90, 16, v53
	v_and_b32_e32 v91, 0xffff0000, v53
	v_pk_mul_f32 v[84:85], v[90:91], v[88:89]
	v_lshlrev_b32_e32 v64, 16, v27
	v_and_b32_e32 v65, 0xffff0000, v27
	s_ashr_i32 s45, s44, 31
	v_lshlrev_b32_e32 v98, 1, v6
	v_pk_mul_f32 v[62:63], v[82:83], v[62:63]
	s_nop 0
	v_pk_fma_f32 v[58:59], v[80:81], v[58:59], v[62:63]
	v_lshlrev_b32_e32 v80, 16, v36
	v_pk_fma_f32 v[58:59], v[84:85], v[74:75], v[58:59]
	v_lshlrev_b32_e32 v74, 16, v44
	v_pk_add_f32 v[58:59], v[78:79], v[58:59]
	v_and_b32_e32 v75, 0xffff0000, v44
	v_pk_mul_f32 v[58:59], v[58:59], v[64:65]
	v_lshlrev_b32_e32 v64, 16, v8
	v_and_b32_e32 v65, 0xffff0000, v8
	v_lshlrev_b32_e32 v78, 16, v30
	v_and_b32_e32 v79, 0xffff0000, v30
	v_and_b32_e32 v81, 0xffff0000, v36
	v_pk_mul_f32 v[64:65], v[74:75], v[64:65]
	v_pk_mul_f32 v[74:75], v[78:79], v[80:81]
	v_lshlrev_b32_e32 v82, 16, v48
	v_and_b32_e32 v83, 0xffff0000, v48
	v_lshlrev_b32_e32 v84, 16, v52
	v_and_b32_e32 v85, 0xffff0000, v52
	v_pk_mul_f32 v[60:61], v[74:75], v[60:61]
	v_pk_mul_f32 v[78:79], v[84:85], v[82:83]
	v_pk_fma_f32 v[56:57], v[64:65], v[56:57], v[60:61]
	v_lshlrev_b32_e32 v62, 16, v26
	v_pk_fma_f32 v[56:57], v[78:79], v[72:73], v[56:57]
	v_and_b32_e32 v63, 0xffff0000, v26
	v_pk_add_f32 v[56:57], v[76:77], v[56:57]
	v_mov_b32_e32 v61, v58
	v_pk_mul_f32 v[56:57], v[56:57], v[62:63]
	v_mov_b32_e32 v63, v59
	v_mov_b32_e32 v62, v57
	v_mov_b32_e32 v60, v56
	v_pk_mul_f32 v[62:63], v[62:63], v[62:63]
	s_nop 0
	v_pk_fma_f32 v[60:61], v[60:61], v[60:61], v[62:63]
	s_nop 0
	v_add_f32_e32 v60, v60, v61
	s_nop 1
	v_mov_b32_dpp v61, v60 quad_perm:[1,0,3,2] row_mask:0xf bank_mask:0xf
	s_waitcnt lgkmcnt(0)
	v_add_f32_e32 v60, v60, v61
	s_nop 1
	v_mov_b32_dpp v61, v60 quad_perm:[2,3,0,1] row_mask:0xf bank_mask:0xf
	s_waitcnt lgkmcnt(0)
	v_add_f32_e32 v60, v60, v61
	s_nop 1
	v_mov_b32_dpp v61, v60 row_half_mirror row_mask:0xf bank_mask:0xf
	s_waitcnt lgkmcnt(0)
	v_add_f32_e32 v60, v60, v61
	s_nop 1
	v_mov_b32_dpp v61, v60 row_mirror row_mask:0xf bank_mask:0xf
	s_waitcnt lgkmcnt(0)
	v_add_f32_e32 v60, v60, v61
	v_mov_b32_e32 v61, v60
	s_nop 1
	v_permlane16_swap_b32_e32 v60, v61
	s_waitcnt lgkmcnt(0)
	v_add_f32_e32 v60, v60, v61
	v_mov_b32_e32 v61, v60
	s_nop 1
	v_permlane32_swap_b32_e32 v60, v61
	s_waitcnt lgkmcnt(0)
	v_add_f32_e32 v60, v60, v61
	v_fmamk_f32 v60, v60, 0x3b800000, v212
	v_cmp_gt_f32_e32 vcc, s12, v60
	v_mul_f32_e32 v61, 0x4f800000, v60
	s_nop 0
	v_cndmask_b32_e32 v60, v60, v61, vcc
	v_sqrt_f32_e32 v61, v60
	s_nop 0
	v_add_u32_e32 v62, -1, v61
	v_fma_f32 v63, -v62, v61, v60
	v_cmp_ge_f32_e64 s[0:1], 0, v63
	v_add_u32_e32 v63, 1, v61
	s_nop 0
	v_cndmask_b32_e64 v62, v61, v62, s[0:1]
	v_fma_f32 v61, -v63, v61, v60
	v_cmp_lt_f32_e64 s[0:1], 0, v61
	s_nop 1
	v_cndmask_b32_e64 v61, v62, v63, s[0:1]
	v_mul_f32_e32 v62, 0x37800000, v61
	v_cndmask_b32_e32 v61, v61, v62, vcc
	v_cmp_class_f32_e32 vcc, v60, v241
	s_nop 1
	v_cndmask_b32_e32 v60, v61, v60, vcc
	v_div_scale_f32 v61, s[0:1], v60, v60, 1.0
	v_rcp_f32_e32 v62, v61
	s_lshl_b64 s[0:1], s[44:45], 11
	s_add_u32 s0, s84, s0
	s_addc_u32 s1, s85, s1
	v_fma_f32 v63, -v61, v62, 1.0
	v_fmac_f32_e32 v62, v63, v62
	v_div_scale_f32 v63, vcc, 1.0, v60, 1.0
	v_mul_f32_e32 v64, v63, v62
	v_fma_f32 v65, -v61, v64, v63
	v_fmac_f32_e32 v64, v65, v62
	v_fma_f32 v61, -v61, v64, v63
	v_div_fmas_f32 v61, v61, v62, v64
	v_div_fixup_f32 v60, v61, v60, 1.0
	v_pk_mul_f32 v[56:57], v[56:57], v[60:61] op_sel_hi:[1,0]
	v_pk_mul_f32 v[58:59], v[58:59], v[60:61] op_sel_hi:[1,0]
	v_cvt_pk_bf16_f32 v56, v56, v57
	v_cvt_pk_bf16_f32 v57, v58, v59
	v_lshl_add_u64 v[58:59], s[0:1], 0, v[98:99]
	v_add_co_u32_e32 v58, vcc, 0x1b00000, v58
	s_nop 1
	v_addc_co_u32_e32 v59, vcc, 0, v59, vcc
	global_store_dwordx2 v[58:59], v[56:57], off offset:1536
.LBB0_730:
	s_andn2_b64 vcc, exec, s[42:43]
	s_cbranch_vccnz .LBB0_698
	ds_bpermute_b32 v56, v3, v5
	s_cmpk_gt_i32 s36, 0x3fff
	v_mov_b32_e32 v57, v5
	s_cbranch_scc1 .LBB0_733
	s_and_b32 s0, s36, 63
	s_bfe_u32 s1, s36, 0x50006
	v_mov_b32_e32 v57, s0
	v_mov_b32_e32 v58, s1
	v_cndmask_b32_e64 v57, v57, v58, s[38:39]
	v_lshlrev_b32_e32 v58, 2, v70
	v_lshl_or_b32 v57, v57, 6, v58
	v_or_b32_e32 v57, 0x26000, v57
	ds_read_b32 v58, v57 offset:4096
	s_waitcnt lgkmcnt(0)
	v_mul_f32_e32 v56, v58, v56
	ds_read_b32 v59, v57
	v_cndmask_b32_e64 v57, v56, -v56, s[40:41]
	s_waitcnt lgkmcnt(0)
	v_fmac_f32_e32 v57, v5, v59
.LBB0_733:
	s_waitcnt lgkmcnt(0)
	v_bfe_u32 v56, v57, 16, 1
	s_movk_i32 s0, 0x7fff
	v_add3_u32 v56, v57, v56, s0
	v_lshrrev_b32_e32 v58, 16, v56
	v_mad_i64_i32 v[56:57], s[0:1], s36, v203, v[10:11]
	s_cmp_ge_i32 s36, s4
	global_store_short v[56:57], v58, off
	global_store_short v[56:57], v58, off offset:384
	global_store_short v[56:57], v58, off offset:768
	global_store_short v[56:57], v58, off offset:1152
	s_cbranch_scc1 .LBB0_698
	v_mov_b32_e32 v56, v104
	v_mov_b32_e32 v57, v105
	v_mov_b32_e32 v58, v106
	v_mov_b32_e32 v59, v107
	v_mov_b32_e32 v60, v108
	v_mov_b32_e32 v61, v109
	v_mov_b32_e32 v62, v110
	v_mov_b32_e32 v63, v111
	v_mov_b32_e32 v72, v112
	v_mov_b32_e32 v73, v113
	v_mov_b32_e32 v74, v114
	v_mov_b32_e32 v75, v115
	v_mov_b32_e32 v76, v116
	v_mov_b32_e32 v77, v117
	v_mov_b32_e32 v78, v118
	v_mov_b32_e32 v79, v119
	v_lshlrev_b32_e32 v80, 16, v43
	v_and_b32_e32 v81, 0xffff0000, v43
	v_lshlrev_b32_e32 v82, 16, v47
	v_and_b32_e32 v83, 0xffff0000, v47
	v_lshlrev_b32_e32 v84, 16, v29
	v_and_b32_e32 v85, 0xffff0000, v29
	v_lshlrev_b32_e32 v86, 16, v35
	v_and_b32_e32 v87, 0xffff0000, v35
	v_pk_mul_f32 v[80:81], v[82:83], v[80:81]
	v_pk_mul_f32 v[82:83], v[84:85], v[86:87]
	v_lshlrev_b32_e32 v88, 16, v51
	v_and_b32_e32 v89, 0xffff0000, v51
	v_lshlrev_b32_e32 v90, 16, v55
	v_and_b32_e32 v91, 0xffff0000, v55
	v_pk_mul_f32 v[84:85], v[90:91], v[88:89]
	v_lshlrev_b32_e32 v64, 16, v25
	v_and_b32_e32 v65, 0xffff0000, v25
	s_ashr_i32 s37, s36, 31
	v_lshlrev_b32_e32 v98, 1, v6
	v_pk_mul_f32 v[62:63], v[82:83], v[62:63]
	s_nop 0
	v_pk_fma_f32 v[58:59], v[80:81], v[58:59], v[62:63]
	v_lshlrev_b32_e32 v80, 16, v34
	v_pk_fma_f32 v[58:59], v[84:85], v[74:75], v[58:59]
	v_lshlrev_b32_e32 v74, 16, v46
	v_pk_add_f32 v[58:59], v[78:79], v[58:59]
	v_and_b32_e32 v75, 0xffff0000, v46
	v_pk_mul_f32 v[58:59], v[58:59], v[64:65]
	v_lshlrev_b32_e32 v64, 16, v42
	v_and_b32_e32 v65, 0xffff0000, v42
	v_lshlrev_b32_e32 v78, 16, v28
	v_and_b32_e32 v79, 0xffff0000, v28
	v_and_b32_e32 v81, 0xffff0000, v34
	v_pk_mul_f32 v[64:65], v[74:75], v[64:65]
	v_pk_mul_f32 v[74:75], v[78:79], v[80:81]
	v_lshlrev_b32_e32 v82, 16, v50
	v_and_b32_e32 v83, 0xffff0000, v50
	v_lshlrev_b32_e32 v84, 16, v54
	v_and_b32_e32 v85, 0xffff0000, v54
	v_pk_mul_f32 v[60:61], v[74:75], v[60:61]
	v_pk_mul_f32 v[78:79], v[84:85], v[82:83]
	v_pk_fma_f32 v[56:57], v[64:65], v[56:57], v[60:61]
	v_lshlrev_b32_e32 v62, 16, v24
	v_pk_fma_f32 v[56:57], v[78:79], v[72:73], v[56:57]
	v_and_b32_e32 v63, 0xffff0000, v24
	v_pk_add_f32 v[56:57], v[76:77], v[56:57]
	v_mov_b32_e32 v61, v58
	v_pk_mul_f32 v[56:57], v[56:57], v[62:63]
	v_mov_b32_e32 v63, v59
	v_mov_b32_e32 v62, v57
	v_mov_b32_e32 v60, v56
	v_pk_mul_f32 v[62:63], v[62:63], v[62:63]
	s_nop 0
	v_pk_fma_f32 v[60:61], v[60:61], v[60:61], v[62:63]
	s_nop 0
	v_add_f32_e32 v60, v60, v61
	s_nop 1
	v_mov_b32_dpp v61, v60 quad_perm:[1,0,3,2] row_mask:0xf bank_mask:0xf
	s_waitcnt lgkmcnt(0)
	v_add_f32_e32 v60, v60, v61
	s_nop 1
	v_mov_b32_dpp v61, v60 quad_perm:[2,3,0,1] row_mask:0xf bank_mask:0xf
	s_waitcnt lgkmcnt(0)
	v_add_f32_e32 v60, v60, v61
	s_nop 1
	v_mov_b32_dpp v61, v60 row_half_mirror row_mask:0xf bank_mask:0xf
	s_waitcnt lgkmcnt(0)
	v_add_f32_e32 v60, v60, v61
	s_nop 1
	v_mov_b32_dpp v61, v60 row_mirror row_mask:0xf bank_mask:0xf
	s_waitcnt lgkmcnt(0)
	v_add_f32_e32 v60, v60, v61
	v_mov_b32_e32 v61, v60
	s_nop 1
	v_permlane16_swap_b32_e32 v60, v61
	s_waitcnt lgkmcnt(0)
	v_add_f32_e32 v60, v60, v61
	v_mov_b32_e32 v61, v60
	s_nop 1
	v_permlane32_swap_b32_e32 v60, v61
	s_waitcnt lgkmcnt(0)
	v_add_f32_e32 v60, v60, v61
	v_fmamk_f32 v60, v60, 0x3b800000, v212
	v_cmp_gt_f32_e32 vcc, s12, v60
	v_mul_f32_e32 v61, 0x4f800000, v60
	s_nop 0
	v_cndmask_b32_e32 v60, v60, v61, vcc
	v_sqrt_f32_e32 v61, v60
	s_nop 0
	v_add_u32_e32 v62, -1, v61
	v_fma_f32 v63, -v62, v61, v60
	v_cmp_ge_f32_e64 s[0:1], 0, v63
	v_add_u32_e32 v63, 1, v61
	s_nop 0
	v_cndmask_b32_e64 v62, v61, v62, s[0:1]
	v_fma_f32 v61, -v63, v61, v60
	v_cmp_lt_f32_e64 s[0:1], 0, v61
	s_nop 1
	v_cndmask_b32_e64 v61, v62, v63, s[0:1]
	v_mul_f32_e32 v62, 0x37800000, v61
	v_cndmask_b32_e32 v61, v61, v62, vcc
	v_cmp_class_f32_e32 vcc, v60, v241
	s_nop 1
	v_cndmask_b32_e32 v60, v61, v60, vcc
	v_div_scale_f32 v61, s[0:1], v60, v60, 1.0
	v_rcp_f32_e32 v62, v61
	s_lshl_b64 s[0:1], s[36:37], 11
	s_add_u32 s0, s84, s0
	s_addc_u32 s1, s85, s1
	v_fma_f32 v63, -v61, v62, 1.0
	v_fmac_f32_e32 v62, v63, v62
	v_div_scale_f32 v63, vcc, 1.0, v60, 1.0
	v_mul_f32_e32 v64, v63, v62
	v_fma_f32 v65, -v61, v64, v63
	v_fmac_f32_e32 v64, v65, v62
	v_fma_f32 v61, -v61, v64, v63
	v_div_fmas_f32 v61, v61, v62, v64
	v_div_fixup_f32 v60, v61, v60, 1.0
	v_pk_mul_f32 v[56:57], v[56:57], v[60:61] op_sel_hi:[1,0]
	v_pk_mul_f32 v[58:59], v[58:59], v[60:61] op_sel_hi:[1,0]
	v_cvt_pk_bf16_f32 v56, v56, v57
	v_cvt_pk_bf16_f32 v57, v58, v59
	v_lshl_add_u64 v[58:59], s[0:1], 0, v[98:99]
	v_add_co_u32_e32 v58, vcc, 0x1b00000, v58
	s_nop 1
	v_addc_co_u32_e32 v59, vcc, 0, v59, vcc
	global_store_dwordx2 v[58:59], v[56:57], off offset:1536
	s_branch .LBB0_698

.LBB0_803:
	s_lshl_b32 s0, s4, 11
	s_and_b32 s7, s4, 31
	v_mov_b32_e32 v78, v0
	s_and_b32 s0, s0, 0x3800
	v_readlane_b32 s1, v252, 2
	s_add_u32 s0, s1, s0
	v_and_b32_e32 v80, 15, v78
	v_readlane_b32 s1, v252, 3
	s_addc_u32 s1, s1, 0
	v_lshlrev_b32_e32 v98, 7, v80
	s_waitcnt lgkmcnt(0)
	v_lshl_add_u64 v[2:3], s[0:1], 0, v[98:99]
	v_readlane_b32 s0, v251, 62
	v_lshlrev_b32_e32 v10, 4, v80
	v_mov_b32_e32 v11, v99
	v_readlane_b32 s1, v251, 63
	v_readlane_b32 s10, v254, 15
	v_ashrrev_i32_e32 v17, 4, v78
	v_bfe_u32 v81, v78, 4, 2
	v_lshl_add_u64 v[14:15], s[0:1], 0, v[10:11]
	v_add_u32_e32 v16, s10, v10
	v_lshlrev_b32_e32 v10, 7, v17
	v_lshlrev_b32_e32 v74, 4, v81
	v_mov_b32_e32 v75, v99
	v_ashrrev_i32_e32 v11, 31, v10
	v_lshl_add_u64 v[2:3], v[2:3], 0, v[74:75]
	v_lshl_add_u64 v[10:11], v[10:11], 1, v[14:15]
	global_load_dwordx4 v[6:9], v[2:3], off
	s_nop 0
	global_load_dwordx4 v[2:5], v[2:3], off offset:64
	v_mul_lo_u32 v17, v17, s31
	global_load_dwordx4 v[10:13], v[10:11], off
	v_add_u32_e32 v18, v16, v17
	v_add_u32_e32 v20, 0x200, v78
	v_readlane_b32 s11, v254, 16
	v_ashrrev_i32_e32 v82, 6, v78
	v_readlane_b32 s8, v252, 0
	v_readlane_b32 s9, v252, 1
	v_lshrrev_b32_e32 v83, 4, v78
	v_lshlrev_b32_e32 v79, 6, v80
	s_waitcnt vmcnt(0)
	ds_write_b128 v18, v[10:13]
	v_ashrrev_i32_e32 v18, 4, v20
	v_lshlrev_b32_e32 v10, 7, v18
	v_ashrrev_i32_e32 v11, 31, v10
	v_lshl_add_u64 v[10:11], v[10:11], 1, v[14:15]
	global_load_dwordx4 v[10:13], v[10:11], off
	v_mul_lo_u32 v21, v18, s31
	v_add_u32_e32 v18, v16, v21
	s_waitcnt vmcnt(0)
	ds_write_b128 v18, v[10:13]
	v_add_u32_e32 v10, 0x400, v78
	v_ashrrev_i32_e32 v18, 4, v10
	v_lshlrev_b32_e32 v10, 7, v18
	v_ashrrev_i32_e32 v11, 31, v10
	v_lshl_add_u64 v[10:11], v[10:11], 1, v[14:15]
	global_load_dwordx4 v[10:13], v[10:11], off
	v_mad_u64_u32 v[18:19], s[0:1], v18, s31, v[16:17]
	s_waitcnt vmcnt(0)
	ds_write_b128 v18, v[10:13]
	v_add_u32_e32 v10, 0x600, v78
	v_ashrrev_i32_e32 v18, 4, v10
	v_lshlrev_b32_e32 v10, 7, v18
	v_ashrrev_i32_e32 v11, 31, v10
	v_lshl_add_u64 v[10:11], v[10:11], 1, v[14:15]
	global_load_dwordx4 v[10:13], v[10:11], off
	v_mad_u64_u32 v[14:15], s[0:1], v18, s31, v[16:17]
	v_readlane_b32 s0, v252, 4
	v_readlane_b32 s1, v252, 5
	s_waitcnt vmcnt(0)
	ds_write_b128 v14, v[10:13]
	v_lshlrev_b32_e32 v10, 4, v78
	v_lshlrev_b32_e32 v14, 2, v78
	v_and_b32_e32 v10, 0xf0, v10
	v_ashrrev_i32_e32 v15, 31, v14
	v_add_u32_e32 v16, s11, v10
	v_lshl_add_u64 v[10:11], v[14:15], 2, s[0:1]
	global_load_dwordx4 v[10:13], v[10:11], off
	v_add_u32_e32 v15, v16, v17
	s_waitcnt vmcnt(0)
	ds_write_b128 v15, v[10:13]
	v_lshlrev_b32_e32 v10, 2, v20
	v_ashrrev_i32_e32 v11, 31, v10
	v_lshl_add_u64 v[10:11], v[10:11], 2, s[0:1]
	global_load_dwordx4 v[10:13], v[10:11], off
	v_add_u32_e32 v15, v16, v21
	s_and_b32 s1, s2, 0xfffff800
	s_lshl_b32 s0, s7, 4
	s_and_b32 s68, s0, 0x180
	s_waitcnt vmcnt(0)
	ds_write_b128 v15, v[10:13]
	v_or_b32_e32 v11, s1, v80
	v_lshlrev_b32_e32 v12, 3, v78
	v_lshl_add_u32 v76, v82, 8, v11
	v_lshlrev_b32_e32 v10, 4, v82
	v_and_b32_e32 v84, 0x80, v12
	v_and_b32_e32 v12, 0x80, v14
	v_ashrrev_i32_e32 v77, 31, v76
	v_add3_u32 v85, 0, v10, v12
	v_lshlrev_b64 v[10:11], 12, v[76:77]
	v_lshl_add_u64 v[10:11], s[86:87], 0, v[10:11]
	v_lshl_add_u64 v[10:11], v[10:11], 0, s[68:69]
	v_lshl_add_u64 v[10:11], v[10:11], 0, v[74:75]
	v_lshl_add_u64 v[12:13], v[10:11], 0, s[34:35]
	v_add_co_u32_e32 v10, vcc, s95, v10
	v_or_b32_e32 v14, 0x50, v76
	s_nop 0
	v_addc_co_u32_e32 v11, vcc, 0, v11, vcc
	global_load_dwordx4 v[70:73], v[10:11], off offset:1536
	global_load_dwordx4 v[62:65], v[12:13], off offset:64
	v_or_b32_e32 v10, 16, v76
	v_ashrrev_i32_e32 v11, 31, v10
	v_lshlrev_b64 v[10:11], 12, v[10:11]
	v_lshl_add_u64 v[10:11], s[86:87], 0, v[10:11]
	v_lshl_add_u64 v[10:11], v[10:11], 0, s[68:69]
	v_lshl_add_u64 v[10:11], v[10:11], 0, v[74:75]
	v_lshl_add_u64 v[12:13], v[10:11], 0, s[34:35]
	v_add_co_u32_e32 v10, vcc, s95, v10
	v_ashrrev_i32_e32 v15, 31, v14
	s_nop 0
	v_addc_co_u32_e32 v11, vcc, 0, v11, vcc
	global_load_dwordx4 v[66:69], v[10:11], off offset:1536
	global_load_dwordx4 v[54:57], v[12:13], off offset:64
	v_or_b32_e32 v10, 32, v76
	v_ashrrev_i32_e32 v11, 31, v10
	v_lshlrev_b64 v[10:11], 12, v[10:11]
	v_lshl_add_u64 v[10:11], s[86:87], 0, v[10:11]
	v_lshl_add_u64 v[10:11], v[10:11], 0, s[68:69]
	v_lshl_add_u64 v[10:11], v[10:11], 0, v[74:75]
	v_lshl_add_u64 v[12:13], v[10:11], 0, s[34:35]
	v_add_co_u32_e32 v10, vcc, s95, v10
	v_lshlrev_b64 v[14:15], 12, v[14:15]
	s_nop 0
	v_addc_co_u32_e32 v11, vcc, 0, v11, vcc
	global_load_dwordx4 v[58:61], v[10:11], off offset:1536
	global_load_dwordx4 v[38:41], v[12:13], off offset:64
	v_or_b32_e32 v10, 48, v76
	v_ashrrev_i32_e32 v11, 31, v10
	v_lshlrev_b64 v[10:11], 12, v[10:11]
	v_lshl_add_u64 v[10:11], s[86:87], 0, v[10:11]
	v_lshl_add_u64 v[10:11], v[10:11], 0, s[68:69]
	v_lshl_add_u64 v[10:11], v[10:11], 0, v[74:75]
	v_lshl_add_u64 v[12:13], v[10:11], 0, s[34:35]
	v_add_co_u32_e32 v10, vcc, s95, v10
	v_lshl_add_u64 v[14:15], s[86:87], 0, v[14:15]
	s_nop 0
	v_addc_co_u32_e32 v11, vcc, 0, v11, vcc
	global_load_dwordx4 v[50:53], v[10:11], off offset:1536
	global_load_dwordx4 v[22:25], v[12:13], off offset:64
	v_or_b32_e32 v10, 64, v76
	v_ashrrev_i32_e32 v11, 31, v10
	v_lshlrev_b64 v[10:11], 12, v[10:11]
	v_lshl_add_u64 v[10:11], s[86:87], 0, v[10:11]
	v_lshl_add_u64 v[10:11], v[10:11], 0, s[68:69]
	v_lshl_add_u64 v[10:11], v[10:11], 0, v[74:75]
	v_lshl_add_u64 v[12:13], v[10:11], 0, s[34:35]
	v_add_co_u32_e32 v10, vcc, s95, v10
	v_lshl_add_u64 v[14:15], v[14:15], 0, s[68:69]
	v_or_b32_e32 v30, 0x60, v76
	v_addc_co_u32_e32 v11, vcc, 0, v11, vcc
	v_lshl_add_u64 v[14:15], v[14:15], 0, v[74:75]
	v_ashrrev_i32_e32 v31, 31, v30
	v_lshl_add_u64 v[18:19], v[14:15], 0, s[34:35]
	v_add_co_u32_e32 v14, vcc, s95, v14
	v_lshlrev_b64 v[30:31], 12, v[30:31]
	s_nop 0
	v_addc_co_u32_e32 v15, vcc, 0, v15, vcc
	v_lshl_add_u64 v[30:31], s[86:87], 0, v[30:31]
	global_load_dwordx4 v[26:29], v[10:11], off offset:1536
	s_nop 0
	global_load_dwordx4 v[10:13], v[12:13], off offset:64
	s_nop 0
	global_load_dwordx4 v[14:17], v[14:15], off offset:1536
	s_nop 0
	global_load_dwordx4 v[18:21], v[18:19], off offset:64
	v_lshl_add_u64 v[30:31], v[30:31], 0, s[68:69]
	v_lshl_add_u64 v[30:31], v[30:31], 0, v[74:75]
	v_lshl_add_u64 v[34:35], v[30:31], 0, s[34:35]
	v_add_co_u32_e32 v30, vcc, s95, v30
	v_or_b32_e32 v42, 0x70, v76
	s_nop 0
	v_addc_co_u32_e32 v31, vcc, 0, v31, vcc
	global_load_dwordx4 v[30:33], v[30:31], off offset:1536
	s_nop 0
	global_load_dwordx4 v[34:37], v[34:35], off offset:64
	v_ashrrev_i32_e32 v43, 31, v42
	v_lshlrev_b64 v[42:43], 12, v[42:43]
	v_lshl_add_u64 v[42:43], s[86:87], 0, v[42:43]
	v_lshl_add_u64 v[42:43], v[42:43], 0, s[68:69]
	v_lshl_add_u64 v[42:43], v[42:43], 0, v[74:75]
	v_lshl_add_u64 v[46:47], v[42:43], 0, s[34:35]
	v_add_co_u32_e32 v42, vcc, s95, v42
	s_waitcnt vmcnt(3)
	v_mfma_f32_16x16x32_bf16 v[14:17], v[6:9], v[14:17], 0
	v_addc_co_u32_e32 v43, vcc, 0, v43, vcc
	global_load_dwordx4 v[42:45], v[42:43], off offset:1536
	s_nop 0
	global_load_dwordx4 v[46:49], v[46:47], off offset:64
	v_mfma_f32_16x16x32_bf16 v[26:29], v[6:9], v[26:29], 0
	s_waitcnt vmcnt(4)
	v_mfma_f32_16x16x32_bf16 v[14:17], v[2:5], v[18:21], v[14:17]
	s_waitcnt vmcnt(3)
	v_mfma_f32_16x16x32_bf16 v[18:21], v[6:9], v[30:33], 0
	v_mfma_f32_16x16x32_bf16 v[70:73], v[6:9], v[70:73], 0
	v_mfma_f32_16x16x32_bf16 v[58:61], v[6:9], v[58:61], 0
	v_mfma_f32_16x16x32_bf16 v[10:13], v[2:5], v[10:13], v[26:29]
	s_waitcnt vmcnt(2)
	v_mfma_f32_16x16x32_bf16 v[18:21], v[2:5], v[34:37], v[18:21]
	v_mfma_f32_16x16x32_bf16 v[62:65], v[2:5], v[62:65], v[70:73]
	v_mfma_f32_16x16x32_bf16 v[38:41], v[2:5], v[38:41], v[58:61]
	s_nop 5
	v_cvt_pk_bf16_f32 v31, v10, v18
	v_or_b32_e32 v18, 32, v84
	v_or_b32_e32 v10, v84, v80
	s_waitcnt vmcnt(1)
	v_mfma_f32_16x16x32_bf16 v[26:29], v[6:9], v[42:45], 0
	v_cvt_pk_bf16_f32 v11, v11, v19
	v_or_b32_e32 v19, v18, v80
	v_cvt_pk_bf16_f32 v30, v62, v38
	v_mfma_f32_16x16x32_bf16 v[66:69], v[6:9], v[66:69], 0
	v_mad_u32_u24 v38, v10, s31, v85
	v_cvt_pk_bf16_f32 v10, v63, v39
	v_mad_u32_u24 v39, v19, s31, v85
	v_mfma_f32_16x16x32_bf16 v[50:53], v[6:9], v[50:53], 0
	ds_write_b64 v38, v[30:31]
	ds_write_b64 v39, v[10:11]
	v_cvt_pk_bf16_f32 v11, v12, v20
	v_or_b32_e32 v12, 64, v84
	v_or_b32_e32 v19, v12, v80
	s_waitcnt vmcnt(0)
	v_mfma_f32_16x16x32_bf16 v[26:29], v[2:5], v[46:49], v[26:29]
	v_cvt_pk_bf16_f32 v10, v64, v40
	v_mad_u32_u24 v40, v19, s31, v85
	ds_write_b64 v40, v[10:11]
	v_mfma_f32_16x16x32_bf16 v[54:57], v[2:5], v[54:57], v[66:69]
	v_cvt_pk_bf16_f32 v11, v13, v21
	v_or_b32_e32 v13, 0x60, v84
	v_or_b32_e32 v19, v13, v80
	v_mfma_f32_16x16x32_bf16 v[22:25], v[2:5], v[22:25], v[50:53]
	v_cvt_pk_bf16_f32 v10, v65, v41
	v_mad_u32_u24 v41, v19, s31, v85
	v_or_b32_e32 v72, 16, v80
	ds_write_b64 v41, v[10:11]
	v_cvt_pk_bf16_f32 v11, v14, v26
	v_or_b32_e32 v14, v84, v72
	s_nop 1
	v_cvt_pk_bf16_f32 v10, v54, v22
	v_mad_u32_u24 v42, v14, s31, v85
	v_or_b32_e32 v14, v18, v72
	ds_write_b64 v42, v[10:11]
	v_cvt_pk_bf16_f32 v10, v55, v23
	v_cvt_pk_bf16_f32 v11, v15, v27
	v_mad_u32_u24 v43, v14, s31, v85
	v_or_b32_e32 v12, v12, v72
	ds_write_b64 v43, v[10:11]
	v_cvt_pk_bf16_f32 v10, v56, v24
	v_cvt_pk_bf16_f32 v11, v16, v28
	v_mad_u32_u24 v44, v12, s31, v85
	v_or_b32_e32 v12, v13, v72
	ds_write_b64 v44, v[10:11]
	v_cvt_pk_bf16_f32 v10, v57, v25
	v_cvt_pk_bf16_f32 v11, v17, v29
	v_mad_u32_u24 v45, v12, s31, v85
	ds_write_b64 v45, v[10:11]
	v_or_b32_e32 v10, 0x80, v76
	v_ashrrev_i32_e32 v11, 31, v10
	v_lshlrev_b64 v[10:11], 12, v[10:11]
	v_lshl_add_u64 v[10:11], s[86:87], 0, v[10:11]
	v_lshl_add_u64 v[10:11], v[10:11], 0, s[68:69]
	v_lshl_add_u64 v[10:11], v[10:11], 0, v[74:75]
	v_lshl_add_u64 v[12:13], v[10:11], 0, s[34:35]
	v_add_co_u32_e32 v10, vcc, s95, v10
	v_or_b32_e32 v14, 0xf0, v76
	s_nop 0
	v_addc_co_u32_e32 v11, vcc, 0, v11, vcc
	global_load_dwordx4 v[46:49], v[10:11], off offset:1536
	global_load_dwordx4 v[50:53], v[12:13], off offset:64
	v_or_b32_e32 v10, 0x90, v76
	v_ashrrev_i32_e32 v11, 31, v10
	v_lshlrev_b64 v[10:11], 12, v[10:11]
	v_lshl_add_u64 v[10:11], s[86:87], 0, v[10:11]
	v_lshl_add_u64 v[10:11], v[10:11], 0, s[68:69]
	v_lshl_add_u64 v[10:11], v[10:11], 0, v[74:75]
	v_lshl_add_u64 v[12:13], v[10:11], 0, s[34:35]
	v_add_co_u32_e32 v10, vcc, s95, v10
	v_ashrrev_i32_e32 v15, 31, v14
	s_nop 0
	v_addc_co_u32_e32 v11, vcc, 0, v11, vcc
	global_load_dwordx4 v[54:57], v[10:11], off offset:1536
	global_load_dwordx4 v[58:61], v[12:13], off offset:64
	v_or_b32_e32 v10, 0xa0, v76
	v_ashrrev_i32_e32 v11, 31, v10
	v_lshlrev_b64 v[10:11], 12, v[10:11]
	v_lshl_add_u64 v[10:11], s[86:87], 0, v[10:11]
	v_lshl_add_u64 v[10:11], v[10:11], 0, s[68:69]
	v_lshl_add_u64 v[10:11], v[10:11], 0, v[74:75]
	v_lshl_add_u64 v[12:13], v[10:11], 0, s[34:35]
	v_add_co_u32_e32 v10, vcc, s95, v10
	v_lshlrev_b64 v[14:15], 12, v[14:15]
	s_nop 0
	v_addc_co_u32_e32 v11, vcc, 0, v11, vcc
	global_load_dwordx4 v[62:65], v[10:11], off offset:1536
	global_load_dwordx4 v[66:69], v[12:13], off offset:64
	v_or_b32_e32 v10, 0xb0, v76
	v_ashrrev_i32_e32 v11, 31, v10
	v_lshlrev_b64 v[10:11], 12, v[10:11]
	v_lshl_add_u64 v[10:11], s[86:87], 0, v[10:11]
	v_lshl_add_u64 v[10:11], v[10:11], 0, s[68:69]
	v_lshl_add_u64 v[10:11], v[10:11], 0, v[74:75]
	v_lshl_add_u64 v[12:13], v[10:11], 0, s[34:35]
	v_add_co_u32_e32 v10, vcc, s95, v10
	v_lshl_add_u64 v[14:15], s[86:87], 0, v[14:15]
	s_nop 0
	v_addc_co_u32_e32 v11, vcc, 0, v11, vcc
	global_load_dwordx4 v[84:87], v[10:11], off offset:1536
	global_load_dwordx4 v[88:91], v[12:13], off offset:64
	v_or_b32_e32 v10, 0xc0, v76
	v_ashrrev_i32_e32 v11, 31, v10
	v_lshlrev_b64 v[10:11], 12, v[10:11]
	v_lshl_add_u64 v[10:11], s[86:87], 0, v[10:11]
	v_lshl_add_u64 v[10:11], v[10:11], 0, s[68:69]
	v_lshl_add_u64 v[10:11], v[10:11], 0, v[74:75]
	v_lshl_add_u64 v[12:13], v[10:11], 0, s[34:35]
	v_add_co_u32_e32 v10, vcc, s95, v10
	v_lshl_add_u64 v[14:15], v[14:15], 0, s[68:69]
	s_nop 0
	v_addc_co_u32_e32 v11, vcc, 0, v11, vcc
	global_load_dwordx4 v[92:95], v[10:11], off offset:1536
	global_load_dwordx4 v[30:33], v[12:13], off offset:64
	v_or_b32_e32 v10, 0xd0, v76
	v_ashrrev_i32_e32 v11, 31, v10
	v_lshlrev_b64 v[10:11], 12, v[10:11]
	v_lshl_add_u64 v[10:11], s[86:87], 0, v[10:11]
	v_lshl_add_u64 v[10:11], v[10:11], 0, s[68:69]
	v_lshl_add_u64 v[10:11], v[10:11], 0, v[74:75]
	v_lshl_add_u64 v[12:13], v[10:11], 0, s[34:35]
	v_add_co_u32_e32 v10, vcc, s95, v10
	v_lshl_add_u64 v[14:15], v[14:15], 0, v[74:75]
	s_nop 0
	v_addc_co_u32_e32 v11, vcc, 0, v11, vcc
	global_load_dwordx4 v[34:37], v[10:11], off offset:1536
	global_load_dwordx4 v[22:25], v[12:13], off offset:64
	v_or_b32_e32 v10, 0xe0, v76
	v_ashrrev_i32_e32 v11, 31, v10
	v_lshlrev_b64 v[10:11], 12, v[10:11]
	v_lshl_add_u64 v[10:11], s[86:87], 0, v[10:11]
	v_lshl_add_u64 v[10:11], v[10:11], 0, s[68:69]
	v_lshl_add_u64 v[10:11], v[10:11], 0, v[74:75]
	v_lshl_add_u64 v[12:13], v[10:11], 0, s[34:35]
	v_add_co_u32_e32 v10, vcc, s95, v10
	v_lshl_add_u64 v[18:19], v[14:15], 0, s[34:35]
	s_nop 0
	v_addc_co_u32_e32 v11, vcc, 0, v11, vcc
	global_load_dwordx4 v[26:29], v[10:11], off offset:1536
	s_nop 0
	global_load_dwordx4 v[10:13], v[12:13], off offset:64
	v_add_co_u32_e32 v14, vcc, s95, v14
	s_waitcnt vmcnt(13)
	v_mfma_f32_16x16x32_bf16 v[46:49], v[6:9], v[46:49], 0
	v_addc_co_u32_e32 v15, vcc, 0, v15, vcc
	global_load_dwordx4 v[14:17], v[14:15], off offset:1536
	s_nop 0
	global_load_dwordx4 v[18:21], v[18:19], off offset:64
	s_waitcnt vmcnt(14)
	v_mfma_f32_16x16x32_bf16 v[46:49], v[2:5], v[50:53], v[46:49]
	s_waitcnt vmcnt(13)
	v_mfma_f32_16x16x32_bf16 v[50:53], v[6:9], v[54:57], 0
	s_waitcnt vmcnt(11)
	v_mfma_f32_16x16x32_bf16 v[54:57], v[6:9], v[62:65], 0
	s_waitcnt vmcnt(7)
	v_mfma_f32_16x16x32_bf16 v[62:65], v[6:9], v[92:95], 0
	s_waitcnt vmcnt(3)
	v_mfma_f32_16x16x32_bf16 v[26:29], v[6:9], v[26:29], 0
	v_mfma_f32_16x16x32_bf16 v[50:53], v[2:5], v[58:61], v[50:53]
	v_mfma_f32_16x16x32_bf16 v[54:57], v[2:5], v[66:69], v[54:57]
	v_mfma_f32_16x16x32_bf16 v[58:61], v[6:9], v[84:87], 0
	v_mfma_f32_16x16x32_bf16 v[30:33], v[2:5], v[30:33], v[62:65]
	v_mfma_f32_16x16x32_bf16 v[34:37], v[6:9], v[34:37], 0
	s_waitcnt vmcnt(2)
	v_mfma_f32_16x16x32_bf16 v[10:13], v[2:5], v[10:13], v[26:29]
	s_waitcnt vmcnt(1)
	v_mfma_f32_16x16x32_bf16 v[6:9], v[6:9], v[14:17], 0
	v_mfma_f32_16x16x32_bf16 v[58:61], v[2:5], v[88:91], v[58:61]
	v_mfma_f32_16x16x32_bf16 v[22:25], v[2:5], v[22:25], v[34:37]
	s_waitcnt vmcnt(0)
	v_mfma_f32_16x16x32_bf16 v[2:5], v[2:5], v[18:21], v[6:9]
	v_lshl_or_b32 v18, v82, 5, v80
	v_mul_lo_u32 v18, v18, s31
	v_mov_b32_e32 v36, 0x1100
	s_nop 0
	v_cvt_pk_bf16_f32 v6, v46, v54
	v_cvt_pk_bf16_f32 v7, v30, v10
	ds_write_b64 v38, v[6:7] offset:8
	v_cvt_pk_bf16_f32 v6, v47, v55
	v_cvt_pk_bf16_f32 v7, v31, v11
	ds_write_b64 v39, v[6:7] offset:8
	v_cvt_pk_bf16_f32 v6, v48, v56
	v_cvt_pk_bf16_f32 v7, v32, v12
	ds_write_b64 v40, v[6:7] offset:8
	v_cvt_pk_bf16_f32 v6, v49, v57
	v_cvt_pk_bf16_f32 v7, v33, v13
	ds_write_b64 v41, v[6:7] offset:8
	v_cvt_pk_bf16_f32 v6, v50, v58
	v_cvt_pk_bf16_f32 v7, v22, v2
	v_cvt_pk_bf16_f32 v2, v51, v59
	v_cvt_pk_bf16_f32 v3, v23, v3
	ds_write_b64 v42, v[6:7] offset:8
	ds_write_b64 v43, v[2:3] offset:8
	v_cvt_pk_bf16_f32 v2, v52, v60
	v_cvt_pk_bf16_f32 v3, v24, v4
	ds_write_b64 v44, v[2:3] offset:8
	v_cvt_pk_bf16_f32 v2, v53, v61
	v_cvt_pk_bf16_f32 v3, v25, v5
	v_mov_b32_e32 v44, 0x2200
	v_mov_b32_e32 v53, 0x3300
	ds_write_b64 v45, v[2:3] offset:8
	v_lshl_add_u64 v[2:3], s[8:9], 0, v[74:75]
	v_add3_u32 v31, 0, v18, v74
	v_add_u32_e32 v52, s10, v74
	v_mad_u32_u24 v75, v80, s31, v36
	v_mad_u32_u24 v74, v80, s31, v44
	v_mad_u32_u24 v73, v80, s31, v53
	v_lshl_add_u64 v[2:3], v[2:3], 0, v[98:99]
	v_mad_u32_u24 v30, v80, s31, v52
	v_add_u32_e32 v76, v52, v75
	v_add_u32_e32 v77, v52, v74
	v_add_u32_e32 v96, v52, v73
	global_load_dwordx4 v[10:13], v[2:3], off
	global_load_dwordx4 v[6:9], v[2:3], off offset:64
	global_load_dwordx4 v[14:17], v[2:3], off offset:2048
	s_nop 0
	global_load_dwordx4 v[2:5], v[2:3], off offset:2112
	s_waitcnt lgkmcnt(0)
	s_barrier
	ds_read_b128 v[18:21], v31
	ds_read_b128 v[22:25], v31 offset:4352
	ds_read_b128 v[26:29], v30
	ds_read_b128 v[60:63], v30 offset:17408
	ds_read_b128 v[36:39], v76
	ds_read_b128 v[100:103], v30 offset:30464
	ds_read_b128 v[44:47], v77
	ds_read_b128 v[52:55], v96
	ds_read_b128 v[68:71], v30 offset:21760
	ds_read_b128 v[88:91], v30 offset:26112
	s_waitcnt lgkmcnt(7)
	v_mfma_f32_16x16x32_bf16 v[32:35], v[18:21], v[26:29], 0
	s_movk_i32 s10, 0x90
	v_bfe_u32 v98, v78, 1, 3
	v_mfma_f32_16x16x32_bf16 v[26:29], v[22:25], v[26:29], 0
	s_waitcnt lgkmcnt(5)
	v_mfma_f32_16x16x32_bf16 v[40:43], v[18:21], v[36:39], 0
	v_mfma_f32_16x16x32_bf16 v[36:39], v[22:25], v[36:39], 0
	s_waitcnt lgkmcnt(3)
	v_mfma_f32_16x16x32_bf16 v[48:51], v[18:21], v[44:47], 0
	v_mfma_f32_16x16x32_bf16 v[44:47], v[22:25], v[44:47], 0
	s_waitcnt lgkmcnt(2)
	v_mfma_f32_16x16x32_bf16 v[56:59], v[18:21], v[52:55], 0
	v_mfma_f32_16x16x32_bf16 v[52:55], v[22:25], v[52:55], 0
	v_mfma_f32_16x16x32_bf16 v[64:67], v[18:21], v[60:63], 0
	v_mfma_f32_16x16x32_bf16 v[60:63], v[22:25], v[60:63], 0
	s_waitcnt lgkmcnt(1)
	v_mfma_f32_16x16x32_bf16 v[84:87], v[18:21], v[68:71], 0
	v_mfma_f32_16x16x32_bf16 v[68:71], v[22:25], v[68:71], 0
	s_waitcnt lgkmcnt(0)
	v_mfma_f32_16x16x32_bf16 v[92:95], v[18:21], v[88:91], 0
	v_mfma_f32_16x16x32_bf16 v[88:91], v[22:25], v[88:91], 0
	v_mfma_f32_16x16x32_bf16 v[18:21], v[18:21], v[100:103], 0
	v_mfma_f32_16x16x32_bf16 v[22:25], v[22:25], v[100:103], 0
	ds_read_b128 v[100:103], v31 offset:64
	ds_read_b128 v[104:107], v31 offset:4416
	ds_read_b128 v[108:111], v30 offset:64
	s_waitcnt lgkmcnt(0)
	v_mfma_f32_16x16x32_bf16 v[32:35], v[100:103], v[108:111], v[32:35]
	v_mfma_f32_16x16x32_bf16 v[26:29], v[104:107], v[108:111], v[26:29]
	ds_read_b128 v[108:111], v76 offset:64
	s_waitcnt lgkmcnt(0)
	v_mfma_f32_16x16x32_bf16 v[40:43], v[100:103], v[108:111], v[40:43]
	v_mfma_f32_16x16x32_bf16 v[36:39], v[104:107], v[108:111], v[36:39]
	ds_read_b128 v[108:111], v77 offset:64
	s_waitcnt lgkmcnt(0)
	v_mfma_f32_16x16x32_bf16 v[48:51], v[100:103], v[108:111], v[48:51]
	v_mfma_f32_16x16x32_bf16 v[44:47], v[104:107], v[108:111], v[44:47]
	ds_read_b128 v[108:111], v96 offset:64
	s_waitcnt lgkmcnt(0)
	v_mfma_f32_16x16x32_bf16 v[56:59], v[100:103], v[108:111], v[56:59]
	v_mfma_f32_16x16x32_bf16 v[52:55], v[104:107], v[108:111], v[52:55]
	ds_read_b128 v[108:111], v30 offset:17472
	s_waitcnt lgkmcnt(0)
	v_mfma_f32_16x16x32_bf16 v[64:67], v[100:103], v[108:111], v[64:67]
	v_mfma_f32_16x16x32_bf16 v[60:63], v[104:107], v[108:111], v[60:63]
	ds_read_b128 v[108:111], v30 offset:21824
	s_waitcnt lgkmcnt(0)
	v_mfma_f32_16x16x32_bf16 v[84:87], v[100:103], v[108:111], v[84:87]
	v_mfma_f32_16x16x32_bf16 v[68:71], v[104:107], v[108:111], v[68:71]
	ds_read_b128 v[108:111], v30 offset:26176
	s_waitcnt lgkmcnt(0)
	v_mfma_f32_16x16x32_bf16 v[92:95], v[100:103], v[108:111], v[92:95]
	v_mfma_f32_16x16x32_bf16 v[88:91], v[104:107], v[108:111], v[88:91]
	ds_read_b128 v[108:111], v30 offset:30528
	s_waitcnt lgkmcnt(0)
	v_mfma_f32_16x16x32_bf16 v[18:21], v[100:103], v[108:111], v[18:21]
	v_mfma_f32_16x16x32_bf16 v[22:25], v[104:107], v[108:111], v[22:25]
	ds_read_b128 v[100:103], v31 offset:128
	ds_read_b128 v[104:107], v31 offset:4480
	ds_read_b128 v[108:111], v30 offset:128
	s_waitcnt lgkmcnt(0)
	v_mfma_f32_16x16x32_bf16 v[32:35], v[100:103], v[108:111], v[32:35]
	v_mfma_f32_16x16x32_bf16 v[26:29], v[104:107], v[108:111], v[26:29]
	ds_read_b128 v[108:111], v76 offset:128
	s_waitcnt lgkmcnt(0)
	v_mfma_f32_16x16x32_bf16 v[40:43], v[100:103], v[108:111], v[40:43]
	v_mfma_f32_16x16x32_bf16 v[36:39], v[104:107], v[108:111], v[36:39]
	ds_read_b128 v[108:111], v77 offset:128
	s_waitcnt lgkmcnt(0)
	v_mfma_f32_16x16x32_bf16 v[112:115], v[100:103], v[108:111], v[48:51]
	v_mfma_f32_16x16x32_bf16 v[46:49], v[104:107], v[108:111], v[44:47]
	ds_read_b128 v[108:111], v96 offset:128
	s_waitcnt lgkmcnt(0)
	v_mfma_f32_16x16x32_bf16 v[56:59], v[100:103], v[108:111], v[56:59]
	v_mfma_f32_16x16x32_bf16 v[108:111], v[104:107], v[108:111], v[52:55]
	s_nop 2
	ds_read_b128 v[50:53], v30 offset:17536
	s_waitcnt lgkmcnt(0)
	v_mfma_f32_16x16x32_bf16 v[116:119], v[100:103], v[50:53], v[64:67]
	v_mfma_f32_16x16x32_bf16 v[120:123], v[104:107], v[50:53], v[60:63]
	ds_read_b128 v[50:53], v30 offset:21888
	s_waitcnt lgkmcnt(0)
	v_mfma_f32_16x16x32_bf16 v[84:87], v[100:103], v[50:53], v[84:87]
	v_mfma_f32_16x16x32_bf16 v[124:127], v[104:107], v[50:53], v[68:71]
	ds_read_b128 v[50:53], v30 offset:26240
	s_waitcnt lgkmcnt(0)
	v_mfma_f32_16x16x32_bf16 v[92:95], v[100:103], v[50:53], v[92:95]
	v_mfma_f32_16x16x32_bf16 v[88:91], v[104:107], v[50:53], v[88:91]
	ds_read_b128 v[50:53], v30 offset:30592
	s_waitcnt lgkmcnt(0)
	v_mfma_f32_16x16x32_bf16 v[100:103], v[100:103], v[50:53], v[18:21]
	ds_read_b128 v[128:131], v31 offset:192
	ds_read_b128 v[132:135], v31 offset:4544
	s_nop 0
	ds_read_b128 v[18:21], v30 offset:192
	s_waitcnt lgkmcnt(0)
	v_mfma_f32_16x16x32_bf16 v[136:139], v[128:131], v[18:21], v[32:35]
	v_mfma_f32_16x16x32_bf16 v[62:65], v[132:135], v[18:21], v[26:29]
	ds_read_b128 v[18:21], v76 offset:192
	v_bfe_u32 v76, v83, 1, 1
	v_mfma_f32_16x16x32_bf16 v[104:107], v[104:107], v[50:53], v[22:25]
	s_waitcnt lgkmcnt(0)
	v_mfma_f32_16x16x32_bf16 v[50:53], v[128:131], v[18:21], v[40:43]
	v_mfma_f32_16x16x32_bf16 v[42:45], v[132:135], v[18:21], v[36:39]
	ds_read_b128 v[18:21], v77 offset:192
	s_nop 1
	ds_read_b128 v[38:41], v30 offset:17600
	s_waitcnt lgkmcnt(1)
	v_mfma_f32_16x16x32_bf16 v[34:37], v[128:131], v[18:21], v[112:115]
	v_lshl_add_u32 v77, v81, 5, s11
	v_mad_u32_u24 v83, v80, s31, v77
	v_add_u32_e32 v75, v77, v75
	v_mfma_f32_16x16x32_bf16 v[26:29], v[132:135], v[18:21], v[46:49]
	ds_read_b128 v[18:21], v96 offset:192
	s_waitcnt lgkmcnt(0)
	v_mfma_f32_16x16x32_bf16 v[22:25], v[128:131], v[18:21], v[56:59]
	v_mfma_f32_16x16x32_bf16 v[18:21], v[132:135], v[18:21], v[108:111]
	v_mfma_f32_16x16x32_bf16 v[108:111], v[128:131], v[38:41], v[116:119]
	v_mfma_f32_16x16x32_bf16 v[112:115], v[132:135], v[38:41], v[120:123]
	ds_read_b128 v[38:41], v30 offset:21952
	s_waitcnt lgkmcnt(0)
	v_mfma_f32_16x16x32_bf16 v[66:69], v[128:131], v[38:41], v[84:87]
	v_mfma_f32_16x16x32_bf16 v[58:61], v[132:135], v[38:41], v[124:127]
	ds_read_b128 v[38:41], v30 offset:26304
	ds_read_b128 v[30:33], v30 offset:30656
	s_waitcnt lgkmcnt(0)
	v_mfma_f32_16x16x32_bf16 v[46:49], v[132:135], v[38:41], v[88:91]
	s_barrier
	ds_read_b128 v[84:87], v83
	s_nop 0
	ds_read_b128 v[88:91], v83 offset:16
	v_mfma_f32_16x16x32_bf16 v[54:57], v[128:131], v[38:41], v[92:95]
	s_waitcnt lgkmcnt(0)
	v_mov_b32_e32 v97, v90
	s_nop 0
	v_lshrrev_b32_e32 v93, 1, v78
	v_mov_b32_e32 v95, v86
	v_mov_b32_e32 v86, v85
	v_mov_b32_e32 v90, v89
	v_and_b32_e32 v70, 8, v93
	v_mov_b32_e32 v94, v84
	v_pk_mul_f32 v[84:85], v[108:109], v[86:87]
	v_mov_b32_e32 v96, v88
	v_pk_mul_f32 v[88:89], v[110:111], v[90:91]
	v_add_u32_e32 v92, 0, v70
	v_lshl_add_u32 v70, v80, 3, v82
	v_pk_fma_f32 v[84:85], v[136:137], v[94:95], v[84:85] neg_lo:[0,0,1] neg_hi:[0,0,1]
	v_pk_fma_f32 v[88:89], v[138:139], v[96:97], v[88:89] neg_lo:[0,0,1] neg_hi:[0,0,1]
	v_mad_u64_u32 v[70:71], s[8:9], v70, s10, v[92:93]
	v_cvt_pk_bf16_f32 v84, v84, v85
	v_cvt_pk_bf16_f32 v85, v88, v89
	v_pk_mul_f32 v[88:89], v[108:109], v[94:95]
	v_bitop3_b32 v71, v76, v93, 7 bitop3:0x78
	v_pk_fma_f32 v[86:87], v[136:137], v[86:87], v[88:89]
	v_pk_mul_f32 v[88:89], v[110:111], v[96:97]
	v_lshlrev_b32_e32 v71, 4, v71
	v_pk_fma_f32 v[88:89], v[138:139], v[90:91], v[88:89]
	v_cvt_pk_bf16_f32 v86, v86, v87
	v_cvt_pk_bf16_f32 v87, v88, v89
	v_add_u32_e32 v88, v70, v71
	ds_write_b64 v88, v[84:85]
	v_bitop3_b32 v84, v76, v98, 4 bitop3:0x36
	v_mfma_f32_16x16x32_bf16 v[38:41], v[128:131], v[30:33], v[100:103]
	s_nop 2
	v_lshlrev_b32_e32 v100, 4, v84
	v_add_u32_e32 v84, v70, v100
	ds_write_b64 v84, v[86:87]
	ds_read_b128 v[84:87], v83 offset:128
	ds_read_b128 v[88:91], v83 offset:144
	v_mfma_f32_16x16x32_bf16 v[30:33], v[132:135], v[30:33], v[104:107]
	s_waitcnt lgkmcnt(1)
	v_mov_b32_e32 v95, v86
	v_mov_b32_e32 v86, v85
	s_waitcnt lgkmcnt(0)
	v_mov_b32_e32 v97, v90
	v_mov_b32_e32 v90, v89
	v_mov_b32_e32 v94, v84
	v_pk_mul_f32 v[84:85], v[112:113], v[86:87]
	v_mov_b32_e32 v96, v88
	v_pk_mul_f32 v[88:89], v[114:115], v[90:91]
	v_pk_fma_f32 v[84:85], v[62:63], v[94:95], v[84:85] neg_lo:[0,0,1] neg_hi:[0,0,1]
	v_pk_fma_f32 v[88:89], v[64:65], v[96:97], v[88:89] neg_lo:[0,0,1] neg_hi:[0,0,1]
	v_cvt_pk_bf16_f32 v84, v84, v85
	v_cvt_pk_bf16_f32 v85, v88, v89
	v_pk_mul_f32 v[88:89], v[112:113], v[94:95]
	s_nop 0
	v_pk_fma_f32 v[62:63], v[62:63], v[86:87], v[88:89]
	v_pk_mul_f32 v[86:87], v[114:115], v[96:97]
	v_cvt_pk_bf16_f32 v62, v62, v63
	v_pk_fma_f32 v[64:65], v[64:65], v[90:91], v[86:87]
	s_nop 0
	v_cvt_pk_bf16_f32 v63, v64, v65
	v_bitop3_b32 v64, v76, v98, 2 bitop3:0x36
	v_lshlrev_b32_e32 v83, 4, v64
	v_add_u32_e32 v64, v70, v83
	ds_write_b64 v64, v[84:85]
	v_bitop3_b32 v64, v76, v98, 6 bitop3:0x36
	v_lshlrev_b32_e32 v94, 4, v64
	v_add_u32_e32 v64, v70, v94
	ds_write_b64 v64, v[62:63]
	v_lshl_add_u32 v62, v72, 3, v82
	v_mad_u64_u32 v[88:89], s[8:9], v62, s10, v[92:93]
	ds_read_b128 v[62:65], v75
	ds_read_b128 v[84:87], v75 offset:16
	s_waitcnt lgkmcnt(1)
	v_mov_b32_e32 v90, v62
	v_mov_b32_e32 v91, v64
	v_mov_b32_e32 v64, v63
	v_pk_mul_f32 v[62:63], v[66:67], v[64:65]
	s_waitcnt lgkmcnt(0)
	v_mov_b32_e32 v92, v84
	v_mov_b32_e32 v93, v86
	v_mov_b32_e32 v86, v85
	v_pk_mul_f32 v[66:67], v[66:67], v[90:91]
	v_pk_fma_f32 v[62:63], v[50:51], v[90:91], v[62:63] neg_lo:[0,0,1] neg_hi:[0,0,1]
	v_pk_mul_f32 v[84:85], v[68:69], v[86:87]
	v_pk_fma_f32 v[50:51], v[50:51], v[64:65], v[66:67]
	v_pk_mul_f32 v[64:65], v[68:69], v[92:93]
	v_pk_fma_f32 v[84:85], v[52:53], v[92:93], v[84:85] neg_lo:[0,0,1] neg_hi:[0,0,1]
	v_pk_fma_f32 v[52:53], v[52:53], v[86:87], v[64:65]
	v_cvt_pk_bf16_f32 v62, v62, v63
	v_cvt_pk_bf16_f32 v63, v84, v85
	v_cvt_pk_bf16_f32 v50, v50, v51
	v_cvt_pk_bf16_f32 v51, v52, v53
	v_add_u32_e32 v52, v88, v71
	ds_write_b64 v52, v[62:63]
	v_add_u32_e32 v52, v88, v100
	ds_write_b64 v52, v[50:51]
	ds_read_b128 v[50:53], v75 offset:128
	ds_read_b128 v[62:65], v75 offset:144
	s_waitcnt lgkmcnt(1)
	v_mov_b32_e32 v66, v50
	v_mov_b32_e32 v67, v52
	v_mov_b32_e32 v52, v51
	v_pk_mul_f32 v[50:51], v[58:59], v[52:53]
	s_waitcnt lgkmcnt(0)
	v_mov_b32_e32 v68, v62
	v_mov_b32_e32 v69, v64
	v_mov_b32_e32 v64, v63
	v_pk_mul_f32 v[58:59], v[58:59], v[66:67]
	v_pk_fma_f32 v[50:51], v[42:43], v[66:67], v[50:51] neg_lo:[0,0,1] neg_hi:[0,0,1]
	v_pk_mul_f32 v[62:63], v[60:61], v[64:65]
	v_pk_fma_f32 v[42:43], v[42:43], v[52:53], v[58:59]
	v_pk_mul_f32 v[52:53], v[60:61], v[68:69]
	v_pk_fma_f32 v[62:63], v[44:45], v[68:69], v[62:63] neg_lo:[0,0,1] neg_hi:[0,0,1]
	v_pk_fma_f32 v[44:45], v[44:45], v[64:65], v[52:53]
	v_cvt_pk_bf16_f32 v50, v50, v51
	v_cvt_pk_bf16_f32 v51, v62, v63
	v_cvt_pk_bf16_f32 v42, v42, v43
	v_cvt_pk_bf16_f32 v43, v44, v45
	v_add_u32_e32 v44, v88, v83
	ds_write_b64 v44, v[50:51]
	v_add_u32_e32 v44, v88, v94
	ds_write_b64 v44, v[42:43]
	v_add_u32_e32 v62, v77, v74
	ds_read_b128 v[42:45], v62
	ds_read_b128 v[50:53], v62 offset:16
	v_add_u32_e32 v63, 0x9000, v70
	s_waitcnt lgkmcnt(1)
	v_mov_b32_e32 v59, v44
	v_mov_b32_e32 v44, v43
	s_waitcnt lgkmcnt(0)
	v_mov_b32_e32 v61, v52
	v_mov_b32_e32 v52, v51
	v_mov_b32_e32 v58, v42
	v_pk_mul_f32 v[42:43], v[54:55], v[44:45]
	v_mov_b32_e32 v60, v50
	v_pk_mul_f32 v[50:51], v[56:57], v[52:53]
	v_pk_fma_f32 v[42:43], v[34:35], v[58:59], v[42:43] neg_lo:[0,0,1] neg_hi:[0,0,1]
	v_pk_fma_f32 v[50:51], v[36:37], v[60:61], v[50:51] neg_lo:[0,0,1] neg_hi:[0,0,1]
	v_cvt_pk_bf16_f32 v42, v42, v43
	v_cvt_pk_bf16_f32 v43, v50, v51
	v_pk_mul_f32 v[50:51], v[54:55], v[58:59]
	s_nop 0
	v_pk_fma_f32 v[34:35], v[34:35], v[44:45], v[50:51]
	v_pk_mul_f32 v[44:45], v[56:57], v[60:61]
	v_cvt_pk_bf16_f32 v34, v34, v35
	v_pk_fma_f32 v[36:37], v[36:37], v[52:53], v[44:45]
	s_nop 0
	v_cvt_pk_bf16_f32 v35, v36, v37
	v_add_u32_e32 v36, v63, v71
	ds_write_b64 v36, v[42:43]
	v_add_u32_e32 v36, v63, v100
	ds_write_b64 v36, v[34:35]
	ds_read_b128 v[34:37], v62 offset:128
	ds_read_b128 v[42:45], v62 offset:144
	s_waitcnt lgkmcnt(1)
	v_mov_b32_e32 v51, v36
	v_mov_b32_e32 v36, v35
	s_waitcnt lgkmcnt(0)
	v_mov_b32_e32 v53, v44
	v_mov_b32_e32 v44, v43
	v_mov_b32_e32 v50, v34
	v_pk_mul_f32 v[34:35], v[46:47], v[36:37]
	v_mov_b32_e32 v52, v42
	v_pk_mul_f32 v[42:43], v[48:49], v[44:45]
	v_pk_fma_f32 v[34:35], v[26:27], v[50:51], v[34:35] neg_lo:[0,0,1] neg_hi:[0,0,1]
	v_pk_fma_f32 v[42:43], v[28:29], v[52:53], v[42:43] neg_lo:[0,0,1] neg_hi:[0,0,1]
	v_cvt_pk_bf16_f32 v34, v34, v35
	v_cvt_pk_bf16_f32 v35, v42, v43
	v_pk_mul_f32 v[42:43], v[46:47], v[50:51]
	v_add_u32_e32 v46, v77, v73
	v_pk_fma_f32 v[26:27], v[26:27], v[36:37], v[42:43]
	v_pk_mul_f32 v[36:37], v[48:49], v[52:53]
	v_cvt_pk_bf16_f32 v26, v26, v27
	v_pk_fma_f32 v[28:29], v[28:29], v[44:45], v[36:37]
	v_add_u32_e32 v47, 0xd800, v70
	v_cvt_pk_bf16_f32 v27, v28, v29
	v_add_u32_e32 v28, v63, v83
	ds_write_b64 v28, v[34:35]
	v_add_u32_e32 v28, v63, v94
	ds_write_b64 v28, v[26:27]
	ds_read_b128 v[26:29], v46
	ds_read_b128 v[34:37], v46 offset:16
	s_waitcnt lgkmcnt(1)
	v_mov_b32_e32 v43, v28
	v_mov_b32_e32 v28, v27
	s_waitcnt lgkmcnt(0)
	v_mov_b32_e32 v45, v36
	v_mov_b32_e32 v36, v35
	v_mov_b32_e32 v42, v26
	v_pk_mul_f32 v[26:27], v[38:39], v[28:29]
	v_mov_b32_e32 v44, v34
	v_pk_mul_f32 v[34:35], v[40:41], v[36:37]
	v_pk_fma_f32 v[26:27], v[22:23], v[42:43], v[26:27] neg_lo:[0,0,1] neg_hi:[0,0,1]
	v_pk_fma_f32 v[34:35], v[24:25], v[44:45], v[34:35] neg_lo:[0,0,1] neg_hi:[0,0,1]
	v_cvt_pk_bf16_f32 v26, v26, v27
	v_cvt_pk_bf16_f32 v27, v34, v35
	v_pk_mul_f32 v[34:35], v[38:39], v[42:43]
	s_nop 0
	v_pk_fma_f32 v[22:23], v[22:23], v[28:29], v[34:35]
	v_pk_mul_f32 v[28:29], v[40:41], v[44:45]
	v_cvt_pk_bf16_f32 v22, v22, v23
	v_pk_fma_f32 v[24:25], v[24:25], v[36:37], v[28:29]
	s_nop 0
	v_cvt_pk_bf16_f32 v23, v24, v25
	v_add_u32_e32 v24, v47, v71
	ds_write_b64 v24, v[26:27]
	v_add_u32_e32 v24, v47, v100
	ds_write_b64 v24, v[22:23]
	ds_read_b128 v[22:25], v46 offset:128
	ds_read_b128 v[26:29], v46 offset:144
	v_lshlrev_b32_e32 v46, 2, v82
	v_or_b32_e32 v42, 2, v46
	s_waitcnt lgkmcnt(1)
	v_mov_b32_e32 v35, v24
	v_mov_b32_e32 v24, v23
	s_waitcnt lgkmcnt(0)
	v_mov_b32_e32 v37, v28
	v_mov_b32_e32 v28, v27
	v_mov_b32_e32 v34, v22
	v_pk_mul_f32 v[22:23], v[30:31], v[24:25]
	v_mov_b32_e32 v36, v26
	v_pk_mul_f32 v[26:27], v[32:33], v[28:29]
	v_pk_fma_f32 v[22:23], v[18:19], v[34:35], v[22:23] neg_lo:[0,0,1] neg_hi:[0,0,1]
	v_pk_fma_f32 v[26:27], v[20:21], v[36:37], v[26:27] neg_lo:[0,0,1] neg_hi:[0,0,1]
	v_cvt_pk_bf16_f32 v22, v22, v23
	v_cvt_pk_bf16_f32 v23, v26, v27
	v_pk_mul_f32 v[26:27], v[30:31], v[34:35]
	s_nop 0
	v_pk_fma_f32 v[18:19], v[18:19], v[24:25], v[26:27]
	v_pk_mul_f32 v[24:25], v[32:33], v[36:37]
	v_cvt_pk_bf16_f32 v18, v18, v19
	v_pk_fma_f32 v[20:21], v[20:21], v[28:29], v[24:25]
	v_bitop3_b32 v27, v81, v46, 4 bitop3:0x72
	v_cvt_pk_bf16_f32 v19, v20, v21
	v_add_u32_e32 v20, v47, v83
	ds_write_b64 v20, v[22:23]
	v_add_u32_e32 v20, v47, v94
	ds_write_b64 v20, v[18:19]
	v_and_b32_e32 v18, 0xfffffcf, v78
	v_mul_lo_u32 v18, v18, s10
	v_add_u32_e32 v26, 0, v18
	v_and_or_b32 v18, v46, 4, v81
	v_lshl_add_u32 v18, v18, 4, v26
	s_waitcnt lgkmcnt(0)
	s_barrier
	ds_read_b128 v[18:21], v18
	v_lshl_add_u32 v26, v27, 4, v26
	ds_read_b128 v[26:29], v26
	s_waitcnt vmcnt(3) lgkmcnt(1)
	v_mfma_f32_16x16x32_bf16 v[22:25], v[18:21], v[10:13], 0
	v_or_b32_e32 v47, 4, v81
	s_waitcnt vmcnt(1)
	v_mfma_f32_16x16x32_bf16 v[18:21], v[18:21], v[14:17], 0
	s_waitcnt lgkmcnt(0)
	v_mfma_f32_16x16x32_bf16 v[38:41], v[26:29], v[6:9], v[22:25]
	s_waitcnt vmcnt(0)
	v_mfma_f32_16x16x32_bf16 v[34:37], v[26:29], v[2:5], v[18:21]
	v_or_b32_e32 v26, 1, v46
	v_or_b32_e32 v46, 3, v46
	s_nop 1
	v_lshl_or_b32 v18, v26, 4, v80
	v_mul_lo_u32 v18, v18, s10
	v_add_u32_e32 v27, 0, v18
	v_bitop3_b32 v18, v26, v81, 5 bitop3:0x6c
	v_lshl_add_u32 v18, v18, 4, v27
	ds_read_b128 v[18:21], v18
	v_bitop3_b32 v26, v26, v47, 5 bitop3:0x6c
	v_lshl_add_u32 v26, v26, 4, v27
	ds_read_b128 v[26:29], v26
	s_waitcnt lgkmcnt(1)
	v_mfma_f32_16x16x32_bf16 v[22:25], v[18:21], v[10:13], 0
	v_mfma_f32_16x16x32_bf16 v[18:21], v[18:21], v[14:17], 0
	s_waitcnt lgkmcnt(0)
	v_mfma_f32_16x16x32_bf16 v[30:33], v[26:29], v[6:9], v[22:25]
	v_mfma_f32_16x16x32_bf16 v[26:29], v[26:29], v[2:5], v[18:21]
	s_nop 4
	v_lshl_or_b32 v18, v42, 4, v80
	v_mul_lo_u32 v18, v18, s10
	v_add_u32_e32 v43, 0, v18
	v_bitop3_b32 v18, v42, v81, 6 bitop3:0x6c
	v_lshl_add_u32 v18, v18, 4, v43
	ds_read_b128 v[18:21], v18
	v_bitop3_b32 v42, v42, v47, 6 bitop3:0x6c
	v_lshl_add_u32 v42, v42, 4, v43
	ds_read_b128 v[42:45], v42
	s_waitcnt lgkmcnt(1)
	v_mfma_f32_16x16x32_bf16 v[22:25], v[18:21], v[10:13], 0
	v_mfma_f32_16x16x32_bf16 v[18:21], v[18:21], v[14:17], 0
	s_waitcnt lgkmcnt(0)
	v_mfma_f32_16x16x32_bf16 v[22:25], v[42:45], v[6:9], v[22:25]
	v_mfma_f32_16x16x32_bf16 v[18:21], v[42:45], v[2:5], v[18:21]
	v_lshl_or_b32 v42, v46, 4, v80
	v_mul_lo_u32 v42, v42, s10
	v_add_u32_e32 v48, 0, v42
	v_bitop3_b32 v42, v46, v81, 7 bitop3:0x6c
	v_lshl_add_u32 v42, v42, 4, v48
	ds_read_b128 v[42:45], v42
	s_waitcnt lgkmcnt(0)
	v_mfma_f32_16x16x32_bf16 v[10:13], v[42:45], v[10:13], 0
	v_mfma_f32_16x16x32_bf16 v[14:17], v[42:45], v[14:17], 0
	v_bitop3_b32 v42, v46, v47, 7 bitop3:0x6c
	v_lshl_add_u32 v42, v42, 4, v48
	ds_read_b128 v[42:45], v42
	s_waitcnt lgkmcnt(0)
	v_mfma_f32_16x16x32_bf16 v[6:9], v[42:45], v[6:9], v[10:13]
	s_nop 2
	v_and_b32_e32 v13, 64, v1
	v_lshlrev_b32_e32 v10, 3, v82
	v_xor_b32_e32 v11, 16, v1
	v_add_u32_e32 v13, 64, v13
	v_add3_u32 v10, v10, s1, v79
	v_cmp_lt_i32_e32 vcc, v11, v13
	v_or_b32_e32 v10, v10, v76
	v_mfma_f32_16x16x32_bf16 v[2:5], v[42:45], v[2:5], v[14:17]
	v_cndmask_b32_e32 v11, v1, v11, vcc
	s_lshl_b32 s1, s7, 2
	v_bfe_u32 v12, v78, 4, 1
	v_lshlrev_b32_e32 v14, 2, v11
	v_pk_mul_f32 v[16:17], v[38:39], s[88:89] op_sel_hi:[1,0]
	v_pk_mul_f32 v[38:39], v[40:41], s[88:89] op_sel_hi:[1,0]
	v_ashrrev_i32_e32 v11, 31, v10
	v_cvt_pk_bf16_f32 v16, v16, v17
	v_cvt_pk_bf16_f32 v17, v38, v39
	v_lshlrev_b64 v[38:39], 11, v[10:11]
	s_add_u32 s22, s24, s1
	v_lshl_add_u64 v[38:39], s[84:85], 0, v[38:39]
	s_mov_b32 s1, s69
	v_lshl_add_u64 v[38:39], v[38:39], 0, s[0:1]
	v_lshlrev_b32_e32 v98, 3, v12
	v_lshl_add_u64 v[38:39], v[38:39], 0, v[98:99]
	s_mov_b32 s0, 0x1b00000
	v_add_co_u32_e32 v38, vcc, s0, v38
	v_and_b32_e32 v15, 0xffff0000, v16
	s_nop 0
	v_addc_co_u32_e32 v39, vcc, 0, v39, vcc
	global_store_dwordx2 v[38:39], v[16:17], off offset:1024
	v_lshlrev_b32_e32 v13, 16, v16
	v_mul_f32_e32 v15, v15, v15
	v_and_b32_e32 v16, 0xffff0000, v17
	v_fmac_f32_e32 v15, v13, v13
	v_lshlrev_b32_e32 v13, 16, v17
	v_mul_f32_e32 v16, v16, v16
	v_fmac_f32_e32 v16, v13, v13
	v_add_f32_e32 v13, v15, v16
	v_mov_b32_e32 v15, v13
	s_nop 1
	v_permlane16_swap_b32_e32 v13, v15
	v_cmp_eq_u32_e64 s[38:39], 0, v12
	s_addc_u32 s23, s25, 0
	s_and_saveexec_b64 s[0:1], s[38:39]
	s_cbranch_execz .LBB0_805
	v_lshlrev_b64 v[16:17], 7, v[10:11]
	s_waitcnt lgkmcnt(0)
	v_add_f32_e32 v13, v13, v15
	v_lshl_add_u64 v[16:17], s[22:23], 0, v[16:17]
	global_store_dword v[16:17], v13, off
.LBB0_805:
	s_or_b64 exec, exec, s[0:1]
	v_lshlrev_b32_e32 v11, 2, v12
	v_pk_mul_f32 v[12:13], v[34:35], s[88:89] op_sel_hi:[1,0]
	s_lshl_b32 s0, s7, 3
	v_cvt_pk_bf16_f32 v16, v12, v13
	v_pk_mul_f32 v[12:13], v[36:37], s[88:89] op_sel_hi:[1,0]
	s_lshl_b32 s68, s0, 1
	v_cvt_pk_bf16_f32 v17, v12, v13
	v_add_u32_e32 v12, 0x400, v10
	v_ashrrev_i32_e32 v13, 31, v12
	v_lshlrev_b64 v[34:35], 11, v[12:13]
	v_lshl_add_u64 v[34:35], s[84:85], 0, v[34:35]
	v_lshl_add_u64 v[34:35], v[34:35], 0, s[68:69]
	v_lshlrev_b32_e32 v98, 1, v11
	v_lshl_add_u64 v[34:35], v[34:35], 0, v[98:99]
	s_mov_b32 s7, 0x1b00000
	v_add_co_u32_e32 v34, vcc, s7, v34
	s_waitcnt lgkmcnt(0)
	v_and_b32_e32 v15, 0xffff0000, v16
	v_addc_co_u32_e32 v35, vcc, 0, v35, vcc
	global_store_dwordx2 v[34:35], v[16:17], off offset:1024
	v_lshlrev_b32_e32 v11, 16, v16
	v_mul_f32_e32 v15, v15, v15
	v_and_b32_e32 v16, 0xffff0000, v17
	v_fmac_f32_e32 v15, v11, v11
	v_lshlrev_b32_e32 v11, 16, v17
	v_mul_f32_e32 v16, v16, v16
	v_fmac_f32_e32 v16, v11, v11
	v_add_f32_e32 v11, v15, v16
	v_mov_b32_e32 v15, v11
	s_nop 1
	v_permlane16_swap_b32_e32 v11, v15
	s_and_saveexec_b64 s[0:1], s[38:39]
	s_cbranch_execz .LBB0_807
	v_lshlrev_b64 v[12:13], 7, v[12:13]
	s_waitcnt lgkmcnt(0)
	v_add_f32_e32 v11, v11, v15
	v_lshl_add_u64 v[12:13], s[22:23], 0, v[12:13]
	global_store_dword v[12:13], v11, off
.LBB0_807:
	s_or_b64 exec, exec, s[0:1]
	v_or_b32_e32 v12, 2, v10
	v_pk_mul_f32 v[16:17], v[30:31], s[88:89] op_sel_hi:[1,0]
	v_pk_mul_f32 v[30:31], v[32:33], s[88:89] op_sel_hi:[1,0]
	v_ashrrev_i32_e32 v13, 31, v12
	v_cvt_pk_bf16_f32 v16, v16, v17
	v_cvt_pk_bf16_f32 v17, v30, v31
	v_lshlrev_b64 v[30:31], 11, v[12:13]
	v_lshl_add_u64 v[30:31], s[84:85], 0, v[30:31]
	v_lshl_add_u64 v[30:31], v[30:31], 0, s[68:69]
	v_lshl_add_u64 v[30:31], v[30:31], 0, v[98:99]
	v_add_co_u32_e32 v30, vcc, s7, v30
	s_waitcnt lgkmcnt(0)
	v_and_b32_e32 v15, 0xffff0000, v16
	v_addc_co_u32_e32 v31, vcc, 0, v31, vcc
	global_store_dwordx2 v[30:31], v[16:17], off offset:1024
	v_lshlrev_b32_e32 v11, 16, v16
	v_mul_f32_e32 v15, v15, v15
	v_and_b32_e32 v16, 0xffff0000, v17
	v_fmac_f32_e32 v15, v11, v11
	v_lshlrev_b32_e32 v11, 16, v17
	v_mul_f32_e32 v16, v16, v16
	v_fmac_f32_e32 v16, v11, v11
	v_add_f32_e32 v11, v15, v16
	v_mov_b32_e32 v15, v11
	s_nop 1
	v_permlane16_swap_b32_e32 v11, v15
	s_and_saveexec_b64 s[0:1], s[38:39]
	s_cbranch_execz .LBB0_809
	v_lshlrev_b64 v[12:13], 7, v[12:13]
	s_waitcnt lgkmcnt(0)
	v_add_f32_e32 v11, v11, v15
	v_lshl_add_u64 v[12:13], s[22:23], 0, v[12:13]
	global_store_dword v[12:13], v11, off
.LBB0_809:
	s_or_b64 exec, exec, s[0:1]
	v_pk_mul_f32 v[12:13], v[26:27], s[88:89] op_sel_hi:[1,0]
	s_nop 0
	v_cvt_pk_bf16_f32 v16, v12, v13
	v_pk_mul_f32 v[12:13], v[28:29], s[88:89] op_sel_hi:[1,0]
	s_waitcnt lgkmcnt(0)
	v_and_b32_e32 v15, 0xffff0000, v16
	v_cvt_pk_bf16_f32 v17, v12, v13
	v_add_u32_e32 v12, 0x402, v10
	v_ashrrev_i32_e32 v13, 31, v12
	v_lshlrev_b64 v[26:27], 11, v[12:13]
	v_lshl_add_u64 v[26:27], s[84:85], 0, v[26:27]
	v_lshl_add_u64 v[26:27], v[26:27], 0, s[68:69]
	v_lshl_add_u64 v[26:27], v[26:27], 0, v[98:99]
	v_add_co_u32_e32 v26, vcc, s7, v26
	v_lshlrev_b32_e32 v11, 16, v16
	s_nop 0
	v_addc_co_u32_e32 v27, vcc, 0, v27, vcc
	global_store_dwordx2 v[26:27], v[16:17], off offset:1024
	v_mul_f32_e32 v15, v15, v15
	v_and_b32_e32 v16, 0xffff0000, v17
	v_fmac_f32_e32 v15, v11, v11
	v_lshlrev_b32_e32 v11, 16, v17
	v_mul_f32_e32 v16, v16, v16
	v_fmac_f32_e32 v16, v11, v11
	v_add_f32_e32 v11, v15, v16
	v_mov_b32_e32 v15, v11
	s_nop 1
	v_permlane16_swap_b32_e32 v11, v15
	s_and_saveexec_b64 s[0:1], s[38:39]
	s_cbranch_execz .LBB0_811
	v_lshlrev_b64 v[12:13], 7, v[12:13]
	s_waitcnt lgkmcnt(0)
	v_add_f32_e32 v11, v11, v15
	v_lshl_add_u64 v[12:13], s[22:23], 0, v[12:13]
	global_store_dword v[12:13], v11, off
.LBB0_811:
	s_or_b64 exec, exec, s[0:1]
	v_or_b32_e32 v12, 4, v10
	v_pk_mul_f32 v[16:17], v[22:23], s[88:89] op_sel_hi:[1,0]
	v_pk_mul_f32 v[22:23], v[24:25], s[88:89] op_sel_hi:[1,0]
	v_ashrrev_i32_e32 v13, 31, v12
	v_cvt_pk_bf16_f32 v16, v16, v17
	v_cvt_pk_bf16_f32 v17, v22, v23
	v_lshlrev_b64 v[22:23], 11, v[12:13]
	v_lshl_add_u64 v[22:23], s[84:85], 0, v[22:23]
	v_lshl_add_u64 v[22:23], v[22:23], 0, s[68:69]
	v_lshl_add_u64 v[22:23], v[22:23], 0, v[98:99]
	v_add_co_u32_e32 v22, vcc, s7, v22
	s_waitcnt lgkmcnt(0)
	v_and_b32_e32 v15, 0xffff0000, v16
	v_addc_co_u32_e32 v23, vcc, 0, v23, vcc
	global_store_dwordx2 v[22:23], v[16:17], off offset:1024
	v_lshlrev_b32_e32 v11, 16, v16
	v_mul_f32_e32 v15, v15, v15
	v_and_b32_e32 v16, 0xffff0000, v17
	v_fmac_f32_e32 v15, v11, v11
	v_lshlrev_b32_e32 v11, 16, v17
	v_mul_f32_e32 v16, v16, v16
	v_fmac_f32_e32 v16, v11, v11
	v_add_f32_e32 v11, v15, v16
	v_mov_b32_e32 v15, v11
	s_nop 1
	v_permlane16_swap_b32_e32 v11, v15
	s_and_saveexec_b64 s[0:1], s[38:39]
	s_cbranch_execz .LBB0_813
	v_lshlrev_b64 v[12:13], 7, v[12:13]
	s_waitcnt lgkmcnt(0)
	v_add_f32_e32 v11, v11, v15
	v_lshl_add_u64 v[12:13], s[22:23], 0, v[12:13]
	global_store_dword v[12:13], v11, off
.LBB0_813:
	s_or_b64 exec, exec, s[0:1]
	v_pk_mul_f32 v[12:13], v[18:19], s[88:89] op_sel_hi:[1,0]
	s_nop 0
	v_cvt_pk_bf16_f32 v16, v12, v13
	v_pk_mul_f32 v[12:13], v[20:21], s[88:89] op_sel_hi:[1,0]
	s_waitcnt lgkmcnt(0)
	v_and_b32_e32 v15, 0xffff0000, v16
	v_cvt_pk_bf16_f32 v17, v12, v13
	v_add_u32_e32 v12, 0x404, v10
	v_ashrrev_i32_e32 v13, 31, v12
	v_lshlrev_b64 v[18:19], 11, v[12:13]
	v_lshl_add_u64 v[18:19], s[84:85], 0, v[18:19]
	v_lshl_add_u64 v[18:19], v[18:19], 0, s[68:69]
	v_lshl_add_u64 v[18:19], v[18:19], 0, v[98:99]
	v_add_co_u32_e32 v18, vcc, s7, v18
	v_lshlrev_b32_e32 v11, 16, v16
	s_nop 0
	v_addc_co_u32_e32 v19, vcc, 0, v19, vcc
	global_store_dwordx2 v[18:19], v[16:17], off offset:1024
	v_mul_f32_e32 v15, v15, v15
	v_and_b32_e32 v16, 0xffff0000, v17
	v_fmac_f32_e32 v15, v11, v11
	v_lshlrev_b32_e32 v11, 16, v17
	v_mul_f32_e32 v16, v16, v16
	v_fmac_f32_e32 v16, v11, v11
	v_add_f32_e32 v11, v15, v16
	v_mov_b32_e32 v15, v11
	s_nop 1
	v_permlane16_swap_b32_e32 v11, v15
	s_and_saveexec_b64 s[0:1], s[38:39]
	s_cbranch_execz .LBB0_815
	v_lshlrev_b64 v[12:13], 7, v[12:13]
	s_waitcnt lgkmcnt(0)
	v_add_f32_e32 v11, v11, v15
	v_lshl_add_u64 v[12:13], s[22:23], 0, v[12:13]
	global_store_dword v[12:13], v11, off
.LBB0_815:
	s_or_b64 exec, exec, s[0:1]
	v_or_b32_e32 v12, 6, v10
	v_pk_mul_f32 v[6:7], v[6:7], s[88:89] op_sel_hi:[1,0]
	v_pk_mul_f32 v[8:9], v[8:9], s[88:89] op_sel_hi:[1,0]
	v_ashrrev_i32_e32 v13, 31, v12
	v_cvt_pk_bf16_f32 v6, v6, v7
	v_cvt_pk_bf16_f32 v7, v8, v9
	v_lshlrev_b64 v[8:9], 11, v[12:13]
	v_lshl_add_u64 v[8:9], s[84:85], 0, v[8:9]
	v_lshl_add_u64 v[8:9], v[8:9], 0, s[68:69]
	v_lshl_add_u64 v[8:9], v[8:9], 0, v[98:99]
	v_add_co_u32_e32 v8, vcc, s7, v8
	s_nop 1
	v_addc_co_u32_e32 v9, vcc, 0, v9, vcc
	global_store_dwordx2 v[8:9], v[6:7], off offset:1024
	v_lshlrev_b32_e32 v8, 16, v6
	v_and_b32_e32 v6, 0xffff0000, v6
	v_mul_f32_e32 v6, v6, v6
	v_fmac_f32_e32 v6, v8, v8
	v_lshlrev_b32_e32 v8, 16, v7
	v_and_b32_e32 v7, 0xffff0000, v7
	v_mul_f32_e32 v7, v7, v7
	v_fmac_f32_e32 v7, v8, v8
	v_add_f32_e32 v6, v6, v7
	v_mov_b32_e32 v7, v6
	s_nop 1
	v_permlane16_swap_b32_e32 v6, v7
	s_and_saveexec_b64 s[0:1], s[38:39]
	s_cbranch_execz .LBB0_817
	s_waitcnt lgkmcnt(0)
	v_add_f32_e32 v8, v6, v7
	v_lshlrev_b64 v[6:7], 7, v[12:13]
	v_lshl_add_u64 v[6:7], s[22:23], 0, v[6:7]
	global_store_dword v[6:7], v8, off
.LBB0_817:
	s_or_b64 exec, exec, s[0:1]
	v_pk_mul_f32 v[2:3], v[2:3], s[88:89] op_sel_hi:[1,0]
	s_nop 0
	v_cvt_pk_bf16_f32 v6, v2, v3
	v_pk_mul_f32 v[2:3], v[4:5], s[88:89] op_sel_hi:[1,0]
	s_waitcnt lgkmcnt(0)
	v_cvt_pk_bf16_f32 v7, v2, v3
	v_add_u32_e32 v2, 0x406, v10
	v_ashrrev_i32_e32 v3, 31, v2
	v_lshlrev_b64 v[4:5], 11, v[2:3]
	v_lshl_add_u64 v[4:5], s[84:85], 0, v[4:5]
	v_lshl_add_u64 v[4:5], v[4:5], 0, s[68:69]
	v_lshl_add_u64 v[4:5], v[4:5], 0, v[98:99]
	v_add_co_u32_e32 v4, vcc, s7, v4
	s_nop 1
	v_addc_co_u32_e32 v5, vcc, 0, v5, vcc
	global_store_dwordx2 v[4:5], v[6:7], off offset:1024
	v_and_b32_e32 v5, 0xffff0000, v6
	v_lshlrev_b32_e32 v4, 16, v6
	v_mul_f32_e32 v5, v5, v5
	v_and_b32_e32 v6, 0xffff0000, v7
	v_fmac_f32_e32 v5, v4, v4
	v_lshlrev_b32_e32 v4, 16, v7
	v_mul_f32_e32 v6, v6, v6
	v_fmac_f32_e32 v6, v4, v4
	v_add_f32_e32 v4, v5, v6
	v_mov_b32_e32 v5, v4
	s_nop 1
	v_permlane16_swap_b32_e32 v4, v5
	s_and_saveexec_b64 s[0:1], s[38:39]
	s_cbranch_execz .LBB0_802
	v_lshlrev_b64 v[2:3], 7, v[2:3]
	s_waitcnt lgkmcnt(0)
	v_add_f32_e32 v4, v4, v5
	v_lshl_add_u64 v[2:3], s[22:23], 0, v[2:3]
	global_store_dword v[2:3], v4, off
	s_branch .LBB0_802

.LBB0_1100:
	s_and_b64 vcc, exec, s[0:1]
	s_cbranch_vccz .LBB0_1252
	v_readlane_b32 s0, v254, 7
	v_readlane_b32 s10, v252, 11
	v_mov_b32_e32 v8, v0
	v_mov_b32_e32 v2, s0
	v_readlane_b32 s0, v254, 8
	s_waitcnt lgkmcnt(0)
	ds_read_b64 v[2:3], v2
	v_readlane_b32 s11, v252, 12
	v_mov_b32_e32 v4, s0
	v_readlane_b32 s0, v254, 25
	ds_read_b64 v[4:5], v4
	s_andn2_b64 vcc, exec, s[10:11]
	v_mov_b32_e32 v6, s0
	ds_read_b64 v[6:7], v6
	s_waitcnt lgkmcnt(2)
	v_readfirstlane_b32 s2, v2
	v_readfirstlane_b32 s4, v3
	s_waitcnt lgkmcnt(1)
	v_readfirstlane_b32 s7, v4
	v_readfirstlane_b32 s8, v5
	s_waitcnt lgkmcnt(0)
	v_readfirstlane_b32 s0, v6
	v_readfirstlane_b32 s1, v7
	s_nop 0
	v_readfirstlane_b32 s18, v8
	s_cbranch_vccnz .LBB0_1170
	v_lshlrev_b32_e32 v5, 4, v8
	v_add_u32_e32 v3, 0x2000, v5
	v_ashrrev_i32_e32 v2, 31, v3
	v_lshrrev_b32_e32 v2, 22, v2
	v_add_u32_e32 v2, v3, v2
	v_ashrrev_i32_e32 v2, 10, v2
	v_mul_i32_i24_e32 v4, 0x400, v2
	v_sub_u32_e32 v3, v3, v4
	v_lshrrev_b32_e32 v4, 4, v3
	v_bitop3_b32 v4, v4, v3, 32 bitop3:0x6c
	v_ashrrev_i32_e32 v3, 31, v4
	v_lshrrev_b32_e32 v3, 26, v3
	v_add_u32_e32 v6, v4, v3
	v_lshlrev_b32_e32 v7, 3, v2
	v_ashrrev_i32_e32 v3, 6, v6
	v_and_b32_e32 v7, -16, v7
	v_add_u32_e32 v7, v3, v7
	v_and_b32_e32 v9, 3, v3
	s_mov_b32 s10, 0x1fffe0
	v_lshrrev_b32_e32 v10, 2, v7
	v_lshlrev_b32_e32 v11, 1, v7
	v_and_b32_e32 v6, 0xc0, v6
	v_and_or_b32 v9, v7, s10, v9
	v_and_b32_e32 v10, 4, v10
	v_and_b32_e32 v11, 24, v11
	v_sub_u32_e32 v4, v4, v6
	v_mov_b32_e32 v14, 1
	v_or3_b32 v9, v9, v10, v11
	v_lshlrev_b32_e32 v10, 5, v2
	v_ashrrev_i16_sdwa v4, v14, sext(v4) dst_sel:DWORD dst_unused:UNUSED_PAD src0_sel:DWORD src1_sel:BYTE_0
	v_and_b32_e32 v10, 32, v10
	v_bfe_i32 v4, v4, 0, 16
	v_add_lshl_u32 v6, v10, v4, 1
	v_lshl_add_u32 v158, v9, 11, v6
	v_lshl_add_u32 v160, v7, 11, v6
	v_bfe_i32 v6, v8, 27, 1
	v_lshrrev_b32_e32 v6, 22, v6
	v_add_u32_e32 v6, v5, v6
	v_and_b32_e32 v6, 0xfffffc00, v6
	v_sub_u32_e32 v5, v5, v6
	v_lshrrev_b32_e32 v6, 4, v5
	v_bitop3_b32 v7, v6, v5, 32 bitop3:0x6c
	v_ashrrev_i32_e32 v6, 31, v8
	v_lshrrev_b32_e32 v6, 26, v6
	v_ashrrev_i32_e32 v5, 31, v7
	v_add_u32_e32 v6, v8, v6
	v_lshrrev_b32_e32 v5, 26, v5
	v_ashrrev_i32_e32 v6, 6, v6
	v_add_u32_e32 v9, v7, v5
	v_lshlrev_b32_e32 v10, 3, v6
	v_ashrrev_i32_e32 v5, 6, v9
	v_and_b32_e32 v10, -16, v10
	v_add_u32_e32 v10, v5, v10
	v_and_b32_e32 v11, 3, v5
	v_lshrrev_b32_e32 v12, 2, v10
	v_lshlrev_b32_e32 v13, 1, v10
	v_and_b32_e32 v9, 0xc0, v9
	v_and_or_b32 v11, v10, s10, v11
	v_and_b32_e32 v12, 4, v12
	v_and_b32_e32 v13, 24, v13
	v_sub_u32_e32 v7, v7, v9
	s_ashr_i32 s14, s18, 6
	v_or3_b32 v11, v11, v12, v13
	v_lshlrev_b32_e32 v12, 5, v6
	v_ashrrev_i16_sdwa v7, v14, sext(v7) dst_sel:DWORD dst_unused:UNUSED_PAD src0_sel:DWORD src1_sel:BYTE_0
	s_lshl_b32 s9, s14, 10
	v_and_b32_e32 v12, 32, v12
	v_bfe_i32 v7, v7, 0, 16
	v_add_lshl_u32 v9, v12, v7, 1
	s_add_i32 s10, s9, 0
	v_readlane_b32 s12, v253, 3
	v_lshl_add_u32 v162, v11, 11, v9
	s_add_i32 m0, s10, 0x10000
	v_readlane_b32 s13, v253, 4
	v_lshl_add_u32 v164, v10, 11, v9
	s_add_i32 s11, s10, 0x2000
	v_readlane_b32 s16, v253, 1
	v_readlane_b32 s17, v253, 2
	v_mov_b32_e32 v9, v0
	global_load_lds_dwordx4 v162, s[12:13]
	s_add_i32 m0, s10, 0x12000
	s_nop 0
	global_load_lds_dwordx4 v158, s[12:13]
	v_readlane_b32 s12, v252, 61
	s_add_i32 m0, s10, 0x14000
	v_readlane_b32 s13, v252, 62
	s_nop 4
	global_load_lds_dwordx4 v162, s[12:13]
	s_add_i32 m0, s10, 0x16000
	s_nop 0
	global_load_lds_dwordx4 v158, s[12:13]
	v_readlane_b32 s12, v252, 63
	s_mov_b32 m0, s10
	v_readlane_b32 s13, v253, 0
	s_nop 4
	global_load_lds_dwordx4 v164, s[12:13]
	s_mov_b32 m0, s11
	s_nop 0
	global_load_lds_dwordx4 v160, s[12:13]
	s_add_i32 s12, s10, 0x4000
	s_mov_b32 m0, s12
	s_add_i32 s13, s10, 0x6000
	global_load_lds_dwordx4 v164, s[16:17]
	s_mov_b32 m0, s13
	s_nop 0
	global_load_lds_dwordx4 v160, s[16:17]
	v_readlane_b32 s16, v252, 49
	v_ashrrev_i32_e32 v10, 1, v9
	v_and_b32_e32 v32, 1, v9
	v_add_u32_e32 v9, s16, v10
	v_lshlrev_b32_e32 v11, 6, v32
	v_lshl_or_b32 v11, v9, 7, v11
	global_load_dwordx4 v[12:15], v11, s[24:25]
	global_load_dwordx4 v[16:19], v11, s[24:25] offset:16
	global_load_dwordx4 v[20:23], v11, s[24:25] offset:32
	global_load_dwordx4 v[24:27], v11, s[24:25] offset:48
	v_readlane_b32 s17, v252, 50
	v_readlane_b32 s16, v251, 58
	v_lshlrev_b32_e32 v9, 4, v9
	v_readlane_b32 s17, v251, 59
	s_waitcnt vmcnt(0)
	v_add_f32_e32 v11, v14, v15
	s_nop 2
	global_load_dwordx4 v[28:31], v9, s[16:17]
	v_add_f32_e32 v9, v12, v13
	v_add_f32_e32 v9, v9, v11
	v_add_f32_e32 v11, v16, v17
	v_add_f32_e32 v12, v18, v19
	v_add_f32_e32 v9, 0, v9
	v_add_f32_e32 v11, v11, v12
	v_add_f32_e32 v9, v9, v11
	v_add_f32_e32 v11, v20, v21
	v_add_f32_e32 v12, v22, v23
	v_add_f32_e32 v11, v11, v12
	v_add_f32_e32 v9, v9, v11
	v_add_f32_e32 v11, v24, v25
	v_add_f32_e32 v12, v26, v27
	v_add_f32_e32 v11, v11, v12
	v_add_f32_e32 v11, v9, v11
	v_xor_b32_e32 v13, 1, v1
	s_waitcnt vmcnt(0)
	v_add_f32_e32 v9, v28, v29
	v_add_f32_e32 v12, v30, v31
	v_add_f32_e32 v12, v9, v12
	v_and_b32_e32 v9, 64, v1
	v_add_u32_e32 v9, 64, v9
	v_cmp_lt_i32_e32 vcc, v13, v9
	s_nop 1
	v_cndmask_b32_e32 v13, v1, v13, vcc
	v_cmp_eq_u32_e32 vcc, 0, v32
	v_lshlrev_b32_e32 v176, 2, v13
	v_mov_b32_dpp v13, v11 quad_perm:[1,0,3,2] row_mask:0xf bank_mask:0xf
	v_cndmask_b32_e32 v14, 0, v12, vcc
	s_nop 1
	v_mov_b32_dpp v14, v14 quad_perm:[1,0,3,2] row_mask:0xf bank_mask:0xf
	s_and_saveexec_b64 s[22:23], vcc
	s_cbranch_execz .LBB0_1104
	s_waitcnt lgkmcnt(0)
	v_add_f32_e32 v11, v11, v13
	v_fmamk_f32 v11, v11, 0x3b800000, v212
	v_rsq_f32_e32 v11, v11
	v_add_f32_e32 v12, v12, v14
	v_fmamk_f32 v12, v12, 0x3b000000, v212
	v_rsq_f32_e32 v12, v12
	v_rcp_f32_e32 v13, v11
	v_lshl_add_u32 v10, v10, 2, 0
	v_add_u32_e32 v10, 0x20400, v10
	v_mul_f32_e32 v13, v12, v13
	ds_write2st64_b32 v10, v13, v11 offset1:4
	ds_write_b32 v10, v12 offset:2048

.LBB0_1698:
	v_and_b32_e32 v5, 64, v1
	v_add_u32_e32 v5, 64, v5
	v_xor_b32_e32 v6, 1, v1
	v_cmp_lt_i32_e32 vcc, v6, v5
	v_lshlrev_b32_e32 v8, 2, v4
	v_mov_b32_e32 v9, 0
	v_cndmask_b32_e32 v6, v1, v6, vcc
	v_lshlrev_b32_e32 v42, 2, v6
	v_xor_b32_e32 v6, 2, v1
	v_cmp_lt_i32_e32 vcc, v6, v5
	v_readlane_b32 s2, v254, 4
	v_and_b32_e32 v10, 63, v0
	v_cndmask_b32_e32 v6, v1, v6, vcc
	v_lshlrev_b32_e32 v43, 2, v6
	v_xor_b32_e32 v6, 4, v1
	v_cmp_lt_i32_e32 vcc, v6, v5
	v_mov_b32_e32 v48, 0x358637bd
	s_mov_b32 s12, 0xf800000
	v_cndmask_b32_e32 v6, v1, v6, vcc
	v_lshlrev_b32_e32 v44, 2, v6
	v_xor_b32_e32 v6, 8, v1
	v_cmp_lt_i32_e32 vcc, v6, v5
	v_mov_b32_e32 v49, 0x260
	s_nop 0
	v_cndmask_b32_e32 v6, v1, v6, vcc
	v_lshlrev_b32_e32 v45, 2, v6
	v_xor_b32_e32 v6, 16, v1
	v_cmp_lt_i32_e32 vcc, v6, v5
	s_nop 1
	v_cndmask_b32_e32 v6, v1, v6, vcc
	v_lshlrev_b32_e32 v46, 2, v6
	v_xor_b32_e32 v6, 32, v1
	v_cmp_lt_i32_e32 vcc, v6, v5
	v_lshl_add_u64 v[4:5], s[0:1], 0, v[8:9]
	s_ashr_i32 s1, s8, 31
	s_add_u32 s0, s8, s89
	s_addc_u32 s1, s1, s2
	s_lshl_b64 s[0:1], s[0:1], 12
	s_add_u32 s0, s84, s0
	v_cndmask_b32_e32 v1, v1, v6, vcc
	v_lshl_add_u64 v[6:7], s[84:85], 0, v[8:9]
	v_lshlrev_b32_e32 v8, 4, v10
	s_addc_u32 s1, s85, s1
	v_lshlrev_b32_e32 v47, 2, v1
	v_lshl_add_u64 v[0:1], s[0:1], 0, v[8:9]
	s_mov_b64 s[0:1], 0xc00
	v_lshl_add_u64 v[0:1], v[0:1], 0, s[0:1]
	v_readlane_b32 s0, v251, 56
	s_mov_b32 s4, s0
	s_ashr_i32 s5, s0, 31
	v_readlane_b32 s0, v252, 6
	s_add_i32 s10, s4, s89
	v_readlane_b32 s1, v251, 57
	s_lshl_b32 s9, s0, 3
	s_add_i32 s0, s10, s8
	s_ashr_i32 s1, s0, 31
	s_lshl_b64 s[2:3], s[4:5], 12
	s_lshl_b64 s[0:1], s[0:1], 11
	s_add_u32 s0, s86, s0
	v_lshlrev_b32_e32 v8, 3, v10
	s_addc_u32 s1, s87, s1
	v_lshl_add_u64 v[8:9], s[0:1], 0, v[8:9]
	s_mov_b64 s[0:1], 0x4d00000
	v_lshl_add_u64 v[8:9], v[8:9], 0, s[0:1]
	v_readlane_b32 s0, v254, 31
	s_mov_b32 s14, s4
	s_lshl_b64 s[4:5], s[4:5], 11
	s_add_i32 s11, s0, s89
	v_readlane_b32 s1, v254, 32
	global_load_dwordx4 v[100:103], v[4:5], off
	global_load_dwordx4 v[104:107], v[4:5], off offset:1024
	global_load_dwordx4 v[108:111], v[4:5], off offset:2048
	global_load_dwordx4 v[112:115], v[4:5], off offset:3072
	s_branch .LBB0_1700
.LBB0_1699:
	s_waitcnt vmcnt(8)
	s_add_i32 s8, s8, s14
	s_add_i32 s0, s89, s8
	v_lshl_add_u64 v[0:1], v[0:1], 0, s[2:3]
	v_lshl_add_u64 v[8:9], v[8:9], 0, s[4:5]
	s_cmpk_lt_i32 s0, 0x4000
	v_mov_b64_e32 v[26:27], v[18:19]
	v_mov_b64_e32 v[28:29], v[20:21]
	v_mov_b64_e32 v[30:31], v[22:23]
	v_mov_b64_e32 v[32:33], v[24:25]
	v_mov_b64_e32 v[34:35], v[10:11]
	v_mov_b64_e32 v[36:37], v[12:13]
	v_mov_b64_e32 v[38:39], v[14:15]
	v_mov_b64_e32 v[40:41], v[16:17]
	s_cbranch_scc0 .LBB0_1706

.LBB0_1704:
	s_waitcnt vmcnt(8)
	v_lshlrev_b32_e32 v51, 16, v41
	v_lshlrev_b32_e32 v50, 16, v40
	v_and_b32_e32 v41, 0xffff0000, v41
	v_and_b32_e32 v40, 0xffff0000, v40
	v_lshlrev_b32_e32 v55, 16, v39
	v_lshlrev_b32_e32 v54, 16, v38
	v_and_b32_e32 v39, 0xffff0000, v39
	v_and_b32_e32 v38, 0xffff0000, v38
	v_pk_mul_f32 v[52:53], v[40:41], v[40:41]
	v_pk_mul_f32 v[56:57], v[38:39], v[38:39]
	v_lshlrev_b32_e32 v58, 16, v36
	v_and_b32_e32 v59, 0xffff0000, v36
	v_lshlrev_b32_e32 v64, 16, v37
	v_lshlrev_b32_e32 v60, 16, v34
	v_pk_fma_f32 v[52:53], v[50:51], v[50:51], v[52:53]
	v_pk_fma_f32 v[56:57], v[54:55], v[54:55], v[56:57]
	v_mul_f32_e32 v61, v58, v58
	v_mul_f32_e32 v63, v59, v59
	v_and_b32_e32 v65, 0xffff0000, v37
	v_mul_f32_e32 v36, v64, v64
	v_mov_b32_e32 v62, v60
	v_pk_add_f32 v[52:53], v[52:53], v[52:53] op_sel_hi:[0,1]
	v_pk_add_f32 v[56:57], v[56:57], v[56:57] op_sel_hi:[0,1]
	v_pk_fma_f32 v[36:37], v[64:65], v[64:65], v[36:37] op_sel_hi:[1,1,0]
	v_and_b32_e32 v68, 0xffff0000, v34
	v_lshlrev_b32_e32 v66, 16, v35
	v_and_b32_e32 v67, 0xffff0000, v35
	v_pk_add_f32 v[62:63], v[60:61], v[62:63]
	v_mul_f32_e32 v36, v68, v68
	v_mul_f32_e32 v56, v66, v66
	v_mul_f32_e32 v52, v67, v67
	v_mul_f32_e32 v34, v60, v60
	v_mov_b32_e32 v35, v63
	v_pk_add_f32 v[34:35], v[34:35], v[36:37]
	v_pk_add_f32 v[36:37], v[56:57], v[52:53]
	s_add_i32 s6, s9, s8
	v_pk_add_f32 v[52:53], v[34:35], v[36:37]
	v_add_f32_e32 v52, v52, v53
	s_nop 1
	v_mov_b32_dpp v53, v52 quad_perm:[1,0,3,2] row_mask:0xf bank_mask:0xf
	s_cmpk_gt_i32 s6, 0x3fff
	s_waitcnt lgkmcnt(0)
	v_add_f32_e32 v52, v52, v53
	s_nop 1
	v_mov_b32_dpp v53, v52 quad_perm:[2,3,0,1] row_mask:0xf bank_mask:0xf
	s_waitcnt lgkmcnt(0)
	v_add_f32_e32 v52, v52, v53
	s_nop 1
	v_mov_b32_dpp v53, v52 row_half_mirror row_mask:0xf bank_mask:0xf
	s_waitcnt lgkmcnt(0)
	v_add_f32_e32 v52, v52, v53
	s_nop 1
	v_mov_b32_dpp v53, v52 row_mirror row_mask:0xf bank_mask:0xf
	s_waitcnt lgkmcnt(0)
	v_add_f32_e32 v52, v52, v53
	v_mov_b32_e32 v53, v52
	s_nop 1
	v_permlane16_swap_b32_e32 v52, v53
	s_waitcnt lgkmcnt(0)
	v_add_f32_e32 v52, v52, v53
	v_mov_b32_e32 v53, v52
	s_nop 1
	v_permlane32_swap_b32_e32 v52, v53
	s_waitcnt lgkmcnt(0)
	v_add_f32_e32 v52, v52, v53
	v_fmamk_f32 v52, v52, 0x3a800000, v48
	v_mul_f32_e32 v53, 0x4f800000, v52
	v_cmp_gt_f32_e32 vcc, s12, v52
	s_nop 1
	v_cndmask_b32_e32 v52, v52, v53, vcc
	v_sqrt_f32_e32 v53, v52
	s_nop 0
	v_add_u32_e32 v56, -1, v53
	v_fma_f32 v57, -v56, v53, v52
	v_cmp_ge_f32_e64 s[0:1], 0, v57
	v_add_u32_e32 v57, 1, v53
	s_nop 0
	v_cndmask_b32_e64 v56, v53, v56, s[0:1]
	v_fma_f32 v53, -v57, v53, v52
	v_cmp_lt_f32_e64 s[0:1], 0, v53
	s_nop 1
	v_cndmask_b32_e64 v53, v56, v57, s[0:1]
	v_mul_f32_e32 v56, 0x37800000, v53
	v_cndmask_b32_e32 v53, v53, v56, vcc
	v_cmp_class_f32_e32 vcc, v52, v49
	s_nop 1
	v_cndmask_b32_e32 v52, v53, v52, vcc
	v_div_scale_f32 v53, s[0:1], v52, v52, 1.0
	v_rcp_f32_e32 v56, v53
	s_nop 0
	v_fma_f32 v57, -v53, v56, 1.0
	v_fmac_f32_e32 v56, v57, v56
	v_div_scale_f32 v57, vcc, 1.0, v52, 1.0
	v_mul_f32_e32 v61, v57, v56
	v_fma_f32 v62, -v53, v61, v57
	v_fmac_f32_e32 v61, v62, v56
	v_fma_f32 v53, -v53, v61, v57
	v_div_fmas_f32 v53, v53, v56, v61
	v_div_fixup_f32 v52, v53, v52, 1.0
	v_mov_b32_e32 v56, v50
	v_mov_b32_e32 v57, v40
	v_mov_b32_e32 v40, v51
	v_pk_mul_f32 v[56:57], v[52:53], v[56:57] op_sel_hi:[0,1]
	v_pk_mul_f32 v[40:41], v[52:53], v[40:41] op_sel_hi:[0,1]
	v_pk_mul_f32 v[36:37], v[102:103], v[40:41]
	v_pk_mul_f32 v[34:35], v[100:101], v[56:57]
	global_store_dwordx4 v[0:1], v[34:37], off offset:-3072 nt
	v_mov_b32_e32 v40, v55
	v_mov_b32_e32 v41, v39
	v_mov_b32_e32 v55, v38
	v_pk_mul_f32 v[38:39], v[52:53], v[40:41] op_sel_hi:[0,1]
	v_pk_mul_f32 v[40:41], v[52:53], v[54:55] op_sel_hi:[0,1]
	v_mov_b32_e32 v61, v68
	v_pk_mul_f32 v[34:35], v[104:105], v[40:41]
	v_pk_mul_f32 v[36:37], v[106:107], v[38:39]
	global_store_dwordx4 v[0:1], v[34:37], off offset:-2048 nt
	v_pk_mul_f32 v[38:39], v[64:65], v[52:53] op_sel_hi:[1,0]
	v_pk_mul_f32 v[40:41], v[58:59], v[52:53] op_sel_hi:[1,0]
	v_pk_mul_f32 v[36:37], v[110:111], v[38:39]
	v_pk_mul_f32 v[34:35], v[108:109], v[40:41]
	global_store_dwordx4 v[0:1], v[34:37], off offset:-1024 nt
	v_pk_mul_f32 v[38:39], v[66:67], v[52:53] op_sel_hi:[1,0]
	v_pk_mul_f32 v[40:41], v[60:61], v[52:53] op_sel_hi:[1,0]
	v_pk_mul_f32 v[36:37], v[114:115], v[38:39]
	v_pk_mul_f32 v[34:35], v[112:113], v[40:41]
	global_store_dwordx4 v[0:1], v[34:37], off nt
	s_cbranch_scc1 .LBB0_1699
	s_nop 0
	v_lshlrev_b32_e32 v35, 16, v33
	v_lshlrev_b32_e32 v34, 16, v32
	v_and_b32_e32 v33, 0xffff0000, v33
	v_and_b32_e32 v32, 0xffff0000, v32
	v_lshlrev_b32_e32 v39, 16, v31
	v_lshlrev_b32_e32 v38, 16, v30
	v_and_b32_e32 v31, 0xffff0000, v31
	v_and_b32_e32 v30, 0xffff0000, v30
	v_pk_mul_f32 v[36:37], v[32:33], v[32:33]
	v_pk_mul_f32 v[40:41], v[30:31], v[30:31]
	v_lshlrev_b32_e32 v50, 16, v28
	v_and_b32_e32 v51, 0xffff0000, v28
	v_lshlrev_b32_e32 v56, 16, v29
	v_lshlrev_b32_e32 v52, 16, v26
	v_pk_fma_f32 v[36:37], v[34:35], v[34:35], v[36:37]
	v_pk_fma_f32 v[40:41], v[38:39], v[38:39], v[40:41]
	v_mul_f32_e32 v53, v50, v50
	v_mul_f32_e32 v55, v51, v51
	v_and_b32_e32 v57, 0xffff0000, v29
	v_mul_f32_e32 v28, v56, v56
	v_mov_b32_e32 v54, v52
	v_pk_add_f32 v[36:37], v[36:37], v[36:37] op_sel_hi:[0,1]
	v_pk_add_f32 v[40:41], v[40:41], v[40:41] op_sel_hi:[0,1]
	v_pk_fma_f32 v[28:29], v[56:57], v[56:57], v[28:29] op_sel_hi:[1,1,0]
	v_and_b32_e32 v60, 0xffff0000, v26
	v_lshlrev_b32_e32 v58, 16, v27
	v_and_b32_e32 v59, 0xffff0000, v27
	v_pk_add_f32 v[54:55], v[52:53], v[54:55]
	v_mul_f32_e32 v28, v60, v60
	v_mul_f32_e32 v40, v58, v58
	v_mul_f32_e32 v36, v59, v59
	v_mul_f32_e32 v26, v52, v52
	v_mov_b32_e32 v27, v55
	v_pk_add_f32 v[26:27], v[26:27], v[28:29]
	v_pk_add_f32 v[28:29], v[40:41], v[36:37]
	s_ashr_i32 s7, s6, 31
	v_pk_add_f32 v[36:37], v[26:27], v[28:29]
	v_add_f32_e32 v36, v36, v37
	s_nop 1
	v_mov_b32_dpp v37, v36 quad_perm:[1,0,3,2] row_mask:0xf bank_mask:0xf
	s_waitcnt lgkmcnt(0)
	v_add_f32_e32 v36, v36, v37
	s_nop 1
	v_mov_b32_dpp v37, v36 quad_perm:[2,3,0,1] row_mask:0xf bank_mask:0xf
	s_waitcnt lgkmcnt(0)
	v_add_f32_e32 v36, v36, v37
	s_nop 1
	v_mov_b32_dpp v37, v36 row_half_mirror row_mask:0xf bank_mask:0xf
	s_waitcnt lgkmcnt(0)
	v_add_f32_e32 v36, v36, v37
	s_nop 1
	v_mov_b32_dpp v37, v36 row_mirror row_mask:0xf bank_mask:0xf
	s_waitcnt lgkmcnt(0)
	v_add_f32_e32 v36, v36, v37
	v_mov_b32_e32 v37, v36
	s_nop 1
	v_permlane16_swap_b32_e32 v36, v37
	s_waitcnt lgkmcnt(0)
	v_add_f32_e32 v36, v36, v37
	v_mov_b32_e32 v37, v36
	s_nop 1
	v_permlane32_swap_b32_e32 v36, v37
	s_waitcnt lgkmcnt(0)
	v_add_f32_e32 v36, v36, v37
	v_fmamk_f32 v36, v36, 0x3a800000, v48
	v_mul_f32_e32 v37, 0x4f800000, v36
	v_cmp_gt_f32_e32 vcc, s12, v36
	s_nop 1
	v_cndmask_b32_e32 v36, v36, v37, vcc
	v_sqrt_f32_e32 v37, v36
	s_nop 0
	v_add_u32_e32 v40, -1, v37
	v_fma_f32 v41, -v40, v37, v36
	v_cmp_ge_f32_e64 s[0:1], 0, v41
	v_add_u32_e32 v41, 1, v37
	s_nop 0
	v_cndmask_b32_e64 v40, v37, v40, s[0:1]
	v_fma_f32 v37, -v41, v37, v36
	v_cmp_lt_f32_e64 s[0:1], 0, v37
	s_nop 1
	v_cndmask_b32_e64 v37, v40, v41, s[0:1]
	v_mul_f32_e32 v40, 0x37800000, v37
	v_cndmask_b32_e32 v37, v37, v40, vcc
	v_cmp_class_f32_e32 vcc, v36, v49
	s_nop 1
	v_cndmask_b32_e32 v36, v37, v36, vcc
	v_div_scale_f32 v37, s[0:1], v36, v36, 1.0
	v_rcp_f32_e32 v40, v37
	s_lshl_b64 s[0:1], s[6:7], 12
	v_fma_f32 v41, -v37, v40, 1.0
	v_fmac_f32_e32 v40, v41, v40
	v_div_scale_f32 v41, vcc, 1.0, v36, 1.0
	v_mul_f32_e32 v53, v41, v40
	v_fma_f32 v54, -v37, v53, v41
	v_fmac_f32_e32 v53, v54, v40
	v_fma_f32 v37, -v37, v53, v41
	v_div_fmas_f32 v37, v37, v40, v53
	v_div_fixup_f32 v36, v37, v36, 1.0
	v_mov_b32_e32 v40, v34
	v_mov_b32_e32 v41, v32
	v_mov_b32_e32 v32, v35
	v_pk_mul_f32 v[40:41], v[36:37], v[40:41] op_sel_hi:[0,1]
	v_pk_mul_f32 v[32:33], v[36:37], v[32:33] op_sel_hi:[0,1]
	v_pk_mul_f32 v[28:29], v[102:103], v[32:33]
	v_pk_mul_f32 v[26:27], v[100:101], v[40:41]
	v_lshl_add_u64 v[32:33], v[6:7], 0, s[0:1]
	global_store_dwordx4 v[32:33], v[26:29], off nt
	v_mov_b32_e32 v34, v39
	v_mov_b32_e32 v35, v31
	v_mov_b32_e32 v39, v30
	v_pk_mul_f32 v[30:31], v[36:37], v[34:35] op_sel_hi:[0,1]
	v_pk_mul_f32 v[34:35], v[36:37], v[38:39] op_sel_hi:[0,1]
	v_mov_b32_e32 v53, v60
	v_pk_mul_f32 v[26:27], v[104:105], v[34:35]
	v_pk_mul_f32 v[28:29], v[106:107], v[30:31]
	global_store_dwordx4 v[32:33], v[26:29], off offset:1024 nt
	v_pk_mul_f32 v[30:31], v[56:57], v[36:37] op_sel_hi:[1,0]
	v_pk_mul_f32 v[34:35], v[50:51], v[36:37] op_sel_hi:[1,0]
	v_pk_mul_f32 v[28:29], v[110:111], v[30:31]
	v_pk_mul_f32 v[26:27], v[108:109], v[34:35]
	global_store_dwordx4 v[32:33], v[26:29], off offset:2048 nt
	v_pk_mul_f32 v[30:31], v[58:59], v[36:37] op_sel_hi:[1,0]
	v_pk_mul_f32 v[34:35], v[52:53], v[36:37] op_sel_hi:[1,0]
	v_pk_mul_f32 v[28:29], v[114:115], v[30:31]
	v_pk_mul_f32 v[26:27], v[112:113], v[34:35]
	global_store_dwordx4 v[32:33], v[26:29], off offset:3072 nt
	s_branch .LBB0_1699

	.amdhsa_kernel _Z6mk_fwd4Args
		.amdhsa_group_segment_fixed_size 0
		.amdhsa_private_segment_fixed_size 0
		.amdhsa_kernarg_size 456
		.amdhsa_user_sgpr_count 2
		.amdhsa_user_sgpr_dispatch_ptr 0
		.amdhsa_user_sgpr_queue_ptr 0
		.amdhsa_user_sgpr_kernarg_segment_ptr 1
		.amdhsa_user_sgpr_dispatch_id 0
		.amdhsa_user_sgpr_kernarg_preload_length 0
		.amdhsa_user_sgpr_kernarg_preload_offset 0
		.amdhsa_user_sgpr_private_segment_size 0
		.amdhsa_uses_dynamic_stack 0
		.amdhsa_enable_private_segment 0
		.amdhsa_system_sgpr_workgroup_id_x 1
		.amdhsa_system_sgpr_workgroup_id_y 0
		.amdhsa_system_sgpr_workgroup_id_z 0
		.amdhsa_system_sgpr_workgroup_info 0
		.amdhsa_system_vgpr_workitem_id 0
		.amdhsa_next_free_vgpr 256
		.amdhsa_next_free_sgpr 102
		.amdhsa_accum_offset 256
		.amdhsa_reserve_vcc 1
		.amdhsa_float_round_mode_32 0
		.amdhsa_float_round_mode_16_64 0
		.amdhsa_float_denorm_mode_32 3
		.amdhsa_float_denorm_mode_16_64 3
		.amdhsa_dx10_clamp 1
		.amdhsa_ieee_mode 1
		.amdhsa_fp16_overflow 0
		.amdhsa_tg_split 0
		.amdhsa_exception_fp_ieee_invalid_op 0
		.amdhsa_exception_fp_denorm_src 0
		.amdhsa_exception_fp_ieee_div_zero 0
		.amdhsa_exception_fp_ieee_overflow 0
		.amdhsa_exception_fp_ieee_underflow 0
		.amdhsa_exception_fp_ieee_inexact 0
		.amdhsa_exception_int_div_zero 0
	.end_amdhsa_kernel

amdhsa.kernels:
  - .agpr_count:     0
    .args:
      - .offset:         0
        .size:           200
        .value_kind:     by_value
      - .offset:         200
        .size:           4
        .value_kind:     hidden_block_count_x
      - .offset:         204
        .size:           4
        .value_kind:     hidden_block_count_y
      - .offset:         208
        .size:           4
        .value_kind:     hidden_block_count_z
      - .offset:         212
        .size:           2
        .value_kind:     hidden_group_size_x
      - .offset:         214
        .size:           2
        .value_kind:     hidden_group_size_y
      - .offset:         216
        .size:           2
        .value_kind:     hidden_group_size_z
      - .offset:         218
        .size:           2
        .value_kind:     hidden_remainder_x
      - .offset:         220
        .size:           2
        .value_kind:     hidden_remainder_y
      - .offset:         222
        .size:           2
        .value_kind:     hidden_remainder_z
      - .offset:         240
        .size:           8
        .value_kind:     hidden_global_offset_x
      - .offset:         248
        .size:           8
        .value_kind:     hidden_global_offset_y
      - .offset:         256
        .size:           8
        .value_kind:     hidden_global_offset_z
      - .offset:         264
        .size:           2
        .value_kind:     hidden_grid_dims
      - .offset:         320
        .size:           4
        .value_kind:     hidden_dynamic_lds_size
    .group_segment_fixed_size: 0
    .kernarg_segment_align: 8
    .kernarg_segment_size: 456
    .language:       OpenCL C
    .language_version:
      - 2
      - 0
    .max_flat_workgroup_size: 512
    .name:           _Z6mk_fwd4Args
    .private_segment_fixed_size: 0
    .sgpr_count:     108
    .sgpr_spill_count: 323
    .symbol:         _Z6mk_fwd4Args.kd
    .uniform_work_group_size: 1
    .uses_dynamic_stack: false
    .vgpr_count:     256
    .vgpr_spill_count: 0
    .wavefront_size: 64
